# v41 + peeled iteration's first two DMA waits no longer force the epilogue's write-through stores to be acknowledged (vmcnt 56), phase prologue drained with vmcnt(0)
# baseline (speedup 1.0000x reference)
; #define PG8_WAIT_V(n) asm volatile("s_waitcnt vmcnt(" #n ")" ::: "memory")
; #define PG8_BAR __builtin_amdgcn_s_barrier()
; template <class Epi, class Sched, bool ALIGN_EPI = false, bool SP2 = false>
; __device__ __forceinline__ void gemm_phase(PG8_LAS unsigned char* lds, const Gemm g, const Sched& S, const Epi& E) {
;     const int tid = threadIdx.x, wid = __builtin_amdgcn_readfirstlane(tid >> 6), lane = tid & 63, wr = wid >> 2, wc = wid & 3, fr = lane & 15, fq = lane >> 4;
;     const int K = g.K, nt = K / BK;
;     unsigned voffA[2], voffB[2];
; #pragma unroll
;     for (int i = 0; i < 2; ++i) { int R, C; stage_rc(tid * 16 + i * 8192, R, C); const int Rb = Epi::PERM ? ((R & ~31) + perm32(R & 31)) : R;
;         voffA[i] = g.a_pre ? (unsigned)(tid * 16 + i * 8192) : (unsigned)(R * g.lda + C) * 2u; voffB[i] = g.b_pre ? (unsigned)(tid * 16 + i * 8192) : (unsigned)(Rb * g.ldb + C) * 2u; }
;     const size_t kstep = g.b_pre ? (size_t)(2 * HTB) : (size_t)(BK * 2);
;     const size_t hstepA = (size_t)HALF * g.lda * 2, hstepB = (size_t)HALF * g.ldb * 2;
;     const size_t tstepA = g.pstepA, tstepB = g.b_pre ? (size_t)(g.K / BK) * (2 * HTB) : 2 * hstepB;
;     const size_t kstepA = g.kstepA;
;     const unsigned ldsw = (unsigned)wid * 1024u;
;     const int aoff = lds_byte(wr * 64 + fr, fq * 8), boff = lds_byte(wc * 32 + fr, fq * 8);
;     ...
;         PG8_WAIT_V(8); PG8_BAR;
;         PG8_WAIT_V(6); PG8_BAR;
.LBB0_135:
	s_sext_i32_i8 s69, s2
	v_and_b32_e32 v0, 15, v188
	s_and_b32 s2, s55, 3
	v_lshlrev_b32_e32 v4, 6, v188
	v_and_b32_e32 v1, 48, v188
	v_lshl_or_b32 v142, s54, 6, v0
	s_lshl_b32 s8, s54, 13
	v_lshlrev_b32_e32 v0, 6, v0
	v_lshlrev_b32_e32 v3, 2, v188
	s_lshl_b32 s79, s2, 5
	s_lshl_b32 s2, s2, 12
	v_and_b32_e32 v4, 0x3c0, v4
	v_or_b32_e32 v2, v0, v1
	v_and_b32_e32 v3, 32, v3
	v_or_b32_e32 v5, v4, v1
	s_cmpk_lt_u32 s3, 0x100
	v_bitop3_b32 v0, v0, v3, v1 bitop3:0x36
	v_bitop3_b32 v2, v2, s8, v3 bitop3:0xde
	v_bitop3_b32 v1, v4, v3, v1 bitop3:0x36
	v_bitop3_b32 v3, s2, v5, v3 bitop3:0xf6
	s_cselect_b64 s[54:55], -1, 0
	s_lshl_b32 s2, s3, 4
	s_and_b32 s2, s2, 0x400
	s_waitcnt vmcnt(8)
	s_barrier
	s_waitcnt vmcnt(0)
	s_or_b32 s2, s2, s8
	v_or_b32_e32 v130, s2, v0
	v_or_b32_e32 v0, s2, v1
	s_add_i32 s86, 0, 0x10000
	s_add_i32 s89, 0, 0x14000
	s_add_i32 s90, 0, 0x18000
	s_add_i32 s91, 0, 0x1c000
	v_ashrrev_i32_e32 v131, 31, v130
	v_or_b32_e32 v132, 0x800, v0
	v_mov_b32_e32 v133, v129
	v_or_b32_e32 v134, 0x1000, v0
	v_mov_b32_e32 v135, v129
	v_or_b32_e32 v136, 0x1800, v0
	v_mov_b32_e32 v137, v129
	s_ashr_i32 s82, s26, 31
	s_mov_b32 s85, s26
	v_mov_b64_e32 v[138:139], 0xb00
	v_mov_b64_e32 v[140:141], 0xaff
	v_add_u32_e32 v143, s86, v3
	v_add_u32_e32 v144, s89, v3
	v_add_u32_e32 v145, 0, v2
	v_add_u32_e32 v146, s90, v3
	v_add_u32_e32 v147, s91, v3
	v_mov_b32_e32 v148, 0x358637bd
	s_barrier
	s_branch .LBB0_138

; #define PG8_STAGE(bufoff, gbase, voff) do { _Pragma("unroll") for (int _i = 0; _i < 2; ++_i) \
;         __builtin_amdgcn_global_load_lds((const unsigned*)((const char*)(gbase) + (voff)[_i]), (PG8_LAS unsigned*)(lds + (bufoff) + ldsw + _i * 8192), 16, 0, 0); } while (0)
; #define PG8_LDA(dst, b, h) do { _Pragma("unroll") for (int m = 0; m < 4; ++m) _Pragma("unroll") for (int k = 0; k < 2; ++k) dst[m][k] = *(const PG8_LAS bf16x8*)(lds + PG8_SA(b, h) + aoff + m * 2048 + k * 1024); } while (0)
; #define PG8_LDB(dst, b, h) do { _Pragma("unroll") for (int n = 0; n < 2; ++n) _Pragma("unroll") for (int k = 0; k < 2; ++k) dst[n][k] = *(const PG8_LAS bf16x8*)(lds + PG8_SB(b, h) + boff + n * 2048 + k * 1024); } while (0)
; #define PG8_WAIT_V(n) asm volatile("s_waitcnt vmcnt(" #n ")" ::: "memory")
; #define PG8_WAIT_L(n) asm volatile("s_waitcnt lgkmcnt(" #n ")" ::: "memory")
; #define PG8_BAR __builtin_amdgcn_s_barrier()
; #define PG8_SCHED __builtin_amdgcn_sched_barrier(0)
; template <class Epi, class Sched, bool ALIGN_EPI = false, bool SP2 = false>
; __device__ __forceinline__ void gemm_phase(PG8_LAS unsigned char* lds, const Gemm g, const Sched& S, const Epi& E) {
;     ...
;         const bool has_next = S.next(ui + 1, nxt);
;         const char* nA = has_next ? (const char*)g.A + (size_t)nxt.pm * tstepA : cA; const char* nB = has_next ? (const char*)g.Bt + (size_t)nxt.pn * tstepB : cB;
;         for (int t = 0; t < nt; t += 2) {
;             const bool last = (t == nt - 2);
;             const char* a1 = cA + (size_t)(t + 1) * kstepA;
;             const char* a2 = last ? nA : cA + (size_t)(t + 2) * kstepA; const char* b2 = last ? nB : cB + (size_t)(t + 2) * kstep;
;             const char* a3 = a2 + kstepA; const char* b3 = b2 + kstep;
;             if (last && has_next) S.a_ready(nxt);
;             if constexpr (SP2) {
;             PG8_LDB(B0, 0, 0); PG8_LDB(B1, 0, 1); PG8_SCHED; PG8_LDA(At, 0, 0); PG8_STAGE(PG8_SA(1, 1), a1 + hstepA, voffA);
;             PG8_WAIT_V(8); PG8_WAIT_L(0); PG8_BAR; PG8_MMA(0, 0, At, B0); PG8_MMA(0, 1, At, B1); PG8_BAR; PG8_SCHED;
;             PG8_LDA(At, 0, 1); PG8_STAGE(PG8_SB(0, 0), b2, voffB); PG8_STAGE(PG8_SB(0, 1), b2 + hstepB, voffB); PG8_STAGE(PG8_SA(0, 0), a2, voffA);
;             PG8_WAIT_V(8); PG8_WAIT_L(0); PG8_BAR; PG8_MMA(1, 0, At, B0); PG8_MMA(1, 1, At, B1); PG8_BAR; PG8_SCHED;
.LBB0_140:
	s_ashr_i32 s59, s58, 31
	s_lshl_b64 s[60:61], s[58:59], 19
	s_add_u32 s60, s12, s60
	s_addc_u32 s61, s13, s61
	s_and_b64 s[62:63], s[2:3], exec
	s_cselect_b32 s59, s61, s71
	s_cselect_b32 s92, s60, s70
	s_ashr_i32 s57, s56, 31
	s_lshl_b64 s[62:63], s[56:57], 19
	s_add_u32 s62, s80, s62
	s_addc_u32 s63, s81, s63
	s_and_b64 s[94:95], s[2:3], exec
	s_cselect_b32 s57, s63, s73
	s_cselect_b32 s93, s62, s72
	s_add_u32 s70, s70, 0x10000
	s_addc_u32 s71, s71, 0
	s_add_u32 s72, s72, 0x10000
	s_addc_u32 s73, s73, 0
	s_mov_b32 s94, -2
	ds_read_b128 v[150:153], v143
	ds_read_b128 v[154:157], v143 offset:1024
	ds_read_b128 v[158:161], v143 offset:2048
	ds_read_b128 v[162:165], v143 offset:3072
	ds_read_b128 v[166:169], v144
	ds_read_b128 v[170:173], v144 offset:1024
	ds_read_b128 v[174:177], v144 offset:2048
	ds_read_b128 v[178:181], v144 offset:3072
	s_cmp_eq_u32 s94, 12
	s_cselect_b32 s97, s59, s71
	s_cselect_b32 s96, s92, s70
	s_cselect_b32 vcc_hi, s57, s73
	s_cselect_b32 vcc_lo, s93, s72
	s_movk_i32 s8, 0xc000
	v_lshl_add_u64 v[186:187], s[70:71], 0, v[128:129]
	s_mov_b32 s9, -1
	v_lshl_add_u64 v[220:221], v[186:187], 0, s[8:9]
	s_movk_i32 s8, 0xe000
	s_add_i32 m0, s18, 0xc000
	s_mov_b32 s9, -1
	ds_read_b128 v[182:185], v145
	ds_read_b128 v[190:193], v145 offset:1024
	ds_read_b128 v[194:197], v145 offset:2048
	ds_read_b128 v[198:201], v145 offset:3072
	ds_read_b128 v[202:205], v145 offset:4096
	ds_read_b128 v[206:209], v145 offset:5120
	ds_read_b128 v[210:213], v145 offset:6144
	ds_read_b128 v[214:217], v145 offset:7168
	global_load_lds_dwordx4 v[220:221], off
	v_lshl_add_u64 v[186:187], v[186:187], 0, s[8:9]
	s_add_i32 m0, s18, 0xe000
	s_nop 0
	global_load_lds_dwordx4 v[186:187], off
	s_waitcnt vmcnt(56)
	s_waitcnt lgkmcnt(0)
	s_barrier
	s_waitcnt lgkmcnt(0)
	v_mfma_f32_16x16x32_bf16 v[116:119], v[150:153], v[182:185], 0
	v_mfma_f32_16x16x32_bf16 v[112:115], v[158:161], v[182:185], 0
	v_mfma_f32_16x16x32_bf16 v[108:111], v[150:153], v[194:197], 0
	v_mfma_f32_16x16x32_bf16 v[100:103], v[158:161], v[194:197], 0
	v_mfma_f32_16x16x32_bf16 v[92:95], v[150:153], v[202:205], 0
	v_mfma_f32_16x16x32_bf16 v[84:87], v[158:161], v[202:205], 0
	v_mfma_f32_16x16x32_bf16 v[76:79], v[150:153], v[210:213], 0
	v_mfma_f32_16x16x32_bf16 v[68:71], v[158:161], v[210:213], 0
	v_mfma_f32_16x16x32_bf16 v[116:119], v[154:157], v[190:193], v[116:119]
	v_mfma_f32_16x16x32_bf16 v[112:115], v[162:165], v[190:193], v[112:115]
	v_mfma_f32_16x16x32_bf16 v[108:111], v[154:157], v[198:201], v[108:111]
	v_mfma_f32_16x16x32_bf16 v[100:103], v[162:165], v[198:201], v[100:103]
	v_mfma_f32_16x16x32_bf16 v[92:95], v[154:157], v[206:209], v[92:95]
	v_mfma_f32_16x16x32_bf16 v[84:87], v[162:165], v[206:209], v[84:87]
	v_mfma_f32_16x16x32_bf16 v[76:79], v[154:157], v[214:217], v[76:79]
	v_mfma_f32_16x16x32_bf16 v[68:71], v[162:165], v[214:217], v[68:71]
	v_mfma_f32_16x16x32_bf16 v[124:127], v[166:169], v[182:185], 0
	v_mfma_f32_16x16x32_bf16 v[120:123], v[174:177], v[182:185], 0
	v_mfma_f32_16x16x32_bf16 v[104:107], v[166:169], v[194:197], 0
	v_mfma_f32_16x16x32_bf16 v[96:99], v[174:177], v[194:197], 0
	v_mfma_f32_16x16x32_bf16 v[88:91], v[166:169], v[202:205], 0
	v_mfma_f32_16x16x32_bf16 v[80:83], v[174:177], v[202:205], 0
	v_mfma_f32_16x16x32_bf16 v[72:75], v[166:169], v[210:213], 0
	v_mfma_f32_16x16x32_bf16 v[64:67], v[174:177], v[210:213], 0
	v_mfma_f32_16x16x32_bf16 v[124:127], v[170:173], v[190:193], v[124:127]
	v_mfma_f32_16x16x32_bf16 v[120:123], v[178:181], v[190:193], v[120:123]
	v_mfma_f32_16x16x32_bf16 v[104:107], v[170:173], v[198:201], v[104:107]
	v_mfma_f32_16x16x32_bf16 v[96:99], v[178:181], v[198:201], v[96:99]
	v_mfma_f32_16x16x32_bf16 v[88:91], v[170:173], v[206:209], v[88:91]
	v_mfma_f32_16x16x32_bf16 v[80:83], v[178:181], v[206:209], v[80:83]
	v_mfma_f32_16x16x32_bf16 v[72:75], v[170:173], v[214:217], v[72:75]
	v_mfma_f32_16x16x32_bf16 v[64:67], v[178:181], v[214:217], v[64:67]
	s_barrier
	s_add_i32 s8, s86, s14
	v_lshl_add_u64 v[186:187], vcc, 0, v[128:129]
	s_mov_b32 m0, s8
	ds_read_b128 v[182:185], v145 offset:16384
	ds_read_b128 v[190:193], v145 offset:17408
	ds_read_b128 v[194:197], v145 offset:18432
	ds_read_b128 v[198:201], v145 offset:19456
	ds_read_b128 v[202:205], v145 offset:20480
	ds_read_b128 v[206:209], v145 offset:21504
	ds_read_b128 v[210:213], v145 offset:22528
	ds_read_b128 v[214:217], v145 offset:23552
	global_load_lds_dwordx4 v[186:187], off
	v_lshl_add_u64 v[220:221], v[186:187], 0, s[4:5]
	s_add_i32 m0, s8, 0x2000
	s_add_i32 s8, s89, s14
	global_load_lds_dwordx4 v[220:221], off
	v_lshl_add_u64 v[220:221], v[186:187], 0, s[6:7]
	s_mov_b32 m0, s8
	s_nop 0
	global_load_lds_dwordx4 v[220:221], off
	v_lshl_add_u64 v[220:221], v[186:187], 0, s[30:31]
	s_add_i32 m0, s8, 0x2000
	s_nop 0
	global_load_lds_dwordx4 v[220:221], off
	v_lshl_add_u64 v[220:221], s[96:97], 0, v[128:129]
	s_mov_b32 m0, s18
	v_lshl_add_u64 v[222:223], v[220:221], 0, s[4:5]
	global_load_lds_dwordx4 v[220:221], off
	s_mov_b32 m0, s19
	s_nop 0
	global_load_lds_dwordx4 v[222:223], off
	s_waitcnt vmcnt(56)
	s_waitcnt lgkmcnt(0)
	s_barrier
; #define PG8_STAGE(bufoff, gbase, voff) do { _Pragma("unroll") for (int _i = 0; _i < 2; ++_i) \
;         __builtin_amdgcn_global_load_lds((const unsigned*)((const char*)(gbase) + (voff)[_i]), (PG8_LAS unsigned*)(lds + (bufoff) + ldsw + _i * 8192), 16, 0, 0); } while (0)
; #define PG8_LDA(dst, b, h) do { _Pragma("unroll") for (int m = 0; m < 4; ++m) _Pragma("unroll") for (int k = 0; k < 2; ++k) dst[m][k] = *(const PG8_LAS bf16x8*)(lds + PG8_SA(b, h) + aoff + m * 2048 + k * 1024); } while (0)
; #define PG8_LDB(dst, b, h) do { _Pragma("unroll") for (int n = 0; n < 2; ++n) _Pragma("unroll") for (int k = 0; k < 2; ++k) dst[n][k] = *(const PG8_LAS bf16x8*)(lds + PG8_SB(b, h) + boff + n * 2048 + k * 1024); } while (0)
; #define PG8_MMA(ai, bj, At, Bt) do { __builtin_amdgcn_s_setprio(1); _Pragma("unroll") for (int m = 0; m < 4; ++m) _Pragma("unroll") for (int n = 0; n < 2; ++n) _Pragma("unroll") for (int k = 0; k < 2; ++k) \
;         acc[ai][bj][m][n] = __builtin_amdgcn_mfma_f32_16x16x32_bf16(Bt[n][k], At[m][k], acc[ai][bj][m][n], 0, 0, 0); __builtin_amdgcn_s_setprio(0); } while (0)
; #define PG8_WAIT_V(n) asm volatile("s_waitcnt vmcnt(" #n ")" ::: "memory")
; #define PG8_WAIT_L(n) asm volatile("s_waitcnt lgkmcnt(" #n ")" ::: "memory")
; #define PG8_BAR __builtin_amdgcn_s_barrier()
; #define PG8_SCHED __builtin_amdgcn_sched_barrier(0)
; template <class Epi, class Sched, bool ALIGN_EPI = false, bool SP2 = false>
; __device__ __forceinline__ void gemm_phase(PG8_LAS unsigned char* lds, const Gemm g, const Sched& S, const Epi& E) {
;     ...
;             PG8_WAIT_V(8); PG8_WAIT_L(0); PG8_BAR; PG8_MMA(1, 0, At, B0); PG8_MMA(1, 1, At, B1); PG8_BAR; PG8_SCHED;
;             PG8_LDB(B0, 1, 0); PG8_LDB(B1, 1, 1); PG8_SCHED; PG8_LDA(At, 1, 0); PG8_STAGE(PG8_SA(0, 1), a2 + hstepA, voffA);
;             PG8_WAIT_V(8); PG8_WAIT_L(0); PG8_BAR; PG8_MMA(0, 0, At, B0); PG8_MMA(0, 1, At, B1); PG8_BAR; PG8_SCHED;
	s_waitcnt lgkmcnt(0)
	v_mfma_f32_16x16x32_bf16 v[60:63], v[150:153], v[182:185], 0
	v_mfma_f32_16x16x32_bf16 v[52:55], v[158:161], v[182:185], 0
	v_mfma_f32_16x16x32_bf16 v[44:47], v[150:153], v[194:197], 0
	v_mfma_f32_16x16x32_bf16 v[36:39], v[158:161], v[194:197], 0
	v_mfma_f32_16x16x32_bf16 v[28:31], v[150:153], v[202:205], 0
	v_mfma_f32_16x16x32_bf16 v[20:23], v[158:161], v[202:205], 0
	v_mfma_f32_16x16x32_bf16 v[12:15], v[150:153], v[210:213], 0
	v_mfma_f32_16x16x32_bf16 v[4:7], v[158:161], v[210:213], 0
	v_mfma_f32_16x16x32_bf16 v[60:63], v[154:157], v[190:193], v[60:63]
	v_mfma_f32_16x16x32_bf16 v[52:55], v[162:165], v[190:193], v[52:55]
	v_mfma_f32_16x16x32_bf16 v[44:47], v[154:157], v[198:201], v[44:47]
	v_mfma_f32_16x16x32_bf16 v[36:39], v[162:165], v[198:201], v[36:39]
	v_mfma_f32_16x16x32_bf16 v[28:31], v[154:157], v[206:209], v[28:31]
	v_mfma_f32_16x16x32_bf16 v[20:23], v[162:165], v[206:209], v[20:23]
	v_mfma_f32_16x16x32_bf16 v[12:15], v[154:157], v[214:217], v[12:15]
	v_mfma_f32_16x16x32_bf16 v[4:7], v[162:165], v[214:217], v[4:7]
	v_mfma_f32_16x16x32_bf16 v[56:59], v[166:169], v[182:185], 0
	v_mfma_f32_16x16x32_bf16 v[48:51], v[174:177], v[182:185], 0
	v_mfma_f32_16x16x32_bf16 v[40:43], v[166:169], v[194:197], 0
	v_mfma_f32_16x16x32_bf16 v[32:35], v[174:177], v[194:197], 0
	v_mfma_f32_16x16x32_bf16 v[24:27], v[166:169], v[202:205], 0
	v_mfma_f32_16x16x32_bf16 v[16:19], v[174:177], v[202:205], 0
	v_mfma_f32_16x16x32_bf16 v[8:11], v[166:169], v[210:213], 0
	v_mfma_f32_16x16x32_bf16 v[0:3], v[174:177], v[210:213], 0
	v_mfma_f32_16x16x32_bf16 v[56:59], v[170:173], v[190:193], v[56:59]
	v_mfma_f32_16x16x32_bf16 v[48:51], v[178:181], v[190:193], v[48:51]
	v_mfma_f32_16x16x32_bf16 v[40:43], v[170:173], v[198:201], v[40:43]
	v_mfma_f32_16x16x32_bf16 v[32:35], v[178:181], v[198:201], v[32:35]
	v_mfma_f32_16x16x32_bf16 v[24:27], v[170:173], v[206:209], v[24:27]
	v_mfma_f32_16x16x32_bf16 v[16:19], v[178:181], v[206:209], v[16:19]
	v_mfma_f32_16x16x32_bf16 v[8:11], v[170:173], v[214:217], v[8:11]
	v_mfma_f32_16x16x32_bf16 v[0:3], v[178:181], v[214:217], v[0:3]
	s_barrier
	ds_read_b128 v[150:153], v146
	ds_read_b128 v[154:157], v146 offset:1024
	ds_read_b128 v[158:161], v146 offset:2048
	ds_read_b128 v[162:165], v146 offset:3072
	ds_read_b128 v[166:169], v147
	ds_read_b128 v[170:173], v147 offset:1024
	ds_read_b128 v[174:177], v147 offset:2048
	ds_read_b128 v[178:181], v147 offset:3072
	s_mov_b32 m0, s74
	v_lshl_add_u64 v[222:223], v[220:221], 0, s[6:7]
	ds_read_b128 v[182:185], v145 offset:32768
	ds_read_b128 v[190:193], v145 offset:33792
	ds_read_b128 v[194:197], v145 offset:34816
	ds_read_b128 v[198:201], v145 offset:35840
	ds_read_b128 v[202:205], v145 offset:36864
	ds_read_b128 v[206:209], v145 offset:37888
	ds_read_b128 v[210:213], v145 offset:38912
	ds_read_b128 v[214:217], v145 offset:39936
	global_load_lds_dwordx4 v[222:223], off
	v_lshl_add_u64 v[222:223], v[220:221], 0, s[30:31]
	s_mov_b32 m0, s75
	s_nop 0
	global_load_lds_dwordx4 v[222:223], off
	s_waitcnt vmcnt(8)
	s_waitcnt lgkmcnt(0)
	s_barrier
	s_waitcnt lgkmcnt(0)
	v_mfma_f32_16x16x32_bf16 v[116:119], v[150:153], v[182:185], v[116:119]
	v_mfma_f32_16x16x32_bf16 v[112:115], v[158:161], v[182:185], v[112:115]
	v_mfma_f32_16x16x32_bf16 v[108:111], v[150:153], v[194:197], v[108:111]
	v_mfma_f32_16x16x32_bf16 v[100:103], v[158:161], v[194:197], v[100:103]
	v_mfma_f32_16x16x32_bf16 v[92:95], v[150:153], v[202:205], v[92:95]
	v_mfma_f32_16x16x32_bf16 v[84:87], v[158:161], v[202:205], v[84:87]
	v_mfma_f32_16x16x32_bf16 v[76:79], v[150:153], v[210:213], v[76:79]
	v_mfma_f32_16x16x32_bf16 v[68:71], v[158:161], v[210:213], v[68:71]
	v_mfma_f32_16x16x32_bf16 v[116:119], v[154:157], v[190:193], v[116:119]
	v_mfma_f32_16x16x32_bf16 v[112:115], v[162:165], v[190:193], v[112:115]
	v_mfma_f32_16x16x32_bf16 v[108:111], v[154:157], v[198:201], v[108:111]
	v_mfma_f32_16x16x32_bf16 v[100:103], v[162:165], v[198:201], v[100:103]
	v_mfma_f32_16x16x32_bf16 v[92:95], v[154:157], v[206:209], v[92:95]
	v_mfma_f32_16x16x32_bf16 v[84:87], v[162:165], v[206:209], v[84:87]
	v_mfma_f32_16x16x32_bf16 v[76:79], v[154:157], v[214:217], v[76:79]
	v_mfma_f32_16x16x32_bf16 v[68:71], v[162:165], v[214:217], v[68:71]
	v_mfma_f32_16x16x32_bf16 v[124:127], v[166:169], v[182:185], v[124:127]
	v_mfma_f32_16x16x32_bf16 v[120:123], v[174:177], v[182:185], v[120:123]
	v_mfma_f32_16x16x32_bf16 v[104:107], v[166:169], v[194:197], v[104:107]
	v_mfma_f32_16x16x32_bf16 v[96:99], v[174:177], v[194:197], v[96:99]
	v_mfma_f32_16x16x32_bf16 v[88:91], v[166:169], v[202:205], v[88:91]
	v_mfma_f32_16x16x32_bf16 v[80:83], v[174:177], v[202:205], v[80:83]
	v_mfma_f32_16x16x32_bf16 v[72:75], v[166:169], v[210:213], v[72:75]
	v_mfma_f32_16x16x32_bf16 v[64:67], v[174:177], v[210:213], v[64:67]
	v_mfma_f32_16x16x32_bf16 v[124:127], v[170:173], v[190:193], v[124:127]
	v_mfma_f32_16x16x32_bf16 v[120:123], v[178:181], v[190:193], v[120:123]
	v_mfma_f32_16x16x32_bf16 v[104:107], v[170:173], v[198:201], v[104:107]
	v_mfma_f32_16x16x32_bf16 v[96:99], v[178:181], v[198:201], v[96:99]
	v_mfma_f32_16x16x32_bf16 v[88:91], v[170:173], v[206:209], v[88:91]
	v_mfma_f32_16x16x32_bf16 v[80:83], v[178:181], v[206:209], v[80:83]
	v_mfma_f32_16x16x32_bf16 v[72:75], v[170:173], v[214:217], v[72:75]
	v_mfma_f32_16x16x32_bf16 v[64:67], v[178:181], v[214:217], v[64:67]
	s_barrier
; #define PG8_STAGE(bufoff, gbase, voff) do { _Pragma("unroll") for (int _i = 0; _i < 2; ++_i) \
;         __builtin_amdgcn_global_load_lds((const unsigned*)((const char*)(gbase) + (voff)[_i]), (PG8_LAS unsigned*)(lds + (bufoff) + ldsw + _i * 8192), 16, 0, 0); } while (0)
; #define PG8_LDA(dst, b, h) do { _Pragma("unroll") for (int m = 0; m < 4; ++m) _Pragma("unroll") for (int k = 0; k < 2; ++k) dst[m][k] = *(const PG8_LAS bf16x8*)(lds + PG8_SA(b, h) + aoff + m * 2048 + k * 1024); } while (0)
; #define PG8_MMA(ai, bj, At, Bt) do { __builtin_amdgcn_s_setprio(1); _Pragma("unroll") for (int m = 0; m < 4; ++m) _Pragma("unroll") for (int n = 0; n < 2; ++n) _Pragma("unroll") for (int k = 0; k < 2; ++k) \
;         acc[ai][bj][m][n] = __builtin_amdgcn_mfma_f32_16x16x32_bf16(Bt[n][k], At[m][k], acc[ai][bj][m][n], 0, 0, 0); __builtin_amdgcn_s_setprio(0); } while (0)
; #define PG8_WAIT_V(n) asm volatile("s_waitcnt vmcnt(" #n ")" ::: "memory")
; #define PG8_WAIT_L(n) asm volatile("s_waitcnt lgkmcnt(" #n ")" ::: "memory")
; #define PG8_BAR __builtin_amdgcn_s_barrier()
; #define PG8_SCHED __builtin_amdgcn_sched_barrier(0)
; template <class Epi, class Sched, bool ALIGN_EPI = false, bool SP2 = false>
; __device__ __forceinline__ void gemm_phase(PG8_LAS unsigned char* lds, const Gemm g, const Sched& S, const Epi& E) {
;     ...
;         for (int t = 0; t < nt; t += 2) {
;     ...
;             PG8_LDA(At, 1, 1); PG8_STAGE(PG8_SB(1, 0), b3, voffB); PG8_STAGE(PG8_SB(1, 1), b3 + hstepB, voffB); PG8_STAGE(PG8_SA(1, 0), a3, voffA);
;             PG8_WAIT_V(8); PG8_WAIT_L(0); PG8_BAR; PG8_MMA(1, 0, At, B0); PG8_MMA(1, 1, At, B1); PG8_BAR; PG8_SCHED;
	s_add_i32 s8, s90, s14
	v_lshl_add_u64 v[222:223], v[186:187], 0, s[34:35]
	s_mov_b32 m0, s8
	ds_read_b128 v[182:185], v145 offset:49152
	ds_read_b128 v[190:193], v145 offset:50176
	ds_read_b128 v[194:197], v145 offset:51200
	ds_read_b128 v[198:201], v145 offset:52224
	ds_read_b128 v[202:205], v145 offset:53248
	ds_read_b128 v[206:209], v145 offset:54272
	ds_read_b128 v[210:213], v145 offset:55296
	ds_read_b128 v[214:217], v145 offset:56320
	global_load_lds_dwordx4 v[222:223], off
	v_lshl_add_u64 v[222:223], v[186:187], 0, s[36:37]
	s_add_i32 m0, s8, 0x2000
	s_add_i32 s8, s91, s14
	global_load_lds_dwordx4 v[222:223], off
	v_lshl_add_u64 v[222:223], v[186:187], 0, s[38:39]
	s_mov_b32 m0, s8
	v_lshl_add_u64 v[186:187], v[186:187], 0, s[40:41]
	global_load_lds_dwordx4 v[222:223], off
	s_add_i32 m0, s8, 0x2000
	s_nop 0
	global_load_lds_dwordx4 v[186:187], off
	v_lshl_add_u64 v[186:187], v[220:221], 0, s[34:35]
	s_mov_b32 m0, s76
	s_nop 0
	global_load_lds_dwordx4 v[186:187], off
	v_lshl_add_u64 v[186:187], v[220:221], 0, s[36:37]
	s_mov_b32 m0, s77
	s_nop 0
	global_load_lds_dwordx4 v[186:187], off
	s_waitcnt vmcnt(8)
	s_waitcnt lgkmcnt(0)
	s_barrier
	s_waitcnt lgkmcnt(0)
	v_mfma_f32_16x16x32_bf16 v[60:63], v[150:153], v[182:185], v[60:63]
	v_mfma_f32_16x16x32_bf16 v[52:55], v[158:161], v[182:185], v[52:55]
	v_mfma_f32_16x16x32_bf16 v[44:47], v[150:153], v[194:197], v[44:47]
	v_mfma_f32_16x16x32_bf16 v[36:39], v[158:161], v[194:197], v[36:39]
	v_mfma_f32_16x16x32_bf16 v[28:31], v[150:153], v[202:205], v[28:31]
	v_mfma_f32_16x16x32_bf16 v[20:23], v[158:161], v[202:205], v[20:23]
	v_mfma_f32_16x16x32_bf16 v[12:15], v[150:153], v[210:213], v[12:15]
	v_mfma_f32_16x16x32_bf16 v[4:7], v[158:161], v[210:213], v[4:7]
	v_mfma_f32_16x16x32_bf16 v[60:63], v[154:157], v[190:193], v[60:63]
	v_mfma_f32_16x16x32_bf16 v[52:55], v[162:165], v[190:193], v[52:55]
	v_mfma_f32_16x16x32_bf16 v[44:47], v[154:157], v[198:201], v[44:47]
	v_mfma_f32_16x16x32_bf16 v[36:39], v[162:165], v[198:201], v[36:39]
	v_mfma_f32_16x16x32_bf16 v[28:31], v[154:157], v[206:209], v[28:31]
	v_mfma_f32_16x16x32_bf16 v[20:23], v[162:165], v[206:209], v[20:23]
	v_mfma_f32_16x16x32_bf16 v[12:15], v[154:157], v[214:217], v[12:15]
	v_mfma_f32_16x16x32_bf16 v[4:7], v[162:165], v[214:217], v[4:7]
	v_mfma_f32_16x16x32_bf16 v[56:59], v[166:169], v[182:185], v[56:59]
	v_mfma_f32_16x16x32_bf16 v[48:51], v[174:177], v[182:185], v[48:51]
	v_mfma_f32_16x16x32_bf16 v[40:43], v[166:169], v[194:197], v[40:43]
	v_mfma_f32_16x16x32_bf16 v[32:35], v[174:177], v[194:197], v[32:35]
	v_mfma_f32_16x16x32_bf16 v[24:27], v[166:169], v[202:205], v[24:27]
	v_mfma_f32_16x16x32_bf16 v[16:19], v[174:177], v[202:205], v[16:19]
	v_mfma_f32_16x16x32_bf16 v[8:11], v[166:169], v[210:213], v[8:11]
	v_mfma_f32_16x16x32_bf16 v[0:3], v[174:177], v[210:213], v[0:3]
	v_mfma_f32_16x16x32_bf16 v[56:59], v[170:173], v[190:193], v[56:59]
	v_mfma_f32_16x16x32_bf16 v[48:51], v[178:181], v[190:193], v[48:51]
	v_mfma_f32_16x16x32_bf16 v[40:43], v[170:173], v[198:201], v[40:43]
	v_mfma_f32_16x16x32_bf16 v[32:35], v[178:181], v[198:201], v[32:35]
	v_mfma_f32_16x16x32_bf16 v[24:27], v[170:173], v[206:209], v[24:27]
	v_mfma_f32_16x16x32_bf16 v[16:19], v[178:181], v[206:209], v[16:19]
	v_mfma_f32_16x16x32_bf16 v[8:11], v[170:173], v[214:217], v[8:11]
	v_mfma_f32_16x16x32_bf16 v[0:3], v[178:181], v[214:217], v[0:3]
	s_barrier
	s_add_i32 s94, s94, 2
	s_add_u32 s70, s70, 0x10000
	s_addc_u32 s71, s71, 0
	s_add_u32 s72, s72, 0x10000
	s_addc_u32 s73, s73, 0
	s_cmp_gt_u32 s94, 13

; #define PG8_STAGE(bufoff, gbase, voff) do { _Pragma("unroll") for (int _i = 0; _i < 2; ++_i) \
;         __builtin_amdgcn_global_load_lds((const unsigned*)((const char*)(gbase) + (voff)[_i]), (PG8_LAS unsigned*)(lds + (bufoff) + ldsw + _i * 8192), 16, 0, 0); } while (0)
; #define PG8_WAIT_V(n) asm volatile("s_waitcnt vmcnt(" #n ")" ::: "memory")
; #define PG8_BAR __builtin_amdgcn_s_barrier()
; template <class Epi, class Sched, bool ALIGN_EPI = false, bool SP2 = false>
; __device__ __forceinline__ void gemm_phase(PG8_LAS unsigned char* lds, const Gemm g, const Sched& S, const Epi& E) {
;     const int tid = threadIdx.x, wid = __builtin_amdgcn_readfirstlane(tid >> 6), lane = tid & 63, wr = wid >> 2, wc = wid & 3, fr = lane & 15, fq = lane >> 4;
;     const int K = g.K, nt = K / BK;
;     unsigned voffA[2], voffB[2];
; #pragma unroll
;     for (int i = 0; i < 2; ++i) { int R, C; stage_rc(tid * 16 + i * 8192, R, C); const int Rb = Epi::PERM ? ((R & ~31) + perm32(R & 31)) : R;
;         voffA[i] = g.a_pre ? (unsigned)(tid * 16 + i * 8192) : (unsigned)(R * g.lda + C) * 2u; voffB[i] = g.b_pre ? (unsigned)(tid * 16 + i * 8192) : (unsigned)(Rb * g.ldb + C) * 2u; }
;     const size_t kstep = g.b_pre ? (size_t)(2 * HTB) : (size_t)(BK * 2);
;     const size_t hstepA = (size_t)HALF * g.lda * 2, hstepB = (size_t)HALF * g.ldb * 2;
;     const size_t tstepA = g.pstepA, tstepB = g.b_pre ? (size_t)(g.K / BK) * (2 * HTB) : 2 * hstepB;
;     const size_t kstepA = g.kstepA;
;     const unsigned ldsw = (unsigned)wid * 1024u;
;     const int aoff = lds_byte(wr * 64 + fr, fq * 8), boff = lds_byte(wc * 32 + fr, fq * 8);
;     ...
;     if constexpr (SP2) {
;         PG8_STAGE(PG8_SB(0, 0), cB, voffB); PG8_STAGE(PG8_SB(0, 1), cB + hstepB, voffB); PG8_STAGE(PG8_SA(0, 0), cA, voffA); PG8_STAGE(PG8_SA(0, 1), cA + hstepA, voffA);
;         PG8_STAGE(PG8_SB(1, 0), cB + kstep, voffB); PG8_STAGE(PG8_SA(1, 0), cA + kstepA, voffA); PG8_STAGE(PG8_SB(1, 1), cB + hstepB + kstep, voffB);
;         if (wr == 1) PG8_BAR;
;         PG8_WAIT_V(8); PG8_BAR;
;         PG8_WAIT_V(6); PG8_BAR;
.LBB0_212:
	v_and_b32_e32 v1, 15, v188
	s_lshl_b32 s2, s0, 12
	v_lshl_or_b32 v189, s1, 6, v1
	s_lshl_b32 s1, s1, 13
	s_and_b32 s2, s2, 0x3000
	v_bfe_u32 v0, v188, 4, 2
	v_lshlrev_b32_e32 v4, 2, v188
	v_lshlrev_b32_e32 v5, 6, v188
	s_cmpk_lt_u32 s4, 0x100
	v_lshlrev_b32_e32 v1, 6, v1
	v_and_b32_e32 v2, 48, v188
	v_and_b32_e32 v4, 32, v4
	v_and_b32_e32 v5, 0x3c0, v5
	s_cselect_b64 s[58:59], -1, 0
	s_and_b32 s81, s0, 2
	v_lshlrev_b32_e32 v6, 4, v0
	s_lshl_b32 s0, s4, 4
	v_or_b32_e32 v3, v1, v2
	v_bitop3_b32 v2, v5, v4, v2 bitop3:0x36
	s_and_b32 s0, s0, 0x400
	v_bitop3_b32 v1, v1, v4, v6 bitop3:0x36
	v_or_b32_e32 v2, s2, v2
	s_or_b32 s2, s1, s0
	v_bitop3_b32 v5, v5, v4, v6 bitop3:0x36
	v_or_b32_e32 v1, s0, v1
	s_waitcnt vmcnt(8)
	s_barrier
	s_waitcnt vmcnt(0)
	v_or_b32_e32 v5, s2, v5
	v_or_b32_e32 v190, s1, v1
	v_bitop3_b32 v3, v3, s1, v4 bitop3:0xde
	v_or_b32_e32 v186, 0x1800, v5
	v_mov_b32_e32 v187, v185
	v_ashrrev_i32_e32 v191, 31, v190
	v_or_b32_e32 v192, 0x800, v5
	v_mov_b32_e32 v193, v185
	v_or_b32_e32 v194, 0x1000, v5
	v_mov_b32_e32 v195, v185
	v_cmp_eq_u32_e64 s[2:3], 0, v0
	s_add_i32 s89, 0, 0x10000
	s_add_i32 s90, 0, 0x14000
	s_movk_i32 s60, 0xe000
	s_add_i32 s91, 0, 0x18000
	s_add_i32 s92, 0, 0x1c000
	v_mbcnt_lo_u32_b32 v0, -1, 0
	s_movk_i32 s96, 0xc000
	s_ashr_i32 s82, s26, 31
	s_mov_b32 s85, s26
	s_ashr_i32 s86, s16, 31
	v_lshl_add_u64 v[196:197], s[12:13], 0, v[186:187]
	v_lshl_add_u64 v[198:199], s[12:13], 0, v[190:191]
	v_lshl_add_u64 v[200:201], s[12:13], 0, v[192:193]
	v_lshl_add_u64 v[202:203], s[12:13], 0, v[194:195]
	v_mov_b64_e32 v[204:205], 0x200
	v_mov_b64_e32 v[206:207], 0x1ff
	v_add_u32_e32 v210, s89, v2
	v_add_u32_e32 v211, s90, v2
	v_add_u32_e32 v212, 0, v3
	s_mov_b32 s61, -1
	v_add_u32_e32 v213, s91, v2
	v_add_u32_e32 v214, s92, v2
	v_mbcnt_hi_u32_b32 v215, -1, v0
	s_mov_b32 s97, -1
	s_barrier
	s_branch .LBB0_215

; #define PG8_STAGE(bufoff, gbase, voff) do { _Pragma("unroll") for (int _i = 0; _i < 2; ++_i) \
;         __builtin_amdgcn_global_load_lds((const unsigned*)((const char*)(gbase) + (voff)[_i]), (PG8_LAS unsigned*)(lds + (bufoff) + ldsw + _i * 8192), 16, 0, 0); } while (0)
; #define PG8_LDA(dst, b, h) do { _Pragma("unroll") for (int m = 0; m < 4; ++m) _Pragma("unroll") for (int k = 0; k < 2; ++k) dst[m][k] = *(const PG8_LAS bf16x8*)(lds + PG8_SA(b, h) + aoff + m * 2048 + k * 1024); } while (0)
; #define PG8_LDB(dst, b, h) do { _Pragma("unroll") for (int n = 0; n < 2; ++n) _Pragma("unroll") for (int k = 0; k < 2; ++k) dst[n][k] = *(const PG8_LAS bf16x8*)(lds + PG8_SB(b, h) + boff + n * 2048 + k * 1024); } while (0)
; #define PG8_WAIT_V(n) asm volatile("s_waitcnt vmcnt(" #n ")" ::: "memory")
; #define PG8_WAIT_L(n) asm volatile("s_waitcnt lgkmcnt(" #n ")" ::: "memory")
; #define PG8_BAR __builtin_amdgcn_s_barrier()
; #define PG8_SCHED __builtin_amdgcn_sched_barrier(0)
; template <class Epi, class Sched, bool ALIGN_EPI = false, bool SP2 = false>
; __device__ __forceinline__ void gemm_phase(PG8_LAS unsigned char* lds, const Gemm g, const Sched& S, const Epi& E) {
;     ...
;         const bool has_next = S.next(ui + 1, nxt);
;         const char* nA = has_next ? (const char*)g.A + (size_t)nxt.pm * tstepA : cA; const char* nB = has_next ? (const char*)g.Bt + (size_t)nxt.pn * tstepB : cB;
;         for (int t = 0; t < nt; t += 2) {
;             const bool last = (t == nt - 2);
;             const char* a1 = cA + (size_t)(t + 1) * kstepA;
;             const char* a2 = last ? nA : cA + (size_t)(t + 2) * kstepA; const char* b2 = last ? nB : cB + (size_t)(t + 2) * kstep;
;             const char* a3 = a2 + kstepA; const char* b3 = b2 + kstep;
;             if (last && has_next) S.a_ready(nxt);
;             if constexpr (SP2) {
;             PG8_LDB(B0, 0, 0); PG8_LDB(B1, 0, 1); PG8_SCHED; PG8_LDA(At, 0, 0); PG8_STAGE(PG8_SA(1, 1), a1 + hstepA, voffA);
;             PG8_WAIT_V(8); PG8_WAIT_L(0); PG8_BAR; PG8_MMA(0, 0, At, B0); PG8_MMA(0, 1, At, B1); PG8_BAR; PG8_SCHED;
;             PG8_LDA(At, 0, 1); PG8_STAGE(PG8_SB(0, 0), b2, voffB); PG8_STAGE(PG8_SB(0, 1), b2 + hstepB, voffB); PG8_STAGE(PG8_SA(0, 0), a2, voffA);
;             PG8_WAIT_V(8); PG8_WAIT_L(0); PG8_BAR; PG8_MMA(1, 0, At, B0); PG8_MMA(1, 1, At, B1); PG8_BAR; PG8_SCHED;
.LBB0_225:
	s_add_u32 s68, s68, 0x10000
	s_addc_u32 s69, s69, 0
	s_add_u32 s70, s70, 0x10000
	s_addc_u32 s71, s71, 0
	s_mov_b32 s73, -2
	s_waitcnt lgkmcnt(0)
	ds_read_b128 v[112:115], v210
	ds_read_b128 v[124:127], v210 offset:1024
	ds_read_b128 v[136:139], v210 offset:2048
	ds_read_b128 v[140:143], v210 offset:3072
	ds_read_b128 v[144:147], v211
	ds_read_b128 v[148:151], v211 offset:1024
	ds_read_b128 v[152:155], v211 offset:2048
	ds_read_b128 v[156:159], v211 offset:3072
	s_cmp_eq_u32 s73, 40
	s_cselect_b32 s9, s1, s69
	s_cselect_b32 s8, s0, s68
	s_cselect_b32 s75, s63, s71
	s_cselect_b32 s74, s62, s70
	v_lshl_add_u64 v[208:209], s[68:69], 0, v[184:185]
	v_lshl_add_u64 v[216:217], v[208:209], 0, s[96:97]
	s_add_i32 m0, s15, 0xc000
	ds_read_b128 v[160:163], v212
	ds_read_b128 v[164:167], v212 offset:1024
	ds_read_b128 v[168:171], v212 offset:2048
	ds_read_b128 v[172:175], v212 offset:3072
	ds_read_b128 v[176:179], v212 offset:4096
	ds_read_b128 v[180:183], v212 offset:5120
	ds_read_b128 v[220:223], v212 offset:6144
	ds_read_b128 v[224:227], v212 offset:7168
	global_load_lds_dwordx4 v[216:217], off
	v_lshl_add_u64 v[208:209], v[208:209], 0, s[60:61]
	s_add_i32 m0, s15, 0xe000
	s_nop 0
	global_load_lds_dwordx4 v[208:209], off
	s_waitcnt vmcnt(56)
	s_waitcnt lgkmcnt(0)
	s_barrier
	s_waitcnt lgkmcnt(0)
	v_mfma_f32_16x16x32_bf16 v[132:135], v[112:115], v[160:163], 0
	v_mfma_f32_16x16x32_bf16 v[128:131], v[136:139], v[160:163], 0
	v_mfma_f32_16x16x32_bf16 v[108:111], v[112:115], v[168:171], 0
	v_mfma_f32_16x16x32_bf16 v[104:107], v[136:139], v[168:171], 0
	v_mfma_f32_16x16x32_bf16 v[92:95], v[112:115], v[176:179], 0
	v_mfma_f32_16x16x32_bf16 v[88:91], v[136:139], v[176:179], 0
	v_mfma_f32_16x16x32_bf16 v[76:79], v[112:115], v[220:223], 0
	v_mfma_f32_16x16x32_bf16 v[72:75], v[136:139], v[220:223], 0
	v_mfma_f32_16x16x32_bf16 v[132:135], v[124:127], v[164:167], v[132:135]
	v_mfma_f32_16x16x32_bf16 v[128:131], v[140:143], v[164:167], v[128:131]
	v_mfma_f32_16x16x32_bf16 v[108:111], v[124:127], v[172:175], v[108:111]
	v_mfma_f32_16x16x32_bf16 v[104:107], v[140:143], v[172:175], v[104:107]
	v_mfma_f32_16x16x32_bf16 v[92:95], v[124:127], v[180:183], v[92:95]
	v_mfma_f32_16x16x32_bf16 v[88:91], v[140:143], v[180:183], v[88:91]
	v_mfma_f32_16x16x32_bf16 v[76:79], v[124:127], v[224:227], v[76:79]
	v_mfma_f32_16x16x32_bf16 v[72:75], v[140:143], v[224:227], v[72:75]
	v_mfma_f32_16x16x32_bf16 v[120:123], v[144:147], v[160:163], 0
	v_mfma_f32_16x16x32_bf16 v[116:119], v[152:155], v[160:163], 0
	v_mfma_f32_16x16x32_bf16 v[100:103], v[144:147], v[168:171], 0
	v_mfma_f32_16x16x32_bf16 v[96:99], v[152:155], v[168:171], 0
	v_mfma_f32_16x16x32_bf16 v[84:87], v[144:147], v[176:179], 0
	v_mfma_f32_16x16x32_bf16 v[80:83], v[152:155], v[176:179], 0
	v_mfma_f32_16x16x32_bf16 v[68:71], v[144:147], v[220:223], 0
	v_mfma_f32_16x16x32_bf16 v[64:67], v[152:155], v[220:223], 0
	v_mfma_f32_16x16x32_bf16 v[120:123], v[148:151], v[164:167], v[120:123]
	v_mfma_f32_16x16x32_bf16 v[116:119], v[156:159], v[164:167], v[116:119]
	v_mfma_f32_16x16x32_bf16 v[100:103], v[148:151], v[172:175], v[100:103]
	v_mfma_f32_16x16x32_bf16 v[96:99], v[156:159], v[172:175], v[96:99]
	v_mfma_f32_16x16x32_bf16 v[84:87], v[148:151], v[180:183], v[84:87]
	v_mfma_f32_16x16x32_bf16 v[80:83], v[156:159], v[180:183], v[80:83]
	v_mfma_f32_16x16x32_bf16 v[68:71], v[148:151], v[224:227], v[68:71]
	v_mfma_f32_16x16x32_bf16 v[64:67], v[156:159], v[224:227], v[64:67]
	s_barrier
	s_add_i32 s33, s89, s14
	v_lshl_add_u64 v[208:209], s[74:75], 0, v[184:185]
	s_mov_b32 m0, s33
	ds_read_b128 v[160:163], v212 offset:16384
	ds_read_b128 v[164:167], v212 offset:17408
	ds_read_b128 v[168:171], v212 offset:18432
	ds_read_b128 v[172:175], v212 offset:19456
	ds_read_b128 v[176:179], v212 offset:20480
	ds_read_b128 v[180:183], v212 offset:21504
	ds_read_b128 v[220:223], v212 offset:22528
	ds_read_b128 v[224:227], v212 offset:23552
	global_load_lds_dwordx4 v[208:209], off
	v_lshl_add_u64 v[216:217], v[208:209], 0, s[30:31]
	s_add_i32 m0, s33, 0x2000
	s_add_i32 s33, s90, s14
	global_load_lds_dwordx4 v[216:217], off
	v_lshl_add_u64 v[216:217], v[208:209], 0, s[34:35]
	s_mov_b32 m0, s33
	s_nop 0
	global_load_lds_dwordx4 v[216:217], off
	v_lshl_add_u64 v[216:217], v[208:209], 0, s[36:37]
	s_add_i32 m0, s33, 0x2000
	s_nop 0
	global_load_lds_dwordx4 v[216:217], off
	v_lshl_add_u64 v[216:217], s[8:9], 0, v[184:185]
	s_mov_b32 m0, s15
	v_lshl_add_u64 v[228:229], v[216:217], 0, s[30:31]
	global_load_lds_dwordx4 v[216:217], off
	s_mov_b32 m0, s17
	s_nop 0
	global_load_lds_dwordx4 v[228:229], off
	s_waitcnt vmcnt(56)
	s_waitcnt lgkmcnt(0)
	s_barrier
; #define PG8_STAGE(bufoff, gbase, voff) do { _Pragma("unroll") for (int _i = 0; _i < 2; ++_i) \
;         __builtin_amdgcn_global_load_lds((const unsigned*)((const char*)(gbase) + (voff)[_i]), (PG8_LAS unsigned*)(lds + (bufoff) + ldsw + _i * 8192), 16, 0, 0); } while (0)
; #define PG8_LDA(dst, b, h) do { _Pragma("unroll") for (int m = 0; m < 4; ++m) _Pragma("unroll") for (int k = 0; k < 2; ++k) dst[m][k] = *(const PG8_LAS bf16x8*)(lds + PG8_SA(b, h) + aoff + m * 2048 + k * 1024); } while (0)
; #define PG8_LDB(dst, b, h) do { _Pragma("unroll") for (int n = 0; n < 2; ++n) _Pragma("unroll") for (int k = 0; k < 2; ++k) dst[n][k] = *(const PG8_LAS bf16x8*)(lds + PG8_SB(b, h) + boff + n * 2048 + k * 1024); } while (0)
; #define PG8_MMA(ai, bj, At, Bt) do { __builtin_amdgcn_s_setprio(1); _Pragma("unroll") for (int m = 0; m < 4; ++m) _Pragma("unroll") for (int n = 0; n < 2; ++n) _Pragma("unroll") for (int k = 0; k < 2; ++k) \
;         acc[ai][bj][m][n] = __builtin_amdgcn_mfma_f32_16x16x32_bf16(Bt[n][k], At[m][k], acc[ai][bj][m][n], 0, 0, 0); __builtin_amdgcn_s_setprio(0); } while (0)
; #define PG8_WAIT_V(n) asm volatile("s_waitcnt vmcnt(" #n ")" ::: "memory")
; #define PG8_WAIT_L(n) asm volatile("s_waitcnt lgkmcnt(" #n ")" ::: "memory")
; #define PG8_BAR __builtin_amdgcn_s_barrier()
; #define PG8_SCHED __builtin_amdgcn_sched_barrier(0)
; template <class Epi, class Sched, bool ALIGN_EPI = false, bool SP2 = false>
; __device__ __forceinline__ void gemm_phase(PG8_LAS unsigned char* lds, const Gemm g, const Sched& S, const Epi& E) {
;     ...
;             PG8_WAIT_V(8); PG8_WAIT_L(0); PG8_BAR; PG8_MMA(1, 0, At, B0); PG8_MMA(1, 1, At, B1); PG8_BAR; PG8_SCHED;
;             PG8_LDB(B0, 1, 0); PG8_LDB(B1, 1, 1); PG8_SCHED; PG8_LDA(At, 1, 0); PG8_STAGE(PG8_SA(0, 1), a2 + hstepA, voffA);
;             PG8_WAIT_V(8); PG8_WAIT_L(0); PG8_BAR; PG8_MMA(0, 0, At, B0); PG8_MMA(0, 1, At, B1); PG8_BAR; PG8_SCHED;
	s_waitcnt lgkmcnt(0)
	v_mfma_f32_16x16x32_bf16 v[60:63], v[112:115], v[160:163], 0
	v_mfma_f32_16x16x32_bf16 v[56:59], v[136:139], v[160:163], 0
	v_mfma_f32_16x16x32_bf16 v[44:47], v[112:115], v[168:171], 0
	v_mfma_f32_16x16x32_bf16 v[40:43], v[136:139], v[168:171], 0
	v_mfma_f32_16x16x32_bf16 v[28:31], v[112:115], v[176:179], 0
	v_mfma_f32_16x16x32_bf16 v[24:27], v[136:139], v[176:179], 0
	v_mfma_f32_16x16x32_bf16 v[12:15], v[112:115], v[220:223], 0
	v_mfma_f32_16x16x32_bf16 v[8:11], v[136:139], v[220:223], 0
	v_mfma_f32_16x16x32_bf16 v[60:63], v[124:127], v[164:167], v[60:63]
	v_mfma_f32_16x16x32_bf16 v[56:59], v[140:143], v[164:167], v[56:59]
	v_mfma_f32_16x16x32_bf16 v[44:47], v[124:127], v[172:175], v[44:47]
	v_mfma_f32_16x16x32_bf16 v[40:43], v[140:143], v[172:175], v[40:43]
	v_mfma_f32_16x16x32_bf16 v[28:31], v[124:127], v[180:183], v[28:31]
	v_mfma_f32_16x16x32_bf16 v[24:27], v[140:143], v[180:183], v[24:27]
	v_mfma_f32_16x16x32_bf16 v[12:15], v[124:127], v[224:227], v[12:15]
	v_mfma_f32_16x16x32_bf16 v[8:11], v[140:143], v[224:227], v[8:11]
	v_mfma_f32_16x16x32_bf16 v[52:55], v[144:147], v[160:163], 0
	v_mfma_f32_16x16x32_bf16 v[48:51], v[152:155], v[160:163], 0
	v_mfma_f32_16x16x32_bf16 v[36:39], v[144:147], v[168:171], 0
	v_mfma_f32_16x16x32_bf16 v[32:35], v[152:155], v[168:171], 0
	v_mfma_f32_16x16x32_bf16 v[20:23], v[144:147], v[176:179], 0
	v_mfma_f32_16x16x32_bf16 v[16:19], v[152:155], v[176:179], 0
	v_mfma_f32_16x16x32_bf16 v[4:7], v[144:147], v[220:223], 0
	v_mfma_f32_16x16x32_bf16 v[0:3], v[152:155], v[220:223], 0
	v_mfma_f32_16x16x32_bf16 v[52:55], v[148:151], v[164:167], v[52:55]
	v_mfma_f32_16x16x32_bf16 v[48:51], v[156:159], v[164:167], v[48:51]
	v_mfma_f32_16x16x32_bf16 v[36:39], v[148:151], v[172:175], v[36:39]
	v_mfma_f32_16x16x32_bf16 v[32:35], v[156:159], v[172:175], v[32:35]
	v_mfma_f32_16x16x32_bf16 v[20:23], v[148:151], v[180:183], v[20:23]
	v_mfma_f32_16x16x32_bf16 v[16:19], v[156:159], v[180:183], v[16:19]
	v_mfma_f32_16x16x32_bf16 v[4:7], v[148:151], v[224:227], v[4:7]
	v_mfma_f32_16x16x32_bf16 v[0:3], v[156:159], v[224:227], v[0:3]
	s_barrier
	ds_read_b128 v[112:115], v213
	ds_read_b128 v[124:127], v213 offset:1024
	ds_read_b128 v[136:139], v213 offset:2048
	ds_read_b128 v[140:143], v213 offset:3072
	ds_read_b128 v[144:147], v214
	ds_read_b128 v[148:151], v214 offset:1024
	ds_read_b128 v[152:155], v214 offset:2048
	ds_read_b128 v[156:159], v214 offset:3072
	s_mov_b32 m0, s18
	v_lshl_add_u64 v[228:229], v[216:217], 0, s[34:35]
	ds_read_b128 v[160:163], v212 offset:32768
	ds_read_b128 v[164:167], v212 offset:33792
	ds_read_b128 v[168:171], v212 offset:34816
	ds_read_b128 v[172:175], v212 offset:35840
	ds_read_b128 v[176:179], v212 offset:36864
	ds_read_b128 v[180:183], v212 offset:37888
	ds_read_b128 v[220:223], v212 offset:38912
	ds_read_b128 v[224:227], v212 offset:39936
	global_load_lds_dwordx4 v[228:229], off
	v_lshl_add_u64 v[228:229], v[216:217], 0, s[36:37]
	s_mov_b32 m0, s19
	s_nop 0
	global_load_lds_dwordx4 v[228:229], off
	s_waitcnt vmcnt(8)
	s_waitcnt lgkmcnt(0)
	s_barrier
	s_waitcnt lgkmcnt(0)
	v_mfma_f32_16x16x32_bf16 v[132:135], v[112:115], v[160:163], v[132:135]
	v_mfma_f32_16x16x32_bf16 v[128:131], v[136:139], v[160:163], v[128:131]
	v_mfma_f32_16x16x32_bf16 v[108:111], v[112:115], v[168:171], v[108:111]
	v_mfma_f32_16x16x32_bf16 v[104:107], v[136:139], v[168:171], v[104:107]
	v_mfma_f32_16x16x32_bf16 v[92:95], v[112:115], v[176:179], v[92:95]
	v_mfma_f32_16x16x32_bf16 v[88:91], v[136:139], v[176:179], v[88:91]
	v_mfma_f32_16x16x32_bf16 v[76:79], v[112:115], v[220:223], v[76:79]
	v_mfma_f32_16x16x32_bf16 v[72:75], v[136:139], v[220:223], v[72:75]
	v_mfma_f32_16x16x32_bf16 v[132:135], v[124:127], v[164:167], v[132:135]
	v_mfma_f32_16x16x32_bf16 v[128:131], v[140:143], v[164:167], v[128:131]
	v_mfma_f32_16x16x32_bf16 v[108:111], v[124:127], v[172:175], v[108:111]
	v_mfma_f32_16x16x32_bf16 v[104:107], v[140:143], v[172:175], v[104:107]
	v_mfma_f32_16x16x32_bf16 v[92:95], v[124:127], v[180:183], v[92:95]
	v_mfma_f32_16x16x32_bf16 v[88:91], v[140:143], v[180:183], v[88:91]
	v_mfma_f32_16x16x32_bf16 v[76:79], v[124:127], v[224:227], v[76:79]
	v_mfma_f32_16x16x32_bf16 v[72:75], v[140:143], v[224:227], v[72:75]
	v_mfma_f32_16x16x32_bf16 v[120:123], v[144:147], v[160:163], v[120:123]
	v_mfma_f32_16x16x32_bf16 v[116:119], v[152:155], v[160:163], v[116:119]
	v_mfma_f32_16x16x32_bf16 v[100:103], v[144:147], v[168:171], v[100:103]
	v_mfma_f32_16x16x32_bf16 v[96:99], v[152:155], v[168:171], v[96:99]
	v_mfma_f32_16x16x32_bf16 v[84:87], v[144:147], v[176:179], v[84:87]
	v_mfma_f32_16x16x32_bf16 v[80:83], v[152:155], v[176:179], v[80:83]
	v_mfma_f32_16x16x32_bf16 v[68:71], v[144:147], v[220:223], v[68:71]
	v_mfma_f32_16x16x32_bf16 v[64:67], v[152:155], v[220:223], v[64:67]
	v_mfma_f32_16x16x32_bf16 v[120:123], v[148:151], v[164:167], v[120:123]
	v_mfma_f32_16x16x32_bf16 v[116:119], v[156:159], v[164:167], v[116:119]
	v_mfma_f32_16x16x32_bf16 v[100:103], v[148:151], v[172:175], v[100:103]
	v_mfma_f32_16x16x32_bf16 v[96:99], v[156:159], v[172:175], v[96:99]
	v_mfma_f32_16x16x32_bf16 v[84:87], v[148:151], v[180:183], v[84:87]
	v_mfma_f32_16x16x32_bf16 v[80:83], v[156:159], v[180:183], v[80:83]
	v_mfma_f32_16x16x32_bf16 v[68:71], v[148:151], v[224:227], v[68:71]
	v_mfma_f32_16x16x32_bf16 v[64:67], v[156:159], v[224:227], v[64:67]
	s_barrier
; #define PG8_STAGE(bufoff, gbase, voff) do { _Pragma("unroll") for (int _i = 0; _i < 2; ++_i) \
;         __builtin_amdgcn_global_load_lds((const unsigned*)((const char*)(gbase) + (voff)[_i]), (PG8_LAS unsigned*)(lds + (bufoff) + ldsw + _i * 8192), 16, 0, 0); } while (0)
; #define PG8_LDA(dst, b, h) do { _Pragma("unroll") for (int m = 0; m < 4; ++m) _Pragma("unroll") for (int k = 0; k < 2; ++k) dst[m][k] = *(const PG8_LAS bf16x8*)(lds + PG8_SA(b, h) + aoff + m * 2048 + k * 1024); } while (0)
; #define PG8_MMA(ai, bj, At, Bt) do { __builtin_amdgcn_s_setprio(1); _Pragma("unroll") for (int m = 0; m < 4; ++m) _Pragma("unroll") for (int n = 0; n < 2; ++n) _Pragma("unroll") for (int k = 0; k < 2; ++k) \
;         acc[ai][bj][m][n] = __builtin_amdgcn_mfma_f32_16x16x32_bf16(Bt[n][k], At[m][k], acc[ai][bj][m][n], 0, 0, 0); __builtin_amdgcn_s_setprio(0); } while (0)
; #define PG8_WAIT_V(n) asm volatile("s_waitcnt vmcnt(" #n ")" ::: "memory")
; #define PG8_WAIT_L(n) asm volatile("s_waitcnt lgkmcnt(" #n ")" ::: "memory")
; #define PG8_BAR __builtin_amdgcn_s_barrier()
; #define PG8_SCHED __builtin_amdgcn_sched_barrier(0)
; template <class Epi, class Sched, bool ALIGN_EPI = false, bool SP2 = false>
; __device__ __forceinline__ void gemm_phase(PG8_LAS unsigned char* lds, const Gemm g, const Sched& S, const Epi& E) {
;     ...
;         for (int t = 0; t < nt; t += 2) {
;     ...
;             PG8_LDA(At, 1, 1); PG8_STAGE(PG8_SB(1, 0), b3, voffB); PG8_STAGE(PG8_SB(1, 1), b3 + hstepB, voffB); PG8_STAGE(PG8_SA(1, 0), a3, voffA);
;             PG8_WAIT_V(8); PG8_WAIT_L(0); PG8_BAR; PG8_MMA(1, 0, At, B0); PG8_MMA(1, 1, At, B1); PG8_BAR; PG8_SCHED;
	s_add_i32 s8, s91, s14
	v_lshl_add_u64 v[228:229], v[208:209], 0, s[38:39]
	s_mov_b32 m0, s8
	ds_read_b128 v[160:163], v212 offset:49152
	ds_read_b128 v[164:167], v212 offset:50176
	ds_read_b128 v[168:171], v212 offset:51200
	ds_read_b128 v[172:175], v212 offset:52224
	ds_read_b128 v[176:179], v212 offset:53248
	ds_read_b128 v[180:183], v212 offset:54272
	ds_read_b128 v[220:223], v212 offset:55296
	ds_read_b128 v[224:227], v212 offset:56320
	global_load_lds_dwordx4 v[228:229], off
	v_lshl_add_u64 v[228:229], v[208:209], 0, s[40:41]
	s_add_i32 m0, s8, 0x2000
	s_add_i32 s8, s92, s14
	global_load_lds_dwordx4 v[228:229], off
	v_lshl_add_u64 v[228:229], v[208:209], 0, s[52:53]
	s_mov_b32 m0, s8
	v_lshl_add_u64 v[208:209], v[208:209], 0, s[54:55]
	global_load_lds_dwordx4 v[228:229], off
	s_add_i32 m0, s8, 0x2000
	s_nop 0
	global_load_lds_dwordx4 v[208:209], off
	v_lshl_add_u64 v[208:209], v[216:217], 0, s[38:39]
	s_mov_b32 m0, s78
	s_nop 0
	global_load_lds_dwordx4 v[208:209], off
	v_lshl_add_u64 v[208:209], v[216:217], 0, s[40:41]
	s_mov_b32 m0, s79
	s_nop 0
	global_load_lds_dwordx4 v[208:209], off
	s_waitcnt vmcnt(8)
	s_waitcnt lgkmcnt(0)
	s_barrier
	s_waitcnt lgkmcnt(0)
	v_mfma_f32_16x16x32_bf16 v[60:63], v[112:115], v[160:163], v[60:63]
	v_mfma_f32_16x16x32_bf16 v[56:59], v[136:139], v[160:163], v[56:59]
	v_mfma_f32_16x16x32_bf16 v[44:47], v[112:115], v[168:171], v[44:47]
	v_mfma_f32_16x16x32_bf16 v[40:43], v[136:139], v[168:171], v[40:43]
	v_mfma_f32_16x16x32_bf16 v[28:31], v[112:115], v[176:179], v[28:31]
	v_mfma_f32_16x16x32_bf16 v[24:27], v[136:139], v[176:179], v[24:27]
	v_mfma_f32_16x16x32_bf16 v[12:15], v[112:115], v[220:223], v[12:15]
	v_mfma_f32_16x16x32_bf16 v[8:11], v[136:139], v[220:223], v[8:11]
	v_mfma_f32_16x16x32_bf16 v[60:63], v[124:127], v[164:167], v[60:63]
	v_mfma_f32_16x16x32_bf16 v[56:59], v[140:143], v[164:167], v[56:59]
	v_mfma_f32_16x16x32_bf16 v[44:47], v[124:127], v[172:175], v[44:47]
	v_mfma_f32_16x16x32_bf16 v[40:43], v[140:143], v[172:175], v[40:43]
	v_mfma_f32_16x16x32_bf16 v[28:31], v[124:127], v[180:183], v[28:31]
	v_mfma_f32_16x16x32_bf16 v[24:27], v[140:143], v[180:183], v[24:27]
	v_mfma_f32_16x16x32_bf16 v[12:15], v[124:127], v[224:227], v[12:15]
	v_mfma_f32_16x16x32_bf16 v[8:11], v[140:143], v[224:227], v[8:11]
	v_mfma_f32_16x16x32_bf16 v[52:55], v[144:147], v[160:163], v[52:55]
	v_mfma_f32_16x16x32_bf16 v[48:51], v[152:155], v[160:163], v[48:51]
	v_mfma_f32_16x16x32_bf16 v[36:39], v[144:147], v[168:171], v[36:39]
	v_mfma_f32_16x16x32_bf16 v[32:35], v[152:155], v[168:171], v[32:35]
	v_mfma_f32_16x16x32_bf16 v[20:23], v[144:147], v[176:179], v[20:23]
	v_mfma_f32_16x16x32_bf16 v[16:19], v[152:155], v[176:179], v[16:19]
	v_mfma_f32_16x16x32_bf16 v[4:7], v[144:147], v[220:223], v[4:7]
	v_mfma_f32_16x16x32_bf16 v[0:3], v[152:155], v[220:223], v[0:3]
	v_mfma_f32_16x16x32_bf16 v[52:55], v[148:151], v[164:167], v[52:55]
	v_mfma_f32_16x16x32_bf16 v[48:51], v[156:159], v[164:167], v[48:51]
	v_mfma_f32_16x16x32_bf16 v[36:39], v[148:151], v[172:175], v[36:39]
	v_mfma_f32_16x16x32_bf16 v[32:35], v[156:159], v[172:175], v[32:35]
	v_mfma_f32_16x16x32_bf16 v[20:23], v[148:151], v[180:183], v[20:23]
	v_mfma_f32_16x16x32_bf16 v[16:19], v[156:159], v[180:183], v[16:19]
	v_mfma_f32_16x16x32_bf16 v[4:7], v[148:151], v[224:227], v[4:7]
	v_mfma_f32_16x16x32_bf16 v[0:3], v[156:159], v[224:227], v[0:3]
	s_barrier
	s_add_i32 s73, s73, 2
	s_add_u32 s68, s68, 0x10000
	s_addc_u32 s69, s69, 0
	s_add_u32 s70, s70, 0x10000
	s_addc_u32 s71, s71, 0
	s_cmp_gt_u32 s73, 41

; #define PG8_STAGE(bufoff, gbase, voff) do { _Pragma("unroll") for (int _i = 0; _i < 2; ++_i) \
;         __builtin_amdgcn_global_load_lds((const unsigned*)((const char*)(gbase) + (voff)[_i]), (PG8_LAS unsigned*)(lds + (bufoff) + ldsw + _i * 8192), 16, 0, 0); } while (0)
; #define PG8_WAIT_V(n) asm volatile("s_waitcnt vmcnt(" #n ")" ::: "memory")
; #define PG8_BAR __builtin_amdgcn_s_barrier()
; template <class Epi, class Sched, bool ALIGN_EPI = false, bool SP2 = false>
; __device__ __forceinline__ void gemm_phase(PG8_LAS unsigned char* lds, const Gemm g, const Sched& S, const Epi& E) {
;     const int tid = threadIdx.x, wid = __builtin_amdgcn_readfirstlane(tid >> 6), lane = tid & 63, wr = wid >> 2, wc = wid & 3, fr = lane & 15, fq = lane >> 4;
;     const int K = g.K, nt = K / BK;
;     unsigned voffA[2], voffB[2];
; #pragma unroll
;     for (int i = 0; i < 2; ++i) { int R, C; stage_rc(tid * 16 + i * 8192, R, C); const int Rb = Epi::PERM ? ((R & ~31) + perm32(R & 31)) : R;
;         voffA[i] = g.a_pre ? (unsigned)(tid * 16 + i * 8192) : (unsigned)(R * g.lda + C) * 2u; voffB[i] = g.b_pre ? (unsigned)(tid * 16 + i * 8192) : (unsigned)(Rb * g.ldb + C) * 2u; }
;     const size_t kstep = g.b_pre ? (size_t)(2 * HTB) : (size_t)(BK * 2);
;     const size_t hstepA = (size_t)HALF * g.lda * 2, hstepB = (size_t)HALF * g.ldb * 2;
;     const size_t tstepA = g.pstepA, tstepB = g.b_pre ? (size_t)(g.K / BK) * (2 * HTB) : 2 * hstepB;
;     const size_t kstepA = g.kstepA;
;     const unsigned ldsw = (unsigned)wid * 1024u;
;     const int aoff = lds_byte(wr * 64 + fr, fq * 8), boff = lds_byte(wc * 32 + fr, fq * 8);
;     ...
;     if constexpr (SP2) {
;         PG8_STAGE(PG8_SB(0, 0), cB, voffB); PG8_STAGE(PG8_SB(0, 1), cB + hstepB, voffB); PG8_STAGE(PG8_SA(0, 0), cA, voffA); PG8_STAGE(PG8_SA(0, 1), cA + hstepA, voffA);
;         PG8_STAGE(PG8_SB(1, 0), cB + kstep, voffB); PG8_STAGE(PG8_SA(1, 0), cA + kstepA, voffA); PG8_STAGE(PG8_SB(1, 1), cB + hstepB + kstep, voffB);
;         if (wr == 1) PG8_BAR;
;         PG8_WAIT_V(8); PG8_BAR;
;         PG8_WAIT_V(6); PG8_BAR;
.LBB0_309:
	v_and_b32_e32 v3, 48, v188
	v_lshlrev_b32_e32 v5, 2, v154
	s_and_b32 s3, s3, 3
	v_bfe_u32 v1, v188, 4, 2
	s_lshl_b32 s7, s2, 13
	v_lshl_or_b32 v4, v154, 6, v3
	v_and_b32_e32 v5, 32, v5
	v_lshlrev_b32_e32 v2, 3, v1
	v_bitop3_b32 v4, v4, s7, v5 bitop3:0xde
	s_lshl_b32 s7, s3, 12
	v_or_b32_e32 v3, v155, v3
	v_lshl_or_b32 v158, s3, 5, v2
	s_cmpk_lt_u32 s14, 0x100
	v_lshlrev_b32_e32 v2, 4, v154
	v_bitop3_b32 v5, s7, v3, v156 bitop3:0xf6
	s_waitcnt vmcnt(8)
	s_barrier
	s_waitcnt vmcnt(0)
	s_cselect_b64 s[58:59], -1, 0
	s_lshl_b32 s7, s2, 5
	v_lshl_or_b32 v2, v1, 8, v2
	v_mov_b32_e32 v3, v0
	s_lshl_b32 s8, s3, 3
	v_lshl_or_b32 v157, s2, 6, v154
	v_lshl_add_u64 v[2:3], s[22:23], 0, v[2:3]
	s_mov_b64 s[2:3], 0x1c000000
	s_or_b32 s14, s7, s8
	s_add_i32 s15, 0, 0x10000
	s_add_i32 s18, 0, 0x14000
	s_add_i32 s19, 0, 0x18000
	s_add_i32 s80, 0, 0x1c000
	s_ashr_i32 s97, s26, 31
	s_mov_b32 s82, s26
	s_ashr_i32 s17, s16, 31
	v_lshl_add_u64 v[134:135], v[2:3], 0, s[2:3]
	s_addk_i32 s14, 0xfe40
	v_mov_b64_e32 v[136:137], 0x780
	v_mov_b64_e32 v[138:139], 0x77f
	v_add_u32_e32 v159, s15, v5
	v_add_u32_e32 v160, s18, v5
	v_add_u32_e32 v161, 0, v4
	v_add_u32_e32 v162, s19, v5
	v_add_u32_e32 v163, s80, v5
	v_mov_b32_e32 v164, 0x358637bd
	s_movk_i32 s81, 0x1e00
	v_mov_b32_e32 v165, 0x3e38aa3b
	s_barrier
	s_branch .LBB0_312

; #define PG8_STAGE(bufoff, gbase, voff) do { _Pragma("unroll") for (int _i = 0; _i < 2; ++_i) \
;         __builtin_amdgcn_global_load_lds((const unsigned*)((const char*)(gbase) + (voff)[_i]), (PG8_LAS unsigned*)(lds + (bufoff) + ldsw + _i * 8192), 16, 0, 0); } while (0)
; #define PG8_LDA(dst, b, h) do { _Pragma("unroll") for (int m = 0; m < 4; ++m) _Pragma("unroll") for (int k = 0; k < 2; ++k) dst[m][k] = *(const PG8_LAS bf16x8*)(lds + PG8_SA(b, h) + aoff + m * 2048 + k * 1024); } while (0)
; #define PG8_LDB(dst, b, h) do { _Pragma("unroll") for (int n = 0; n < 2; ++n) _Pragma("unroll") for (int k = 0; k < 2; ++k) dst[n][k] = *(const PG8_LAS bf16x8*)(lds + PG8_SB(b, h) + boff + n * 2048 + k * 1024); } while (0)
; #define PG8_WAIT_V(n) asm volatile("s_waitcnt vmcnt(" #n ")" ::: "memory")
; #define PG8_WAIT_L(n) asm volatile("s_waitcnt lgkmcnt(" #n ")" ::: "memory")
; #define PG8_BAR __builtin_amdgcn_s_barrier()
; #define PG8_SCHED __builtin_amdgcn_sched_barrier(0)
; template <class Epi, class Sched, bool ALIGN_EPI = false, bool SP2 = false>
; __device__ __forceinline__ void gemm_phase(PG8_LAS unsigned char* lds, const Gemm g, const Sched& S, const Epi& E) {
;     ...
;         const bool has_next = S.next(ui + 1, nxt);
;         const char* nA = has_next ? (const char*)g.A + (size_t)nxt.pm * tstepA : cA; const char* nB = has_next ? (const char*)g.Bt + (size_t)nxt.pn * tstepB : cB;
;         for (int t = 0; t < nt; t += 2) {
;             const bool last = (t == nt - 2);
;             const char* a1 = cA + (size_t)(t + 1) * kstepA;
;             const char* a2 = last ? nA : cA + (size_t)(t + 2) * kstepA; const char* b2 = last ? nB : cB + (size_t)(t + 2) * kstep;
;             const char* a3 = a2 + kstepA; const char* b3 = b2 + kstep;
;             if (last && has_next) S.a_ready(nxt);
;             if constexpr (SP2) {
;             PG8_LDB(B0, 0, 0); PG8_LDB(B1, 0, 1); PG8_SCHED; PG8_LDA(At, 0, 0); PG8_STAGE(PG8_SA(1, 1), a1 + hstepA, voffA);
;             PG8_WAIT_V(8); PG8_WAIT_L(0); PG8_BAR; PG8_MMA(0, 0, At, B0); PG8_MMA(0, 1, At, B1); PG8_BAR; PG8_SCHED;
;             PG8_LDA(At, 0, 1); PG8_STAGE(PG8_SB(0, 0), b2, voffB); PG8_STAGE(PG8_SB(0, 1), b2 + hstepB, voffB); PG8_STAGE(PG8_SA(0, 0), a2, voffA);
;             PG8_WAIT_V(8); PG8_WAIT_L(0); PG8_BAR; PG8_MMA(1, 0, At, B0); PG8_MMA(1, 1, At, B1); PG8_BAR; PG8_SCHED;
.LBB0_314:
	s_ashr_i32 s63, s62, 31
	s_lshl_b64 s[8:9], s[62:63], 19
	s_add_u32 s68, s12, s8
	s_addc_u32 s69, s13, s9
	s_and_b64 s[8:9], s[2:3], exec
	s_cselect_b32 s7, s69, s5
	s_cselect_b32 s63, s68, s4
	s_ashr_i32 s61, s60, 31
	s_lshl_b64 s[8:9], s[60:61], 19
	s_add_u32 s70, s87, s8
	s_addc_u32 s71, s88, s9
	s_and_b64 s[8:9], s[2:3], exec
	s_cselect_b32 s61, s71, s75
	s_cselect_b32 s73, s70, s74
	s_add_u32 s4, s4, 0x10000
	s_addc_u32 s5, s5, 0
	s_add_u32 s74, s74, 0x10000
	s_addc_u32 s75, s75, 0
	s_mov_b32 s76, -2
	ds_read_b128 v[140:143], v159
	ds_read_b128 v[144:147], v159 offset:1024
	ds_read_b128 v[148:151], v159 offset:2048
	ds_read_b128 v[166:169], v159 offset:3072
	ds_read_b128 v[170:173], v160
	ds_read_b128 v[174:177], v160 offset:1024
	ds_read_b128 v[178:181], v160 offset:2048
	ds_read_b128 v[182:185], v160 offset:3072
	s_cmp_eq_u32 s76, 12
	s_cselect_b32 s9, s7, s5
	s_cselect_b32 s8, s63, s4
	s_cselect_b32 vcc_hi, s61, s75
	s_cselect_b32 vcc_lo, s73, s74
	s_movk_i32 s78, 0xc000
	v_lshl_add_u64 v[2:3], s[4:5], 0, v[132:133]
	s_mov_b32 s79, -1
	v_lshl_add_u64 v[152:153], v[2:3], 0, s[78:79]
	s_movk_i32 s78, 0xe000
	s_add_i32 m0, s90, 0xc000
	s_mov_b32 s79, -1
	ds_read_b128 v[190:193], v161
	ds_read_b128 v[194:197], v161 offset:1024
	ds_read_b128 v[198:201], v161 offset:2048
	ds_read_b128 v[202:205], v161 offset:3072
	ds_read_b128 v[206:209], v161 offset:4096
	ds_read_b128 v[210:213], v161 offset:5120
	ds_read_b128 v[214:217], v161 offset:6144
	ds_read_b128 v[220:223], v161 offset:7168
	global_load_lds_dwordx4 v[152:153], off
	v_lshl_add_u64 v[2:3], v[2:3], 0, s[78:79]
	s_add_i32 m0, s90, 0xe000
	s_nop 0
	global_load_lds_dwordx4 v[2:3], off
	s_waitcnt vmcnt(56)
	s_waitcnt lgkmcnt(0)
	s_barrier
	s_waitcnt lgkmcnt(0)
	v_mfma_f32_16x16x32_bf16 v[128:131], v[140:143], v[190:193], 0
	v_mfma_f32_16x16x32_bf16 v[124:127], v[148:151], v[190:193], 0
	v_mfma_f32_16x16x32_bf16 v[112:115], v[140:143], v[198:201], 0
	v_mfma_f32_16x16x32_bf16 v[108:111], v[148:151], v[198:201], 0
	v_mfma_f32_16x16x32_bf16 v[96:99], v[140:143], v[206:209], 0
	v_mfma_f32_16x16x32_bf16 v[92:95], v[148:151], v[206:209], 0
	v_mfma_f32_16x16x32_bf16 v[80:83], v[140:143], v[214:217], 0
	v_mfma_f32_16x16x32_bf16 v[76:79], v[148:151], v[214:217], 0
	v_mfma_f32_16x16x32_bf16 v[128:131], v[144:147], v[194:197], v[128:131]
	v_mfma_f32_16x16x32_bf16 v[124:127], v[166:169], v[194:197], v[124:127]
	v_mfma_f32_16x16x32_bf16 v[112:115], v[144:147], v[202:205], v[112:115]
	v_mfma_f32_16x16x32_bf16 v[108:111], v[166:169], v[202:205], v[108:111]
	v_mfma_f32_16x16x32_bf16 v[96:99], v[144:147], v[210:213], v[96:99]
	v_mfma_f32_16x16x32_bf16 v[92:95], v[166:169], v[210:213], v[92:95]
	v_mfma_f32_16x16x32_bf16 v[80:83], v[144:147], v[220:223], v[80:83]
	v_mfma_f32_16x16x32_bf16 v[76:79], v[166:169], v[220:223], v[76:79]
	v_mfma_f32_16x16x32_bf16 v[120:123], v[170:173], v[190:193], 0
	v_mfma_f32_16x16x32_bf16 v[116:119], v[178:181], v[190:193], 0
	v_mfma_f32_16x16x32_bf16 v[104:107], v[170:173], v[198:201], 0
	v_mfma_f32_16x16x32_bf16 v[100:103], v[178:181], v[198:201], 0
	v_mfma_f32_16x16x32_bf16 v[88:91], v[170:173], v[206:209], 0
	v_mfma_f32_16x16x32_bf16 v[84:87], v[178:181], v[206:209], 0
	v_mfma_f32_16x16x32_bf16 v[72:75], v[170:173], v[214:217], 0
	v_mfma_f32_16x16x32_bf16 v[68:71], v[178:181], v[214:217], 0
	v_mfma_f32_16x16x32_bf16 v[120:123], v[174:177], v[194:197], v[120:123]
	v_mfma_f32_16x16x32_bf16 v[116:119], v[182:185], v[194:197], v[116:119]
	v_mfma_f32_16x16x32_bf16 v[104:107], v[174:177], v[202:205], v[104:107]
	v_mfma_f32_16x16x32_bf16 v[100:103], v[182:185], v[202:205], v[100:103]
	v_mfma_f32_16x16x32_bf16 v[88:91], v[174:177], v[210:213], v[88:91]
	v_mfma_f32_16x16x32_bf16 v[84:87], v[182:185], v[210:213], v[84:87]
	v_mfma_f32_16x16x32_bf16 v[72:75], v[174:177], v[220:223], v[72:75]
	v_mfma_f32_16x16x32_bf16 v[68:71], v[182:185], v[220:223], v[68:71]
	s_barrier
	s_add_i32 s77, s15, s89
	v_lshl_add_u64 v[152:153], vcc, 0, v[132:133]
	s_mov_b32 m0, s77
	ds_read_b128 v[190:193], v161 offset:16384
	ds_read_b128 v[194:197], v161 offset:17408
	ds_read_b128 v[198:201], v161 offset:18432
	ds_read_b128 v[202:205], v161 offset:19456
	ds_read_b128 v[206:209], v161 offset:20480
	ds_read_b128 v[210:213], v161 offset:21504
	ds_read_b128 v[214:217], v161 offset:22528
	ds_read_b128 v[220:223], v161 offset:23552
	global_load_lds_dwordx4 v[152:153], off
	v_lshl_add_u64 v[2:3], v[152:153], 0, s[30:31]
	s_add_i32 m0, s77, 0x2000
	s_add_i32 s77, s18, s89
	global_load_lds_dwordx4 v[2:3], off
	v_lshl_add_u64 v[2:3], v[152:153], 0, s[34:35]
	s_mov_b32 m0, s77
	v_lshl_add_u64 v[186:187], s[8:9], 0, v[132:133]
	global_load_lds_dwordx4 v[2:3], off
	v_lshl_add_u64 v[2:3], v[152:153], 0, s[36:37]
	s_add_i32 m0, s77, 0x2000
	s_nop 0
	global_load_lds_dwordx4 v[2:3], off
	s_mov_b32 m0, s90
	v_lshl_add_u64 v[2:3], v[186:187], 0, s[30:31]
	global_load_lds_dwordx4 v[186:187], off
	s_mov_b32 m0, s91
	s_nop 0
	global_load_lds_dwordx4 v[2:3], off
	s_waitcnt vmcnt(56)
	s_waitcnt lgkmcnt(0)
	s_barrier
; #define PG8_STAGE(bufoff, gbase, voff) do { _Pragma("unroll") for (int _i = 0; _i < 2; ++_i) \
;         __builtin_amdgcn_global_load_lds((const unsigned*)((const char*)(gbase) + (voff)[_i]), (PG8_LAS unsigned*)(lds + (bufoff) + ldsw + _i * 8192), 16, 0, 0); } while (0)
; #define PG8_LDA(dst, b, h) do { _Pragma("unroll") for (int m = 0; m < 4; ++m) _Pragma("unroll") for (int k = 0; k < 2; ++k) dst[m][k] = *(const PG8_LAS bf16x8*)(lds + PG8_SA(b, h) + aoff + m * 2048 + k * 1024); } while (0)
; #define PG8_LDB(dst, b, h) do { _Pragma("unroll") for (int n = 0; n < 2; ++n) _Pragma("unroll") for (int k = 0; k < 2; ++k) dst[n][k] = *(const PG8_LAS bf16x8*)(lds + PG8_SB(b, h) + boff + n * 2048 + k * 1024); } while (0)
; #define PG8_MMA(ai, bj, At, Bt) do { __builtin_amdgcn_s_setprio(1); _Pragma("unroll") for (int m = 0; m < 4; ++m) _Pragma("unroll") for (int n = 0; n < 2; ++n) _Pragma("unroll") for (int k = 0; k < 2; ++k) \
;         acc[ai][bj][m][n] = __builtin_amdgcn_mfma_f32_16x16x32_bf16(Bt[n][k], At[m][k], acc[ai][bj][m][n], 0, 0, 0); __builtin_amdgcn_s_setprio(0); } while (0)
; #define PG8_WAIT_V(n) asm volatile("s_waitcnt vmcnt(" #n ")" ::: "memory")
; #define PG8_WAIT_L(n) asm volatile("s_waitcnt lgkmcnt(" #n ")" ::: "memory")
; #define PG8_BAR __builtin_amdgcn_s_barrier()
; #define PG8_SCHED __builtin_amdgcn_sched_barrier(0)
; template <class Epi, class Sched, bool ALIGN_EPI = false, bool SP2 = false>
; __device__ __forceinline__ void gemm_phase(PG8_LAS unsigned char* lds, const Gemm g, const Sched& S, const Epi& E) {
;     ...
;             PG8_WAIT_V(8); PG8_WAIT_L(0); PG8_BAR; PG8_MMA(1, 0, At, B0); PG8_MMA(1, 1, At, B1); PG8_BAR; PG8_SCHED;
;             PG8_LDB(B0, 1, 0); PG8_LDB(B1, 1, 1); PG8_SCHED; PG8_LDA(At, 1, 0); PG8_STAGE(PG8_SA(0, 1), a2 + hstepA, voffA);
;             PG8_WAIT_V(8); PG8_WAIT_L(0); PG8_BAR; PG8_MMA(0, 0, At, B0); PG8_MMA(0, 1, At, B1); PG8_BAR; PG8_SCHED;
	s_waitcnt lgkmcnt(0)
	v_mfma_f32_16x16x32_bf16 v[64:67], v[140:143], v[190:193], 0
	v_mfma_f32_16x16x32_bf16 v[60:63], v[148:151], v[190:193], 0
	v_mfma_f32_16x16x32_bf16 v[48:51], v[140:143], v[198:201], 0
	v_mfma_f32_16x16x32_bf16 v[44:47], v[148:151], v[198:201], 0
	v_mfma_f32_16x16x32_bf16 v[32:35], v[140:143], v[206:209], 0
	v_mfma_f32_16x16x32_bf16 v[28:31], v[148:151], v[206:209], 0
	v_mfma_f32_16x16x32_bf16 v[16:19], v[140:143], v[214:217], 0
	v_mfma_f32_16x16x32_bf16 v[12:15], v[148:151], v[214:217], 0
	v_mfma_f32_16x16x32_bf16 v[64:67], v[144:147], v[194:197], v[64:67]
	v_mfma_f32_16x16x32_bf16 v[60:63], v[166:169], v[194:197], v[60:63]
	v_mfma_f32_16x16x32_bf16 v[48:51], v[144:147], v[202:205], v[48:51]
	v_mfma_f32_16x16x32_bf16 v[44:47], v[166:169], v[202:205], v[44:47]
	v_mfma_f32_16x16x32_bf16 v[32:35], v[144:147], v[210:213], v[32:35]
	v_mfma_f32_16x16x32_bf16 v[28:31], v[166:169], v[210:213], v[28:31]
	v_mfma_f32_16x16x32_bf16 v[16:19], v[144:147], v[220:223], v[16:19]
	v_mfma_f32_16x16x32_bf16 v[12:15], v[166:169], v[220:223], v[12:15]
	v_mfma_f32_16x16x32_bf16 v[56:59], v[170:173], v[190:193], 0
	v_mfma_f32_16x16x32_bf16 v[52:55], v[178:181], v[190:193], 0
	v_mfma_f32_16x16x32_bf16 v[40:43], v[170:173], v[198:201], 0
	v_mfma_f32_16x16x32_bf16 v[36:39], v[178:181], v[198:201], 0
	v_mfma_f32_16x16x32_bf16 v[24:27], v[170:173], v[206:209], 0
	v_mfma_f32_16x16x32_bf16 v[20:23], v[178:181], v[206:209], 0
	v_mfma_f32_16x16x32_bf16 v[8:11], v[170:173], v[214:217], 0
	v_mfma_f32_16x16x32_bf16 v[2:5], v[178:181], v[214:217], 0
	v_mfma_f32_16x16x32_bf16 v[56:59], v[174:177], v[194:197], v[56:59]
	v_mfma_f32_16x16x32_bf16 v[52:55], v[182:185], v[194:197], v[52:55]
	v_mfma_f32_16x16x32_bf16 v[40:43], v[174:177], v[202:205], v[40:43]
	v_mfma_f32_16x16x32_bf16 v[36:39], v[182:185], v[202:205], v[36:39]
	v_mfma_f32_16x16x32_bf16 v[24:27], v[174:177], v[210:213], v[24:27]
	v_mfma_f32_16x16x32_bf16 v[20:23], v[182:185], v[210:213], v[20:23]
	v_mfma_f32_16x16x32_bf16 v[8:11], v[174:177], v[220:223], v[8:11]
	v_mfma_f32_16x16x32_bf16 v[2:5], v[182:185], v[220:223], v[2:5]
	s_barrier
	ds_read_b128 v[140:143], v162
	ds_read_b128 v[144:147], v162 offset:1024
	ds_read_b128 v[148:151], v162 offset:2048
	ds_read_b128 v[166:169], v162 offset:3072
	ds_read_b128 v[170:173], v163
	ds_read_b128 v[174:177], v163 offset:1024
	ds_read_b128 v[178:181], v163 offset:2048
	ds_read_b128 v[182:185], v163 offset:3072
	s_mov_b32 m0, s92
	v_lshl_add_u64 v[6:7], v[186:187], 0, s[34:35]
	ds_read_b128 v[190:193], v161 offset:32768
	ds_read_b128 v[194:197], v161 offset:33792
	ds_read_b128 v[198:201], v161 offset:34816
	ds_read_b128 v[202:205], v161 offset:35840
	ds_read_b128 v[206:209], v161 offset:36864
	ds_read_b128 v[210:213], v161 offset:37888
	ds_read_b128 v[214:217], v161 offset:38912
	ds_read_b128 v[220:223], v161 offset:39936
	global_load_lds_dwordx4 v[6:7], off
	v_lshl_add_u64 v[6:7], v[186:187], 0, s[36:37]
	s_mov_b32 m0, s93
	s_nop 0
	global_load_lds_dwordx4 v[6:7], off
	s_waitcnt vmcnt(8)
	s_waitcnt lgkmcnt(0)
	s_barrier
	s_waitcnt lgkmcnt(0)
	v_mfma_f32_16x16x32_bf16 v[128:131], v[140:143], v[190:193], v[128:131]
	v_mfma_f32_16x16x32_bf16 v[124:127], v[148:151], v[190:193], v[124:127]
	v_mfma_f32_16x16x32_bf16 v[112:115], v[140:143], v[198:201], v[112:115]
	v_mfma_f32_16x16x32_bf16 v[108:111], v[148:151], v[198:201], v[108:111]
	v_mfma_f32_16x16x32_bf16 v[96:99], v[140:143], v[206:209], v[96:99]
	v_mfma_f32_16x16x32_bf16 v[92:95], v[148:151], v[206:209], v[92:95]
	v_mfma_f32_16x16x32_bf16 v[80:83], v[140:143], v[214:217], v[80:83]
	v_mfma_f32_16x16x32_bf16 v[76:79], v[148:151], v[214:217], v[76:79]
	v_mfma_f32_16x16x32_bf16 v[128:131], v[144:147], v[194:197], v[128:131]
	v_mfma_f32_16x16x32_bf16 v[124:127], v[166:169], v[194:197], v[124:127]
	v_mfma_f32_16x16x32_bf16 v[112:115], v[144:147], v[202:205], v[112:115]
	v_mfma_f32_16x16x32_bf16 v[108:111], v[166:169], v[202:205], v[108:111]
	v_mfma_f32_16x16x32_bf16 v[96:99], v[144:147], v[210:213], v[96:99]
	v_mfma_f32_16x16x32_bf16 v[92:95], v[166:169], v[210:213], v[92:95]
	v_mfma_f32_16x16x32_bf16 v[80:83], v[144:147], v[220:223], v[80:83]
	v_mfma_f32_16x16x32_bf16 v[76:79], v[166:169], v[220:223], v[76:79]
	v_mfma_f32_16x16x32_bf16 v[120:123], v[170:173], v[190:193], v[120:123]
	v_mfma_f32_16x16x32_bf16 v[116:119], v[178:181], v[190:193], v[116:119]
	v_mfma_f32_16x16x32_bf16 v[104:107], v[170:173], v[198:201], v[104:107]
	v_mfma_f32_16x16x32_bf16 v[100:103], v[178:181], v[198:201], v[100:103]
	v_mfma_f32_16x16x32_bf16 v[88:91], v[170:173], v[206:209], v[88:91]
	v_mfma_f32_16x16x32_bf16 v[84:87], v[178:181], v[206:209], v[84:87]
	v_mfma_f32_16x16x32_bf16 v[72:75], v[170:173], v[214:217], v[72:75]
	v_mfma_f32_16x16x32_bf16 v[68:71], v[178:181], v[214:217], v[68:71]
	v_mfma_f32_16x16x32_bf16 v[120:123], v[174:177], v[194:197], v[120:123]
	v_mfma_f32_16x16x32_bf16 v[116:119], v[182:185], v[194:197], v[116:119]
	v_mfma_f32_16x16x32_bf16 v[104:107], v[174:177], v[202:205], v[104:107]
	v_mfma_f32_16x16x32_bf16 v[100:103], v[182:185], v[202:205], v[100:103]
	v_mfma_f32_16x16x32_bf16 v[88:91], v[174:177], v[210:213], v[88:91]
	v_mfma_f32_16x16x32_bf16 v[84:87], v[182:185], v[210:213], v[84:87]
	v_mfma_f32_16x16x32_bf16 v[72:75], v[174:177], v[220:223], v[72:75]
	v_mfma_f32_16x16x32_bf16 v[68:71], v[182:185], v[220:223], v[68:71]
	s_barrier
; #define PG8_STAGE(bufoff, gbase, voff) do { _Pragma("unroll") for (int _i = 0; _i < 2; ++_i) \
;         __builtin_amdgcn_global_load_lds((const unsigned*)((const char*)(gbase) + (voff)[_i]), (PG8_LAS unsigned*)(lds + (bufoff) + ldsw + _i * 8192), 16, 0, 0); } while (0)
; #define PG8_LDA(dst, b, h) do { _Pragma("unroll") for (int m = 0; m < 4; ++m) _Pragma("unroll") for (int k = 0; k < 2; ++k) dst[m][k] = *(const PG8_LAS bf16x8*)(lds + PG8_SA(b, h) + aoff + m * 2048 + k * 1024); } while (0)
; #define PG8_MMA(ai, bj, At, Bt) do { __builtin_amdgcn_s_setprio(1); _Pragma("unroll") for (int m = 0; m < 4; ++m) _Pragma("unroll") for (int n = 0; n < 2; ++n) _Pragma("unroll") for (int k = 0; k < 2; ++k) \
;         acc[ai][bj][m][n] = __builtin_amdgcn_mfma_f32_16x16x32_bf16(Bt[n][k], At[m][k], acc[ai][bj][m][n], 0, 0, 0); __builtin_amdgcn_s_setprio(0); } while (0)
; #define PG8_WAIT_V(n) asm volatile("s_waitcnt vmcnt(" #n ")" ::: "memory")
; #define PG8_WAIT_L(n) asm volatile("s_waitcnt lgkmcnt(" #n ")" ::: "memory")
; #define PG8_BAR __builtin_amdgcn_s_barrier()
; #define PG8_SCHED __builtin_amdgcn_sched_barrier(0)
; template <class Epi, class Sched, bool ALIGN_EPI = false, bool SP2 = false>
; __device__ __forceinline__ void gemm_phase(PG8_LAS unsigned char* lds, const Gemm g, const Sched& S, const Epi& E) {
;     ...
;         for (int t = 0; t < nt; t += 2) {
;     ...
;             PG8_LDA(At, 1, 1); PG8_STAGE(PG8_SB(1, 0), b3, voffB); PG8_STAGE(PG8_SB(1, 1), b3 + hstepB, voffB); PG8_STAGE(PG8_SA(1, 0), a3, voffA);
;             PG8_WAIT_V(8); PG8_WAIT_L(0); PG8_BAR; PG8_MMA(1, 0, At, B0); PG8_MMA(1, 1, At, B1); PG8_BAR; PG8_SCHED;
	s_add_i32 s8, s19, s89
	v_lshl_add_u64 v[6:7], v[152:153], 0, s[38:39]
	s_mov_b32 m0, s8
	ds_read_b128 v[190:193], v161 offset:49152
	ds_read_b128 v[194:197], v161 offset:50176
	ds_read_b128 v[198:201], v161 offset:51200
	ds_read_b128 v[202:205], v161 offset:52224
	ds_read_b128 v[206:209], v161 offset:53248
	ds_read_b128 v[210:213], v161 offset:54272
	ds_read_b128 v[214:217], v161 offset:55296
	ds_read_b128 v[220:223], v161 offset:56320
	global_load_lds_dwordx4 v[6:7], off
	v_lshl_add_u64 v[6:7], v[152:153], 0, s[40:41]
	s_add_i32 m0, s8, 0x2000
	s_add_i32 s8, s80, s89
	global_load_lds_dwordx4 v[6:7], off
	v_lshl_add_u64 v[6:7], v[152:153], 0, s[52:53]
	s_mov_b32 m0, s8
	s_nop 0
	global_load_lds_dwordx4 v[6:7], off
	v_lshl_add_u64 v[6:7], v[152:153], 0, s[54:55]
	s_add_i32 m0, s8, 0x2000
	s_nop 0
	global_load_lds_dwordx4 v[6:7], off
	v_lshl_add_u64 v[6:7], v[186:187], 0, s[38:39]
	s_mov_b32 m0, s94
	s_nop 0
	global_load_lds_dwordx4 v[6:7], off
	v_lshl_add_u64 v[6:7], v[186:187], 0, s[40:41]
	s_mov_b32 m0, s95
	s_nop 0
	global_load_lds_dwordx4 v[6:7], off
	s_waitcnt vmcnt(8)
	s_waitcnt lgkmcnt(0)
	s_barrier
	s_waitcnt lgkmcnt(0)
	v_mfma_f32_16x16x32_bf16 v[64:67], v[140:143], v[190:193], v[64:67]
	v_mfma_f32_16x16x32_bf16 v[60:63], v[148:151], v[190:193], v[60:63]
	v_mfma_f32_16x16x32_bf16 v[48:51], v[140:143], v[198:201], v[48:51]
	v_mfma_f32_16x16x32_bf16 v[44:47], v[148:151], v[198:201], v[44:47]
	v_mfma_f32_16x16x32_bf16 v[32:35], v[140:143], v[206:209], v[32:35]
	v_mfma_f32_16x16x32_bf16 v[28:31], v[148:151], v[206:209], v[28:31]
	v_mfma_f32_16x16x32_bf16 v[16:19], v[140:143], v[214:217], v[16:19]
	v_mfma_f32_16x16x32_bf16 v[12:15], v[148:151], v[214:217], v[12:15]
	v_mfma_f32_16x16x32_bf16 v[64:67], v[144:147], v[194:197], v[64:67]
	v_mfma_f32_16x16x32_bf16 v[60:63], v[166:169], v[194:197], v[60:63]
	v_mfma_f32_16x16x32_bf16 v[48:51], v[144:147], v[202:205], v[48:51]
	v_mfma_f32_16x16x32_bf16 v[44:47], v[166:169], v[202:205], v[44:47]
	v_mfma_f32_16x16x32_bf16 v[32:35], v[144:147], v[210:213], v[32:35]
	v_mfma_f32_16x16x32_bf16 v[28:31], v[166:169], v[210:213], v[28:31]
	v_mfma_f32_16x16x32_bf16 v[16:19], v[144:147], v[220:223], v[16:19]
	v_mfma_f32_16x16x32_bf16 v[12:15], v[166:169], v[220:223], v[12:15]
	v_mfma_f32_16x16x32_bf16 v[56:59], v[170:173], v[190:193], v[56:59]
	v_mfma_f32_16x16x32_bf16 v[52:55], v[178:181], v[190:193], v[52:55]
	v_mfma_f32_16x16x32_bf16 v[40:43], v[170:173], v[198:201], v[40:43]
	v_mfma_f32_16x16x32_bf16 v[36:39], v[178:181], v[198:201], v[36:39]
	v_mfma_f32_16x16x32_bf16 v[24:27], v[170:173], v[206:209], v[24:27]
	v_mfma_f32_16x16x32_bf16 v[20:23], v[178:181], v[206:209], v[20:23]
	v_mfma_f32_16x16x32_bf16 v[6:9], v[170:173], v[214:217], v[8:11]
	v_mfma_f32_16x16x32_bf16 v[2:5], v[178:181], v[214:217], v[2:5]
	v_mfma_f32_16x16x32_bf16 v[56:59], v[174:177], v[194:197], v[56:59]
	v_mfma_f32_16x16x32_bf16 v[52:55], v[182:185], v[194:197], v[52:55]
	v_mfma_f32_16x16x32_bf16 v[40:43], v[174:177], v[202:205], v[40:43]
	v_mfma_f32_16x16x32_bf16 v[36:39], v[182:185], v[202:205], v[36:39]
	v_mfma_f32_16x16x32_bf16 v[24:27], v[174:177], v[210:213], v[24:27]
	v_mfma_f32_16x16x32_bf16 v[20:23], v[182:185], v[210:213], v[20:23]
	v_mfma_f32_16x16x32_bf16 v[8:11], v[174:177], v[220:223], v[6:9]
	v_mfma_f32_16x16x32_bf16 v[4:7], v[182:185], v[220:223], v[2:5]
	s_barrier
	s_add_i32 s76, s76, 2
	s_add_u32 s4, s4, 0x10000
	s_addc_u32 s5, s5, 0
	s_add_u32 s74, s74, 0x10000
	s_addc_u32 s75, s75, 0
	s_cmp_gt_u32 s76, 13

; #define PG8_STAGE(bufoff, gbase, voff) do { _Pragma("unroll") for (int _i = 0; _i < 2; ++_i) \
;         __builtin_amdgcn_global_load_lds((const unsigned*)((const char*)(gbase) + (voff)[_i]), (PG8_LAS unsigned*)(lds + (bufoff) + ldsw + _i * 8192), 16, 0, 0); } while (0)
; #define PG8_WAIT_V(n) asm volatile("s_waitcnt vmcnt(" #n ")" ::: "memory")
; #define PG8_BAR __builtin_amdgcn_s_barrier()
; template <class Epi, class Sched, bool ALIGN_EPI = false, bool SP2 = false>
; __device__ __forceinline__ void gemm_phase(PG8_LAS unsigned char* lds, const Gemm g, const Sched& S, const Epi& E) {
;     const int tid = threadIdx.x, wid = __builtin_amdgcn_readfirstlane(tid >> 6), lane = tid & 63, wr = wid >> 2, wc = wid & 3, fr = lane & 15, fq = lane >> 4;
;     const int K = g.K, nt = K / BK;
;     unsigned voffA[2], voffB[2];
; #pragma unroll
;     for (int i = 0; i < 2; ++i) { int R, C; stage_rc(tid * 16 + i * 8192, R, C); const int Rb = Epi::PERM ? ((R & ~31) + perm32(R & 31)) : R;
;         voffA[i] = g.a_pre ? (unsigned)(tid * 16 + i * 8192) : (unsigned)(R * g.lda + C) * 2u; voffB[i] = g.b_pre ? (unsigned)(tid * 16 + i * 8192) : (unsigned)(Rb * g.ldb + C) * 2u; }
;     const size_t kstep = g.b_pre ? (size_t)(2 * HTB) : (size_t)(BK * 2);
;     const size_t hstepA = (size_t)HALF * g.lda * 2, hstepB = (size_t)HALF * g.ldb * 2;
;     const size_t tstepA = g.pstepA, tstepB = g.b_pre ? (size_t)(g.K / BK) * (2 * HTB) : 2 * hstepB;
;     const size_t kstepA = g.kstepA;
;     const unsigned ldsw = (unsigned)wid * 1024u;
;     const int aoff = lds_byte(wr * 64 + fr, fq * 8), boff = lds_byte(wc * 32 + fr, fq * 8);
;     ...
;     if constexpr (SP2) {
;         PG8_STAGE(PG8_SB(0, 0), cB, voffB); PG8_STAGE(PG8_SB(0, 1), cB + hstepB, voffB); PG8_STAGE(PG8_SA(0, 0), cA, voffA); PG8_STAGE(PG8_SA(0, 1), cA + hstepA, voffA);
;         PG8_STAGE(PG8_SB(1, 0), cB + kstep, voffB); PG8_STAGE(PG8_SA(1, 0), cA + kstepA, voffA); PG8_STAGE(PG8_SB(1, 1), cB + hstepB + kstep, voffB);
;         if (wr == 1) PG8_BAR;
;         PG8_WAIT_V(8); PG8_BAR;
;         PG8_WAIT_V(6); PG8_BAR;
.LBB0_634:
	s_sext_i32_i8 s89, s0
	s_and_b32 s0, s1, 3
	s_lshl_b32 s8, s3, 13
	v_lshlrev_b32_e32 v3, 2, v189
	s_cmpk_lt_u32 s2, 0x100
	v_or_b32_e32 v2, v182, v184
	v_and_b32_e32 v4, 32, v3
	s_cselect_b64 s[56:57], -1, 0
	s_and_b32 s73, s1, 2
	v_lshlrev_b32_e32 v7, 4, v183
	s_lshl_b32 s1, s2, 4
	v_bitop3_b32 v5, v2, s8, v4 bitop3:0xde
	s_and_b32 s1, s1, 0x400
	v_bitop3_b32 v4, v182, v4, v7 bitop3:0x36
	s_waitcnt vmcnt(8)
	s_barrier
	s_waitcnt vmcnt(0)
	v_lshlrev_b32_e32 v2, 4, v189
	v_or_b32_e32 v7, s1, v4
	s_or_b32 s1, s8, s1
	v_lshl_or_b32 v6, s0, 12, v185
	s_lshl_b32 s3, s3, 5
	s_lshl_b32 s0, s0, 3
	v_lshl_or_b32 v2, v183, 8, v2
	v_mov_b32_e32 v3, v191
	v_or_b32_e32 v164, s8, v7
	v_or_b32_e32 v4, s1, v4
	s_add_i32 s77, 0, 0x10000
	s_add_i32 s80, 0, 0x14000
	s_add_i32 s81, 0, 0x18000
	s_add_i32 s82, 0, 0x1c000
	v_ashrrev_i32_e32 v165, 31, v164
	v_or_b32_e32 v166, 0x800, v4
	v_mov_b32_e32 v167, v191
	v_or_b32_e32 v168, 0x1000, v4
	v_mov_b32_e32 v169, v191
	v_or_b32_e32 v170, 0x1800, v4
	v_mov_b32_e32 v171, v191
	s_ashr_i32 s74, s26, 31
	s_mov_b32 s75, s26
	s_or_b32 s76, s0, s3
	v_lshl_add_u64 v[172:173], s[10:11], 0, v[2:3]
	v_add3_u32 v174, v1, v192, v193
	v_mov_b32_e32 v175, v191
	v_add3_u32 v176, v0, v192, v193
	v_mov_b32_e32 v177, v191
	v_mov_b64_e32 v[178:179], 0x200
	v_mov_b64_e32 v[180:181], 0x1ff
	v_add_u32_e32 v197, s77, v6
	v_add_u32_e32 v198, s80, v6
	v_add_u32_e32 v199, 0, v5
	v_add_u32_e32 v200, s81, v6
	v_add_u32_e32 v201, s82, v6
	s_mov_b32 s58, 0x3b808081
	s_barrier
	s_branch .LBB0_637

; #define PG8_STAGE(bufoff, gbase, voff) do { _Pragma("unroll") for (int _i = 0; _i < 2; ++_i) \
;         __builtin_amdgcn_global_load_lds((const unsigned*)((const char*)(gbase) + (voff)[_i]), (PG8_LAS unsigned*)(lds + (bufoff) + ldsw + _i * 8192), 16, 0, 0); } while (0)
; #define PG8_LDA(dst, b, h) do { _Pragma("unroll") for (int m = 0; m < 4; ++m) _Pragma("unroll") for (int k = 0; k < 2; ++k) dst[m][k] = *(const PG8_LAS bf16x8*)(lds + PG8_SA(b, h) + aoff + m * 2048 + k * 1024); } while (0)
; #define PG8_LDB(dst, b, h) do { _Pragma("unroll") for (int n = 0; n < 2; ++n) _Pragma("unroll") for (int k = 0; k < 2; ++k) dst[n][k] = *(const PG8_LAS bf16x8*)(lds + PG8_SB(b, h) + boff + n * 2048 + k * 1024); } while (0)
; #define PG8_WAIT_V(n) asm volatile("s_waitcnt vmcnt(" #n ")" ::: "memory")
; #define PG8_WAIT_L(n) asm volatile("s_waitcnt lgkmcnt(" #n ")" ::: "memory")
; #define PG8_BAR __builtin_amdgcn_s_barrier()
; #define PG8_SCHED __builtin_amdgcn_sched_barrier(0)
; template <class Epi, class Sched, bool ALIGN_EPI = false, bool SP2 = false>
; __device__ __forceinline__ void gemm_phase(PG8_LAS unsigned char* lds, const Gemm g, const Sched& S, const Epi& E) {
;     ...
;         const bool has_next = S.next(ui + 1, nxt);
;         const char* nA = has_next ? (const char*)g.A + (size_t)nxt.pm * tstepA : cA; const char* nB = has_next ? (const char*)g.Bt + (size_t)nxt.pn * tstepB : cB;
;         for (int t = 0; t < nt; t += 2) {
;             const bool last = (t == nt - 2);
;             const char* a1 = cA + (size_t)(t + 1) * kstepA;
;             const char* a2 = last ? nA : cA + (size_t)(t + 2) * kstepA; const char* b2 = last ? nB : cB + (size_t)(t + 2) * kstep;
;             const char* a3 = a2 + kstepA; const char* b3 = b2 + kstep;
;             if (last && has_next) S.a_ready(nxt);
;             if constexpr (SP2) {
;             PG8_LDB(B0, 0, 0); PG8_LDB(B1, 0, 1); PG8_SCHED; PG8_LDA(At, 0, 0); PG8_STAGE(PG8_SA(1, 1), a1 + hstepA, voffA);
;             PG8_WAIT_V(8); PG8_WAIT_L(0); PG8_BAR; PG8_MMA(0, 0, At, B0); PG8_MMA(0, 1, At, B1); PG8_BAR; PG8_SCHED;
;             PG8_LDA(At, 0, 1); PG8_STAGE(PG8_SB(0, 0), b2, voffB); PG8_STAGE(PG8_SB(0, 1), b2 + hstepB, voffB); PG8_STAGE(PG8_SA(0, 0), a2, voffA);
;             PG8_WAIT_V(8); PG8_WAIT_L(0); PG8_BAR; PG8_MMA(1, 0, At, B0); PG8_MMA(1, 1, At, B1); PG8_BAR; PG8_SCHED;
.LBB0_645:
	s_ashr_i32 s61, s60, 31
	s_lshl_b64 s[8:9], s[60:61], 19
	s_add_u32 s64, s85, s8
	s_addc_u32 s65, s86, s9
	s_and_b64 s[0:1], s[0:1], exec
	s_cselect_b32 s61, s65, s67
	s_cselect_b32 s90, s64, s66
	s_add_u32 s91, s66, 0x10000
	s_addc_u32 s92, s67, 0
	s_add_u32 s0, s68, 0xf0080
	s_addc_u32 s1, s69, 0
	s_mov_b32 s68, -2
	ds_read_b128 v[128:131], v197
	ds_read_b128 v[132:135], v197 offset:1024
	ds_read_b128 v[136:139], v197 offset:2048
	ds_read_b128 v[140:143], v197 offset:3072
	ds_read_b128 v[144:147], v198
	ds_read_b128 v[148:151], v198 offset:1024
	ds_read_b128 v[152:155], v198 offset:2048
	ds_read_b128 v[156:159], v198 offset:3072
	s_add_u32 s8, s0, 0xfff10080
	s_addc_u32 s9, s1, -1
	s_cmp_eq_u32 s68, 12
	s_cselect_b32 s67, s63, s9
	s_cselect_b32 s66, s62, s8
	s_cselect_b32 s9, s61, s92
	s_cselect_b32 s8, s90, s91
	v_lshl_add_u64 v[236:237], s[0:1], 0, v[174:175]
	s_add_i32 m0, s17, 0xc000
	ds_read_b128 v[202:205], v199
	ds_read_b128 v[206:209], v199 offset:1024
	ds_read_b128 v[210:213], v199 offset:2048
	ds_read_b128 v[214:217], v199 offset:3072
	ds_read_b128 v[220:223], v199 offset:4096
	ds_read_b128 v[224:227], v199 offset:5120
	ds_read_b128 v[228:231], v199 offset:6144
	ds_read_b128 v[232:235], v199 offset:7168
	global_load_lds_dwordx4 v[236:237], off
	v_lshl_add_u64 v[236:237], s[0:1], 0, v[176:177]
	s_add_i32 m0, s17, 0xe000
	s_nop 0
	global_load_lds_dwordx4 v[236:237], off
	s_waitcnt vmcnt(56)
	s_waitcnt lgkmcnt(0)
	s_barrier
	s_waitcnt lgkmcnt(0)
	v_mfma_f32_16x16x32_bf16 v[124:127], v[128:131], v[202:205], 0
	v_mfma_f32_16x16x32_bf16 v[120:123], v[136:139], v[202:205], 0
	v_mfma_f32_16x16x32_bf16 v[108:111], v[128:131], v[210:213], 0
	v_mfma_f32_16x16x32_bf16 v[104:107], v[136:139], v[210:213], 0
	v_mfma_f32_16x16x32_bf16 v[96:99], v[128:131], v[220:223], 0
	v_mfma_f32_16x16x32_bf16 v[88:91], v[136:139], v[220:223], 0
	v_mfma_f32_16x16x32_bf16 v[80:83], v[128:131], v[228:231], 0
	v_mfma_f32_16x16x32_bf16 v[72:75], v[136:139], v[228:231], 0
	v_mfma_f32_16x16x32_bf16 v[124:127], v[132:135], v[206:209], v[124:127]
	v_mfma_f32_16x16x32_bf16 v[120:123], v[140:143], v[206:209], v[120:123]
	v_mfma_f32_16x16x32_bf16 v[108:111], v[132:135], v[214:217], v[108:111]
	v_mfma_f32_16x16x32_bf16 v[104:107], v[140:143], v[214:217], v[104:107]
	v_mfma_f32_16x16x32_bf16 v[96:99], v[132:135], v[224:227], v[96:99]
	v_mfma_f32_16x16x32_bf16 v[88:91], v[140:143], v[224:227], v[88:91]
	v_mfma_f32_16x16x32_bf16 v[80:83], v[132:135], v[232:235], v[80:83]
	v_mfma_f32_16x16x32_bf16 v[72:75], v[140:143], v[232:235], v[72:75]
	v_mfma_f32_16x16x32_bf16 v[116:119], v[144:147], v[202:205], 0
	v_mfma_f32_16x16x32_bf16 v[112:115], v[152:155], v[202:205], 0
	v_mfma_f32_16x16x32_bf16 v[100:103], v[144:147], v[210:213], 0
	v_mfma_f32_16x16x32_bf16 v[92:95], v[152:155], v[210:213], 0
	v_mfma_f32_16x16x32_bf16 v[84:87], v[144:147], v[220:223], 0
	v_mfma_f32_16x16x32_bf16 v[76:79], v[152:155], v[220:223], 0
	v_mfma_f32_16x16x32_bf16 v[68:71], v[144:147], v[228:231], 0
	v_mfma_f32_16x16x32_bf16 v[64:67], v[152:155], v[228:231], 0
	v_mfma_f32_16x16x32_bf16 v[116:119], v[148:151], v[206:209], v[116:119]
	v_mfma_f32_16x16x32_bf16 v[112:115], v[156:159], v[206:209], v[112:115]
	v_mfma_f32_16x16x32_bf16 v[100:103], v[148:151], v[214:217], v[100:103]
	v_mfma_f32_16x16x32_bf16 v[92:95], v[156:159], v[214:217], v[92:95]
	v_mfma_f32_16x16x32_bf16 v[84:87], v[148:151], v[224:227], v[84:87]
	v_mfma_f32_16x16x32_bf16 v[76:79], v[156:159], v[224:227], v[76:79]
	v_mfma_f32_16x16x32_bf16 v[68:71], v[148:151], v[232:235], v[68:71]
	v_mfma_f32_16x16x32_bf16 v[64:67], v[156:159], v[232:235], v[64:67]
	s_barrier
	v_lshl_add_u64 v[236:237], s[8:9], 0, v[190:191]
	s_add_i32 s8, s77, s15
	s_mov_b32 m0, s8
	ds_read_b128 v[202:205], v199 offset:16384
	ds_read_b128 v[206:209], v199 offset:17408
	ds_read_b128 v[210:213], v199 offset:18432
	ds_read_b128 v[214:217], v199 offset:19456
	ds_read_b128 v[220:223], v199 offset:20480
	ds_read_b128 v[224:227], v199 offset:21504
	ds_read_b128 v[228:231], v199 offset:22528
	ds_read_b128 v[232:235], v199 offset:23552
	global_load_lds_dwordx4 v[236:237], off
	v_lshl_add_u64 v[238:239], v[236:237], 0, s[36:37]
	s_add_i32 m0, s8, 0x2000
	s_add_i32 s8, s80, s15
	global_load_lds_dwordx4 v[238:239], off
	v_lshl_add_u64 v[238:239], v[236:237], 0, s[38:39]
	s_mov_b32 m0, s8
	v_lshl_add_u64 v[240:241], s[66:67], 0, v[162:163]
	global_load_lds_dwordx4 v[238:239], off
	v_lshl_add_u64 v[238:239], v[236:237], 0, s[40:41]
	s_add_i32 m0, s8, 0x2000
	s_nop 0
	global_load_lds_dwordx4 v[238:239], off
	v_lshl_add_u64 v[238:239], s[66:67], 0, v[160:161]
	s_mov_b32 m0, s17
	s_nop 0
	global_load_lds_dwordx4 v[238:239], off
	s_mov_b32 m0, s18
	s_nop 0
	global_load_lds_dwordx4 v[240:241], off
	s_waitcnt vmcnt(56)
	s_waitcnt lgkmcnt(0)
	s_barrier
; #define PG8_STAGE(bufoff, gbase, voff) do { _Pragma("unroll") for (int _i = 0; _i < 2; ++_i) \
;         __builtin_amdgcn_global_load_lds((const unsigned*)((const char*)(gbase) + (voff)[_i]), (PG8_LAS unsigned*)(lds + (bufoff) + ldsw + _i * 8192), 16, 0, 0); } while (0)
; #define PG8_LDA(dst, b, h) do { _Pragma("unroll") for (int m = 0; m < 4; ++m) _Pragma("unroll") for (int k = 0; k < 2; ++k) dst[m][k] = *(const PG8_LAS bf16x8*)(lds + PG8_SA(b, h) + aoff + m * 2048 + k * 1024); } while (0)
; #define PG8_LDB(dst, b, h) do { _Pragma("unroll") for (int n = 0; n < 2; ++n) _Pragma("unroll") for (int k = 0; k < 2; ++k) dst[n][k] = *(const PG8_LAS bf16x8*)(lds + PG8_SB(b, h) + boff + n * 2048 + k * 1024); } while (0)
; #define PG8_MMA(ai, bj, At, Bt) do { __builtin_amdgcn_s_setprio(1); _Pragma("unroll") for (int m = 0; m < 4; ++m) _Pragma("unroll") for (int n = 0; n < 2; ++n) _Pragma("unroll") for (int k = 0; k < 2; ++k) \
;         acc[ai][bj][m][n] = __builtin_amdgcn_mfma_f32_16x16x32_bf16(Bt[n][k], At[m][k], acc[ai][bj][m][n], 0, 0, 0); __builtin_amdgcn_s_setprio(0); } while (0)
; #define PG8_WAIT_V(n) asm volatile("s_waitcnt vmcnt(" #n ")" ::: "memory")
; #define PG8_WAIT_L(n) asm volatile("s_waitcnt lgkmcnt(" #n ")" ::: "memory")
; #define PG8_BAR __builtin_amdgcn_s_barrier()
; #define PG8_SCHED __builtin_amdgcn_sched_barrier(0)
; template <class Epi, class Sched, bool ALIGN_EPI = false, bool SP2 = false>
; __device__ __forceinline__ void gemm_phase(PG8_LAS unsigned char* lds, const Gemm g, const Sched& S, const Epi& E) {
;     ...
;             PG8_WAIT_V(8); PG8_WAIT_L(0); PG8_BAR; PG8_MMA(1, 0, At, B0); PG8_MMA(1, 1, At, B1); PG8_BAR; PG8_SCHED;
;             PG8_LDB(B0, 1, 0); PG8_LDB(B1, 1, 1); PG8_SCHED; PG8_LDA(At, 1, 0); PG8_STAGE(PG8_SA(0, 1), a2 + hstepA, voffA);
;             PG8_WAIT_V(8); PG8_WAIT_L(0); PG8_BAR; PG8_MMA(0, 0, At, B0); PG8_MMA(0, 1, At, B1); PG8_BAR; PG8_SCHED;
	s_waitcnt lgkmcnt(0)
	v_mfma_f32_16x16x32_bf16 v[60:63], v[128:131], v[202:205], 0
	v_mfma_f32_16x16x32_bf16 v[56:59], v[136:139], v[202:205], 0
	v_mfma_f32_16x16x32_bf16 v[48:51], v[128:131], v[210:213], 0
	v_mfma_f32_16x16x32_bf16 v[40:43], v[136:139], v[210:213], 0
	v_mfma_f32_16x16x32_bf16 v[32:35], v[128:131], v[220:223], 0
	v_mfma_f32_16x16x32_bf16 v[24:27], v[136:139], v[220:223], 0
	v_mfma_f32_16x16x32_bf16 v[16:19], v[128:131], v[228:231], 0
	v_mfma_f32_16x16x32_bf16 v[8:11], v[136:139], v[228:231], 0
	v_mfma_f32_16x16x32_bf16 v[60:63], v[132:135], v[206:209], v[60:63]
	v_mfma_f32_16x16x32_bf16 v[56:59], v[140:143], v[206:209], v[56:59]
	v_mfma_f32_16x16x32_bf16 v[48:51], v[132:135], v[214:217], v[48:51]
	v_mfma_f32_16x16x32_bf16 v[40:43], v[140:143], v[214:217], v[40:43]
	v_mfma_f32_16x16x32_bf16 v[32:35], v[132:135], v[224:227], v[32:35]
	v_mfma_f32_16x16x32_bf16 v[24:27], v[140:143], v[224:227], v[24:27]
	v_mfma_f32_16x16x32_bf16 v[16:19], v[132:135], v[232:235], v[16:19]
	v_mfma_f32_16x16x32_bf16 v[8:11], v[140:143], v[232:235], v[8:11]
	v_mfma_f32_16x16x32_bf16 v[52:55], v[144:147], v[202:205], 0
	v_mfma_f32_16x16x32_bf16 v[44:47], v[152:155], v[202:205], 0
	v_mfma_f32_16x16x32_bf16 v[36:39], v[144:147], v[210:213], 0
	v_mfma_f32_16x16x32_bf16 v[28:31], v[152:155], v[210:213], 0
	v_mfma_f32_16x16x32_bf16 v[20:23], v[144:147], v[220:223], 0
	v_mfma_f32_16x16x32_bf16 v[12:15], v[152:155], v[220:223], 0
	v_mfma_f32_16x16x32_bf16 v[4:7], v[144:147], v[228:231], 0
	v_mfma_f32_16x16x32_bf16 v[0:3], v[152:155], v[228:231], 0
	v_mfma_f32_16x16x32_bf16 v[52:55], v[148:151], v[206:209], v[52:55]
	v_mfma_f32_16x16x32_bf16 v[44:47], v[156:159], v[206:209], v[44:47]
	v_mfma_f32_16x16x32_bf16 v[36:39], v[148:151], v[214:217], v[36:39]
	v_mfma_f32_16x16x32_bf16 v[28:31], v[156:159], v[214:217], v[28:31]
	v_mfma_f32_16x16x32_bf16 v[20:23], v[148:151], v[224:227], v[20:23]
	v_mfma_f32_16x16x32_bf16 v[12:15], v[156:159], v[224:227], v[12:15]
	v_mfma_f32_16x16x32_bf16 v[4:7], v[148:151], v[232:235], v[4:7]
	v_mfma_f32_16x16x32_bf16 v[0:3], v[156:159], v[232:235], v[0:3]
	s_barrier
	ds_read_b128 v[128:131], v200
	ds_read_b128 v[132:135], v200 offset:1024
	ds_read_b128 v[136:139], v200 offset:2048
	ds_read_b128 v[140:143], v200 offset:3072
	ds_read_b128 v[144:147], v201
	ds_read_b128 v[148:151], v201 offset:1024
	ds_read_b128 v[152:155], v201 offset:2048
	ds_read_b128 v[156:159], v201 offset:3072
	s_add_u32 s8, s66, 0xf0000
	s_addc_u32 s9, s67, 0
	s_mov_b32 m0, s19
	v_lshl_add_u64 v[242:243], s[8:9], 0, v[160:161]
	ds_read_b128 v[202:205], v199 offset:32768
	ds_read_b128 v[206:209], v199 offset:33792
	ds_read_b128 v[210:213], v199 offset:34816
	ds_read_b128 v[214:217], v199 offset:35840
	ds_read_b128 v[220:223], v199 offset:36864
	ds_read_b128 v[224:227], v199 offset:37888
	ds_read_b128 v[228:231], v199 offset:38912
	ds_read_b128 v[232:235], v199 offset:39936
	global_load_lds_dwordx4 v[242:243], off
	v_lshl_add_u64 v[242:243], s[8:9], 0, v[162:163]
	s_mov_b32 m0, s59
	s_nop 0
	global_load_lds_dwordx4 v[242:243], off
	s_waitcnt vmcnt(8)
	s_waitcnt lgkmcnt(0)
	s_barrier
	s_waitcnt lgkmcnt(0)
	v_mfma_f32_16x16x32_bf16 v[124:127], v[128:131], v[202:205], v[124:127]
	v_mfma_f32_16x16x32_bf16 v[120:123], v[136:139], v[202:205], v[120:123]
	v_mfma_f32_16x16x32_bf16 v[108:111], v[128:131], v[210:213], v[108:111]
	v_mfma_f32_16x16x32_bf16 v[104:107], v[136:139], v[210:213], v[104:107]
	v_mfma_f32_16x16x32_bf16 v[96:99], v[128:131], v[220:223], v[96:99]
	v_mfma_f32_16x16x32_bf16 v[88:91], v[136:139], v[220:223], v[88:91]
	v_mfma_f32_16x16x32_bf16 v[80:83], v[128:131], v[228:231], v[80:83]
	v_mfma_f32_16x16x32_bf16 v[72:75], v[136:139], v[228:231], v[72:75]
	v_mfma_f32_16x16x32_bf16 v[124:127], v[132:135], v[206:209], v[124:127]
	v_mfma_f32_16x16x32_bf16 v[120:123], v[140:143], v[206:209], v[120:123]
	v_mfma_f32_16x16x32_bf16 v[108:111], v[132:135], v[214:217], v[108:111]
	v_mfma_f32_16x16x32_bf16 v[104:107], v[140:143], v[214:217], v[104:107]
	v_mfma_f32_16x16x32_bf16 v[96:99], v[132:135], v[224:227], v[96:99]
	v_mfma_f32_16x16x32_bf16 v[88:91], v[140:143], v[224:227], v[88:91]
	v_mfma_f32_16x16x32_bf16 v[80:83], v[132:135], v[232:235], v[80:83]
	v_mfma_f32_16x16x32_bf16 v[72:75], v[140:143], v[232:235], v[72:75]
	v_mfma_f32_16x16x32_bf16 v[116:119], v[144:147], v[202:205], v[116:119]
	v_mfma_f32_16x16x32_bf16 v[112:115], v[152:155], v[202:205], v[112:115]
	v_mfma_f32_16x16x32_bf16 v[100:103], v[144:147], v[210:213], v[100:103]
	v_mfma_f32_16x16x32_bf16 v[92:95], v[152:155], v[210:213], v[92:95]
	v_mfma_f32_16x16x32_bf16 v[84:87], v[144:147], v[220:223], v[84:87]
	v_mfma_f32_16x16x32_bf16 v[76:79], v[152:155], v[220:223], v[76:79]
	v_mfma_f32_16x16x32_bf16 v[68:71], v[144:147], v[228:231], v[68:71]
	v_mfma_f32_16x16x32_bf16 v[64:67], v[152:155], v[228:231], v[64:67]
	v_mfma_f32_16x16x32_bf16 v[116:119], v[148:151], v[206:209], v[116:119]
	v_mfma_f32_16x16x32_bf16 v[112:115], v[156:159], v[206:209], v[112:115]
	v_mfma_f32_16x16x32_bf16 v[100:103], v[148:151], v[214:217], v[100:103]
	v_mfma_f32_16x16x32_bf16 v[92:95], v[156:159], v[214:217], v[92:95]
	v_mfma_f32_16x16x32_bf16 v[84:87], v[148:151], v[224:227], v[84:87]
	v_mfma_f32_16x16x32_bf16 v[76:79], v[156:159], v[224:227], v[76:79]
	v_mfma_f32_16x16x32_bf16 v[68:71], v[148:151], v[232:235], v[68:71]
	v_mfma_f32_16x16x32_bf16 v[64:67], v[156:159], v[232:235], v[64:67]
	s_barrier
; #define PG8_STAGE(bufoff, gbase, voff) do { _Pragma("unroll") for (int _i = 0; _i < 2; ++_i) \
;         __builtin_amdgcn_global_load_lds((const unsigned*)((const char*)(gbase) + (voff)[_i]), (PG8_LAS unsigned*)(lds + (bufoff) + ldsw + _i * 8192), 16, 0, 0); } while (0)
; #define PG8_LDA(dst, b, h) do { _Pragma("unroll") for (int m = 0; m < 4; ++m) _Pragma("unroll") for (int k = 0; k < 2; ++k) dst[m][k] = *(const PG8_LAS bf16x8*)(lds + PG8_SA(b, h) + aoff + m * 2048 + k * 1024); } while (0)
; #define PG8_MMA(ai, bj, At, Bt) do { __builtin_amdgcn_s_setprio(1); _Pragma("unroll") for (int m = 0; m < 4; ++m) _Pragma("unroll") for (int n = 0; n < 2; ++n) _Pragma("unroll") for (int k = 0; k < 2; ++k) \
;         acc[ai][bj][m][n] = __builtin_amdgcn_mfma_f32_16x16x32_bf16(Bt[n][k], At[m][k], acc[ai][bj][m][n], 0, 0, 0); __builtin_amdgcn_s_setprio(0); } while (0)
; #define PG8_WAIT_V(n) asm volatile("s_waitcnt vmcnt(" #n ")" ::: "memory")
; #define PG8_WAIT_L(n) asm volatile("s_waitcnt lgkmcnt(" #n ")" ::: "memory")
; #define PG8_BAR __builtin_amdgcn_s_barrier()
; #define PG8_SCHED __builtin_amdgcn_sched_barrier(0)
; template <class Epi, class Sched, bool ALIGN_EPI = false, bool SP2 = false>
; __device__ __forceinline__ void gemm_phase(PG8_LAS unsigned char* lds, const Gemm g, const Sched& S, const Epi& E) {
;     ...
;         for (int t = 0; t < nt; t += 2) {
;     ...
;             PG8_LDA(At, 1, 1); PG8_STAGE(PG8_SB(1, 0), b3, voffB); PG8_STAGE(PG8_SB(1, 1), b3 + hstepB, voffB); PG8_STAGE(PG8_SA(1, 0), a3, voffA);
;             PG8_WAIT_V(8); PG8_WAIT_L(0); PG8_BAR; PG8_MMA(1, 0, At, B0); PG8_MMA(1, 1, At, B1); PG8_BAR; PG8_SCHED;
	s_add_i32 s8, s81, s15
	v_lshl_add_u64 v[242:243], v[236:237], 0, s[42:43]
	s_mov_b32 m0, s8
	ds_read_b128 v[202:205], v199 offset:49152
	ds_read_b128 v[206:209], v199 offset:50176
	ds_read_b128 v[210:213], v199 offset:51200
	ds_read_b128 v[214:217], v199 offset:52224
	ds_read_b128 v[220:223], v199 offset:53248
	ds_read_b128 v[224:227], v199 offset:54272
	ds_read_b128 v[228:231], v199 offset:55296
	ds_read_b128 v[232:235], v199 offset:56320
	global_load_lds_dwordx4 v[242:243], off
	v_lshl_add_u64 v[242:243], v[236:237], 0, s[44:45]
	s_add_i32 m0, s8, 0x2000
	s_add_i32 s8, s82, s15
	global_load_lds_dwordx4 v[242:243], off
	v_lshl_add_u64 v[242:243], v[236:237], 0, s[48:49]
	s_mov_b32 m0, s8
	v_lshl_add_u64 v[236:237], v[236:237], 0, s[52:53]
	global_load_lds_dwordx4 v[242:243], off
	s_add_i32 m0, s8, 0x2000
	s_nop 0
	global_load_lds_dwordx4 v[236:237], off
	v_lshl_add_u64 v[236:237], v[238:239], 0, s[46:47]
	s_mov_b32 m0, s70
	s_nop 0
	global_load_lds_dwordx4 v[236:237], off
	v_lshl_add_u64 v[236:237], v[240:241], 0, s[46:47]
	s_mov_b32 m0, s71
	s_nop 0
	global_load_lds_dwordx4 v[236:237], off
	s_waitcnt vmcnt(8)
	s_waitcnt lgkmcnt(0)
	s_barrier
	s_waitcnt lgkmcnt(0)
	v_mfma_f32_16x16x32_bf16 v[60:63], v[128:131], v[202:205], v[60:63]
	v_mfma_f32_16x16x32_bf16 v[56:59], v[136:139], v[202:205], v[56:59]
	v_mfma_f32_16x16x32_bf16 v[48:51], v[128:131], v[210:213], v[48:51]
	v_mfma_f32_16x16x32_bf16 v[40:43], v[136:139], v[210:213], v[40:43]
	v_mfma_f32_16x16x32_bf16 v[32:35], v[128:131], v[220:223], v[32:35]
	v_mfma_f32_16x16x32_bf16 v[24:27], v[136:139], v[220:223], v[24:27]
	v_mfma_f32_16x16x32_bf16 v[16:19], v[128:131], v[228:231], v[16:19]
	v_mfma_f32_16x16x32_bf16 v[8:11], v[136:139], v[228:231], v[8:11]
	v_mfma_f32_16x16x32_bf16 v[60:63], v[132:135], v[206:209], v[60:63]
	v_mfma_f32_16x16x32_bf16 v[56:59], v[140:143], v[206:209], v[56:59]
	v_mfma_f32_16x16x32_bf16 v[48:51], v[132:135], v[214:217], v[48:51]
	v_mfma_f32_16x16x32_bf16 v[40:43], v[140:143], v[214:217], v[40:43]
	v_mfma_f32_16x16x32_bf16 v[32:35], v[132:135], v[224:227], v[32:35]
	v_mfma_f32_16x16x32_bf16 v[24:27], v[140:143], v[224:227], v[24:27]
	v_mfma_f32_16x16x32_bf16 v[16:19], v[132:135], v[232:235], v[16:19]
	v_mfma_f32_16x16x32_bf16 v[8:11], v[140:143], v[232:235], v[8:11]
	v_mfma_f32_16x16x32_bf16 v[52:55], v[144:147], v[202:205], v[52:55]
	v_mfma_f32_16x16x32_bf16 v[44:47], v[152:155], v[202:205], v[44:47]
	v_mfma_f32_16x16x32_bf16 v[36:39], v[144:147], v[210:213], v[36:39]
	v_mfma_f32_16x16x32_bf16 v[28:31], v[152:155], v[210:213], v[28:31]
	v_mfma_f32_16x16x32_bf16 v[20:23], v[144:147], v[220:223], v[20:23]
	v_mfma_f32_16x16x32_bf16 v[12:15], v[152:155], v[220:223], v[12:15]
	v_mfma_f32_16x16x32_bf16 v[4:7], v[144:147], v[228:231], v[4:7]
	v_mfma_f32_16x16x32_bf16 v[0:3], v[152:155], v[228:231], v[0:3]
	v_mfma_f32_16x16x32_bf16 v[52:55], v[148:151], v[206:209], v[52:55]
	v_mfma_f32_16x16x32_bf16 v[44:47], v[156:159], v[206:209], v[44:47]
	v_mfma_f32_16x16x32_bf16 v[36:39], v[148:151], v[214:217], v[36:39]
	v_mfma_f32_16x16x32_bf16 v[28:31], v[156:159], v[214:217], v[28:31]
	v_mfma_f32_16x16x32_bf16 v[20:23], v[148:151], v[224:227], v[20:23]
	v_mfma_f32_16x16x32_bf16 v[12:15], v[156:159], v[224:227], v[12:15]
	v_mfma_f32_16x16x32_bf16 v[4:7], v[148:151], v[232:235], v[4:7]
	v_mfma_f32_16x16x32_bf16 v[0:3], v[156:159], v[232:235], v[0:3]
	s_barrier
	s_add_i32 s68, s68, 2
	s_add_u32 s91, s91, 0x10000
	s_addc_u32 s92, s92, 0
	s_add_u32 s0, s0, 0x100
	s_addc_u32 s1, s1, 0
	s_cmp_gt_u32 s68, 13

; #define PG8_STAGE(bufoff, gbase, voff) do { _Pragma("unroll") for (int _i = 0; _i < 2; ++_i) \
;         __builtin_amdgcn_global_load_lds((const unsigned*)((const char*)(gbase) + (voff)[_i]), (PG8_LAS unsigned*)(lds + (bufoff) + ldsw + _i * 8192), 16, 0, 0); } while (0)
; #define PG8_WAIT_V(n) asm volatile("s_waitcnt vmcnt(" #n ")" ::: "memory")
; #define PG8_BAR __builtin_amdgcn_s_barrier()
; template <class Epi, class Sched, bool ALIGN_EPI = false, bool SP2 = false>
; __device__ __forceinline__ void gemm_phase(PG8_LAS unsigned char* lds, const Gemm g, const Sched& S, const Epi& E) {
;     const int tid = threadIdx.x, wid = __builtin_amdgcn_readfirstlane(tid >> 6), lane = tid & 63, wr = wid >> 2, wc = wid & 3, fr = lane & 15, fq = lane >> 4;
;     const int K = g.K, nt = K / BK;
;     unsigned voffA[2], voffB[2];
; #pragma unroll
;     for (int i = 0; i < 2; ++i) { int R, C; stage_rc(tid * 16 + i * 8192, R, C); const int Rb = Epi::PERM ? ((R & ~31) + perm32(R & 31)) : R;
;         voffA[i] = g.a_pre ? (unsigned)(tid * 16 + i * 8192) : (unsigned)(R * g.lda + C) * 2u; voffB[i] = g.b_pre ? (unsigned)(tid * 16 + i * 8192) : (unsigned)(Rb * g.ldb + C) * 2u; }
;     const size_t kstep = g.b_pre ? (size_t)(2 * HTB) : (size_t)(BK * 2);
;     const size_t hstepA = (size_t)HALF * g.lda * 2, hstepB = (size_t)HALF * g.ldb * 2;
;     const size_t tstepA = g.pstepA, tstepB = g.b_pre ? (size_t)(g.K / BK) * (2 * HTB) : 2 * hstepB;
;     const size_t kstepA = g.kstepA;
;     const unsigned ldsw = (unsigned)wid * 1024u;
;     const int aoff = lds_byte(wr * 64 + fr, fq * 8), boff = lds_byte(wc * 32 + fr, fq * 8);
;     ...
;     if constexpr (SP2) {
;         PG8_STAGE(PG8_SB(0, 0), cB, voffB); PG8_STAGE(PG8_SB(0, 1), cB + hstepB, voffB); PG8_STAGE(PG8_SA(0, 0), cA, voffA); PG8_STAGE(PG8_SA(0, 1), cA + hstepA, voffA);
;         PG8_STAGE(PG8_SB(1, 0), cB + kstep, voffB); PG8_STAGE(PG8_SA(1, 0), cA + kstepA, voffA); PG8_STAGE(PG8_SB(1, 1), cB + hstepB + kstep, voffB);
;         if (wr == 1) PG8_BAR;
;         PG8_WAIT_V(8); PG8_BAR;
;         PG8_WAIT_V(6); PG8_BAR;
.LBB0_660:
	v_lshlrev_b32_e32 v1, 2, v189
	s_lshl_b32 s8, s55, 13
	v_or_b32_e32 v0, v182, v184
	v_and_b32_e32 v2, 32, v1
	v_bitop3_b32 v3, v0, s8, v2 bitop3:0xde
	v_lshlrev_b32_e32 v0, 4, v189
	s_sext_i32_i8 s63, s2
	s_and_b32 s2, s54, 3
	v_lshl_or_b32 v0, v183, 8, v0
	v_mov_b32_e32 v1, v191
	v_lshl_or_b32 v199, s2, 12, v185
	v_lshl_add_u64 v[184:185], s[10:11], 0, v[0:1]
	v_lshlrev_b32_e32 v0, 7, v188
	s_cmpk_lt_u32 s3, 0x100
	v_and_b32_e32 v0, 0x1c000, v0
	v_lshlrev_b32_e32 v1, 10, v186
	s_cselect_b64 s[52:53], -1, 0
	v_lshlrev_b32_e32 v4, 4, v183
	s_lshl_b32 s3, s3, 4
	v_or3_b32 v0, v192, v0, v1
	s_and_b32 s3, s3, 0x400
	v_bitop3_b32 v2, v182, v2, v4 bitop3:0x36
	v_add_u32_e32 v186, v0, v193
	v_lshlrev_b32_e32 v0, 3, v194
	s_waitcnt vmcnt(8)
	s_barrier
	s_waitcnt vmcnt(0)
	s_lshl_b32 s9, s55, 5
	s_lshl_b32 s2, s2, 3
	v_or_b32_e32 v4, s3, v2
	s_or_b32 s3, s8, s3
	v_and_b32_e32 v0, 0x3c000, v0
	v_or_b32_e32 v176, s8, v4
	v_or_b32_e32 v2, s3, v2
	s_or_b32 s77, s9, s2
	v_or3_b32 v0, v192, v0, v1
	s_add_i32 s11, 0, 0x10000
	s_add_i32 s80, 0, 0x14000
	s_add_i32 s81, 0, 0x18000
	v_lshl_or_b32 v198, s55, 6, v189
	s_and_b32 s74, s54, 2
	v_ashrrev_i32_e32 v177, 31, v176
	v_or_b32_e32 v178, 0x800, v2
	v_mov_b32_e32 v179, v191
	v_or_b32_e32 v180, 0x1000, v2
	v_mov_b32_e32 v181, v191
	v_or_b32_e32 v182, 0x1800, v2
	v_mov_b32_e32 v183, v191
	s_ashr_i32 s75, s26, 31
	s_mov_b32 s76, s26
	s_addk_i32 s77, 0x100
	v_mov_b32_e32 v187, v191
	v_add_u32_e32 v192, v0, v193
	v_mov_b32_e32 v193, v191
	v_mov_b64_e32 v[194:195], 0x200
	v_mov_b64_e32 v[196:197], 0x1ff
	v_add_u32_e32 v200, s11, v199
	v_add_u32_e32 v201, s80, v199
	v_add_u32_e32 v202, 0, v3
	v_add_u32_e32 v203, s81, v199
	s_mov_b32 s10, 0x3b808081
	s_barrier
	s_branch .LBB0_663

; #define PG8_STAGE(bufoff, gbase, voff) do { _Pragma("unroll") for (int _i = 0; _i < 2; ++_i) \
;         __builtin_amdgcn_global_load_lds((const unsigned*)((const char*)(gbase) + (voff)[_i]), (PG8_LAS unsigned*)(lds + (bufoff) + ldsw + _i * 8192), 16, 0, 0); } while (0)
; #define PG8_LDA(dst, b, h) do { _Pragma("unroll") for (int m = 0; m < 4; ++m) _Pragma("unroll") for (int k = 0; k < 2; ++k) dst[m][k] = *(const PG8_LAS bf16x8*)(lds + PG8_SA(b, h) + aoff + m * 2048 + k * 1024); } while (0)
; #define PG8_LDB(dst, b, h) do { _Pragma("unroll") for (int n = 0; n < 2; ++n) _Pragma("unroll") for (int k = 0; k < 2; ++k) dst[n][k] = *(const PG8_LAS bf16x8*)(lds + PG8_SB(b, h) + boff + n * 2048 + k * 1024); } while (0)
; #define PG8_WAIT_V(n) asm volatile("s_waitcnt vmcnt(" #n ")" ::: "memory")
; #define PG8_WAIT_L(n) asm volatile("s_waitcnt lgkmcnt(" #n ")" ::: "memory")
; #define PG8_BAR __builtin_amdgcn_s_barrier()
; #define PG8_SCHED __builtin_amdgcn_sched_barrier(0)
; template <class Epi, class Sched, bool ALIGN_EPI = false, bool SP2 = false>
; __device__ __forceinline__ void gemm_phase(PG8_LAS unsigned char* lds, const Gemm g, const Sched& S, const Epi& E) {
;     ...
;         const bool has_next = S.next(ui + 1, nxt);
;         const char* nA = has_next ? (const char*)g.A + (size_t)nxt.pm * tstepA : cA; const char* nB = has_next ? (const char*)g.Bt + (size_t)nxt.pn * tstepB : cB;
;         for (int t = 0; t < nt; t += 2) {
;             const bool last = (t == nt - 2);
;             const char* a1 = cA + (size_t)(t + 1) * kstepA;
;             const char* a2 = last ? nA : cA + (size_t)(t + 2) * kstepA; const char* b2 = last ? nB : cB + (size_t)(t + 2) * kstep;
;             const char* a3 = a2 + kstepA; const char* b3 = b2 + kstep;
;             if (last && has_next) S.a_ready(nxt);
;             if constexpr (SP2) {
;             PG8_LDB(B0, 0, 0); PG8_LDB(B1, 0, 1); PG8_SCHED; PG8_LDA(At, 0, 0); PG8_STAGE(PG8_SA(1, 1), a1 + hstepA, voffA);
;             PG8_WAIT_V(8); PG8_WAIT_L(0); PG8_BAR; PG8_MMA(0, 0, At, B0); PG8_MMA(0, 1, At, B1); PG8_BAR; PG8_SCHED;
;             PG8_LDA(At, 0, 1); PG8_STAGE(PG8_SB(0, 0), b2, voffB); PG8_STAGE(PG8_SB(0, 1), b2 + hstepB, voffB); PG8_STAGE(PG8_SA(0, 0), a2, voffA);
;             PG8_WAIT_V(8); PG8_WAIT_L(0); PG8_BAR; PG8_MMA(1, 0, At, B0); PG8_MMA(1, 1, At, B1); PG8_BAR; PG8_SCHED;
.LBB0_669:
	s_ashr_i32 s57, s56, 31
	s_lshl_b64 s[8:9], s[56:57], 18
	s_add_u32 s58, s30, s8
	s_addc_u32 s59, s31, s9
	s_and_b64 s[8:9], s[2:3], exec
	s_cselect_b32 s57, s59, s67
	s_cselect_b32 s68, s58, s66
	s_ashr_i32 s55, s54, 31
	s_lshl_b64 s[8:9], s[54:55], 18
	v_readlane_b32 s60, v246, 7
	v_readlane_b32 s61, v246, 8
	s_add_u32 s60, s60, s8
	s_addc_u32 s61, s61, s9
	s_and_b64 s[8:9], s[2:3], exec
	s_cselect_b32 s55, s61, s65
	s_cselect_b32 s69, s60, s64
	s_add_u32 s82, s64, 0x10000
	s_addc_u32 s85, s65, 0
	s_add_u32 s64, s66, 0x20080
	s_addc_u32 s65, s67, 0
	s_mov_b32 s86, -2
	ds_read_b128 v[108:111], v200
	ds_read_b128 v[132:135], v200 offset:1024
	ds_read_b128 v[136:139], v200 offset:2048
	ds_read_b128 v[140:143], v200 offset:3072
	ds_read_b128 v[144:147], v201
	ds_read_b128 v[148:151], v201 offset:1024
	ds_read_b128 v[152:155], v201 offset:2048
	ds_read_b128 v[156:159], v201 offset:3072
	s_add_u32 s8, s64, 0xfffe0080
	s_addc_u32 s9, s65, -1
	s_cmp_eq_u32 s86, 4
	s_cselect_b32 s67, s57, s9
	s_cselect_b32 s66, s68, s8
	s_cselect_b32 s9, s55, s85
	s_cselect_b32 s8, s69, s82
	v_lshl_add_u64 v[216:217], s[64:65], 0, v[186:187]
	s_add_i32 m0, s17, 0xc000
	ds_read_b128 v[160:163], v202
	ds_read_b128 v[164:167], v202 offset:1024
	ds_read_b128 v[168:171], v202 offset:2048
	ds_read_b128 v[204:207], v202 offset:3072
	ds_read_b128 v[208:211], v202 offset:4096
	ds_read_b128 v[212:215], v202 offset:5120
	ds_read_b128 v[220:223], v202 offset:6144
	ds_read_b128 v[224:227], v202 offset:7168
	global_load_lds_dwordx4 v[216:217], off
	v_lshl_add_u64 v[216:217], s[64:65], 0, v[192:193]
	s_add_i32 m0, s17, 0xe000
	s_nop 0
	global_load_lds_dwordx4 v[216:217], off
	s_waitcnt vmcnt(56)
	s_waitcnt lgkmcnt(0)
	s_barrier
	s_waitcnt lgkmcnt(0)
	v_mfma_f32_16x16x32_bf16 v[128:131], v[108:111], v[160:163], 0
	v_mfma_f32_16x16x32_bf16 v[124:127], v[136:139], v[160:163], 0
	v_mfma_f32_16x16x32_bf16 v[112:115], v[108:111], v[168:171], 0
	v_mfma_f32_16x16x32_bf16 v[104:107], v[136:139], v[168:171], 0
	v_mfma_f32_16x16x32_bf16 v[92:95], v[108:111], v[208:211], 0
	v_mfma_f32_16x16x32_bf16 v[88:91], v[136:139], v[208:211], 0
	v_mfma_f32_16x16x32_bf16 v[76:79], v[108:111], v[220:223], 0
	v_mfma_f32_16x16x32_bf16 v[72:75], v[136:139], v[220:223], 0
	v_mfma_f32_16x16x32_bf16 v[128:131], v[132:135], v[164:167], v[128:131]
	v_mfma_f32_16x16x32_bf16 v[124:127], v[140:143], v[164:167], v[124:127]
	v_mfma_f32_16x16x32_bf16 v[112:115], v[132:135], v[204:207], v[112:115]
	v_mfma_f32_16x16x32_bf16 v[104:107], v[140:143], v[204:207], v[104:107]
	v_mfma_f32_16x16x32_bf16 v[92:95], v[132:135], v[212:215], v[92:95]
	v_mfma_f32_16x16x32_bf16 v[88:91], v[140:143], v[212:215], v[88:91]
	v_mfma_f32_16x16x32_bf16 v[76:79], v[132:135], v[224:227], v[76:79]
	v_mfma_f32_16x16x32_bf16 v[72:75], v[140:143], v[224:227], v[72:75]
	v_mfma_f32_16x16x32_bf16 v[120:123], v[144:147], v[160:163], 0
	v_mfma_f32_16x16x32_bf16 v[116:119], v[152:155], v[160:163], 0
	v_mfma_f32_16x16x32_bf16 v[100:103], v[144:147], v[168:171], 0
	v_mfma_f32_16x16x32_bf16 v[96:99], v[152:155], v[168:171], 0
	v_mfma_f32_16x16x32_bf16 v[84:87], v[144:147], v[208:211], 0
	v_mfma_f32_16x16x32_bf16 v[80:83], v[152:155], v[208:211], 0
	v_mfma_f32_16x16x32_bf16 v[68:71], v[144:147], v[220:223], 0
	v_mfma_f32_16x16x32_bf16 v[64:67], v[152:155], v[220:223], 0
	v_mfma_f32_16x16x32_bf16 v[120:123], v[148:151], v[164:167], v[120:123]
	v_mfma_f32_16x16x32_bf16 v[116:119], v[156:159], v[164:167], v[116:119]
	v_mfma_f32_16x16x32_bf16 v[100:103], v[148:151], v[204:207], v[100:103]
	v_mfma_f32_16x16x32_bf16 v[96:99], v[156:159], v[204:207], v[96:99]
	v_mfma_f32_16x16x32_bf16 v[84:87], v[148:151], v[212:215], v[84:87]
	v_mfma_f32_16x16x32_bf16 v[80:83], v[156:159], v[212:215], v[80:83]
	v_mfma_f32_16x16x32_bf16 v[68:71], v[148:151], v[224:227], v[68:71]
	v_mfma_f32_16x16x32_bf16 v[64:67], v[156:159], v[224:227], v[64:67]
	s_barrier
	v_lshl_add_u64 v[216:217], s[8:9], 0, v[190:191]
	s_add_i32 s8, s11, s15
	s_mov_b32 m0, s8
	ds_read_b128 v[160:163], v202 offset:16384
	ds_read_b128 v[164:167], v202 offset:17408
	ds_read_b128 v[168:171], v202 offset:18432
	ds_read_b128 v[204:207], v202 offset:19456
	ds_read_b128 v[208:211], v202 offset:20480
	ds_read_b128 v[212:215], v202 offset:21504
	ds_read_b128 v[220:223], v202 offset:22528
	ds_read_b128 v[224:227], v202 offset:23552
	global_load_lds_dwordx4 v[216:217], off
	v_lshl_add_u64 v[228:229], v[216:217], 0, s[0:1]
	s_add_i32 m0, s8, 0x2000
	s_add_i32 s8, s80, s15
	global_load_lds_dwordx4 v[228:229], off
	v_lshl_add_u64 v[228:229], v[216:217], 0, s[34:35]
	s_mov_b32 m0, s8
	v_lshl_add_u64 v[230:231], s[66:67], 0, v[174:175]
	global_load_lds_dwordx4 v[228:229], off
	v_lshl_add_u64 v[228:229], v[216:217], 0, s[36:37]
	s_add_i32 m0, s8, 0x2000
	s_nop 0
	global_load_lds_dwordx4 v[228:229], off
	v_lshl_add_u64 v[228:229], s[66:67], 0, v[172:173]
	s_mov_b32 m0, s17
	s_nop 0
	global_load_lds_dwordx4 v[228:229], off
	s_mov_b32 m0, s18
	s_nop 0
	global_load_lds_dwordx4 v[230:231], off
	s_waitcnt vmcnt(56)
	s_waitcnt lgkmcnt(0)
	s_barrier
; #define PG8_STAGE(bufoff, gbase, voff) do { _Pragma("unroll") for (int _i = 0; _i < 2; ++_i) \
;         __builtin_amdgcn_global_load_lds((const unsigned*)((const char*)(gbase) + (voff)[_i]), (PG8_LAS unsigned*)(lds + (bufoff) + ldsw + _i * 8192), 16, 0, 0); } while (0)
; #define PG8_LDA(dst, b, h) do { _Pragma("unroll") for (int m = 0; m < 4; ++m) _Pragma("unroll") for (int k = 0; k < 2; ++k) dst[m][k] = *(const PG8_LAS bf16x8*)(lds + PG8_SA(b, h) + aoff + m * 2048 + k * 1024); } while (0)
; #define PG8_LDB(dst, b, h) do { _Pragma("unroll") for (int n = 0; n < 2; ++n) _Pragma("unroll") for (int k = 0; k < 2; ++k) dst[n][k] = *(const PG8_LAS bf16x8*)(lds + PG8_SB(b, h) + boff + n * 2048 + k * 1024); } while (0)
; #define PG8_MMA(ai, bj, At, Bt) do { __builtin_amdgcn_s_setprio(1); _Pragma("unroll") for (int m = 0; m < 4; ++m) _Pragma("unroll") for (int n = 0; n < 2; ++n) _Pragma("unroll") for (int k = 0; k < 2; ++k) \
;         acc[ai][bj][m][n] = __builtin_amdgcn_mfma_f32_16x16x32_bf16(Bt[n][k], At[m][k], acc[ai][bj][m][n], 0, 0, 0); __builtin_amdgcn_s_setprio(0); } while (0)
; #define PG8_WAIT_V(n) asm volatile("s_waitcnt vmcnt(" #n ")" ::: "memory")
; #define PG8_WAIT_L(n) asm volatile("s_waitcnt lgkmcnt(" #n ")" ::: "memory")
; #define PG8_BAR __builtin_amdgcn_s_barrier()
; #define PG8_SCHED __builtin_amdgcn_sched_barrier(0)
; template <class Epi, class Sched, bool ALIGN_EPI = false, bool SP2 = false>
; __device__ __forceinline__ void gemm_phase(PG8_LAS unsigned char* lds, const Gemm g, const Sched& S, const Epi& E) {
;     ...
;             PG8_WAIT_V(8); PG8_WAIT_L(0); PG8_BAR; PG8_MMA(1, 0, At, B0); PG8_MMA(1, 1, At, B1); PG8_BAR; PG8_SCHED;
;             PG8_LDB(B0, 1, 0); PG8_LDB(B1, 1, 1); PG8_SCHED; PG8_LDA(At, 1, 0); PG8_STAGE(PG8_SA(0, 1), a2 + hstepA, voffA);
;             PG8_WAIT_V(8); PG8_WAIT_L(0); PG8_BAR; PG8_MMA(0, 0, At, B0); PG8_MMA(0, 1, At, B1); PG8_BAR; PG8_SCHED;
	s_waitcnt lgkmcnt(0)
	v_mfma_f32_16x16x32_bf16 v[60:63], v[108:111], v[160:163], 0
	v_mfma_f32_16x16x32_bf16 v[56:59], v[136:139], v[160:163], 0
	v_mfma_f32_16x16x32_bf16 v[44:47], v[108:111], v[168:171], 0
	v_mfma_f32_16x16x32_bf16 v[40:43], v[136:139], v[168:171], 0
	v_mfma_f32_16x16x32_bf16 v[28:31], v[108:111], v[208:211], 0
	v_mfma_f32_16x16x32_bf16 v[24:27], v[136:139], v[208:211], 0
	v_mfma_f32_16x16x32_bf16 v[12:15], v[108:111], v[220:223], 0
	v_mfma_f32_16x16x32_bf16 v[8:11], v[136:139], v[220:223], 0
	v_mfma_f32_16x16x32_bf16 v[60:63], v[132:135], v[164:167], v[60:63]
	v_mfma_f32_16x16x32_bf16 v[56:59], v[140:143], v[164:167], v[56:59]
	v_mfma_f32_16x16x32_bf16 v[44:47], v[132:135], v[204:207], v[44:47]
	v_mfma_f32_16x16x32_bf16 v[40:43], v[140:143], v[204:207], v[40:43]
	v_mfma_f32_16x16x32_bf16 v[28:31], v[132:135], v[212:215], v[28:31]
	v_mfma_f32_16x16x32_bf16 v[24:27], v[140:143], v[212:215], v[24:27]
	v_mfma_f32_16x16x32_bf16 v[12:15], v[132:135], v[224:227], v[12:15]
	v_mfma_f32_16x16x32_bf16 v[8:11], v[140:143], v[224:227], v[8:11]
	v_mfma_f32_16x16x32_bf16 v[52:55], v[144:147], v[160:163], 0
	v_mfma_f32_16x16x32_bf16 v[48:51], v[152:155], v[160:163], 0
	v_mfma_f32_16x16x32_bf16 v[36:39], v[144:147], v[168:171], 0
	v_mfma_f32_16x16x32_bf16 v[32:35], v[152:155], v[168:171], 0
	v_mfma_f32_16x16x32_bf16 v[20:23], v[144:147], v[208:211], 0
	v_mfma_f32_16x16x32_bf16 v[16:19], v[152:155], v[208:211], 0
	v_mfma_f32_16x16x32_bf16 v[4:7], v[144:147], v[220:223], 0
	v_mfma_f32_16x16x32_bf16 v[0:3], v[152:155], v[220:223], 0
	v_mfma_f32_16x16x32_bf16 v[52:55], v[148:151], v[164:167], v[52:55]
	v_mfma_f32_16x16x32_bf16 v[48:51], v[156:159], v[164:167], v[48:51]
	v_mfma_f32_16x16x32_bf16 v[36:39], v[148:151], v[204:207], v[36:39]
	v_mfma_f32_16x16x32_bf16 v[32:35], v[156:159], v[204:207], v[32:35]
	v_mfma_f32_16x16x32_bf16 v[20:23], v[148:151], v[212:215], v[20:23]
	v_mfma_f32_16x16x32_bf16 v[16:19], v[156:159], v[212:215], v[16:19]
	v_mfma_f32_16x16x32_bf16 v[4:7], v[148:151], v[224:227], v[4:7]
	v_mfma_f32_16x16x32_bf16 v[0:3], v[156:159], v[224:227], v[0:3]
	s_barrier
	s_add_i32 s78, 0, 0x1c000
	v_add_u32_e32 v156, s78, v199
	ds_read_b128 v[108:111], v203
	ds_read_b128 v[132:135], v203 offset:1024
	ds_read_b128 v[136:139], v203 offset:2048
	ds_read_b128 v[140:143], v203 offset:3072
	ds_read_b128 v[144:147], v156
	ds_read_b128 v[148:151], v156 offset:1024
	ds_read_b128 v[152:155], v156 offset:2048
	ds_read_b128 v[156:159], v156 offset:3072
	s_add_u32 s8, s66, 0x20000
	s_addc_u32 s9, s67, 0
	s_mov_b32 m0, s19
	v_lshl_add_u64 v[232:233], s[8:9], 0, v[172:173]
	ds_read_b128 v[160:163], v202 offset:32768
	ds_read_b128 v[164:167], v202 offset:33792
	ds_read_b128 v[168:171], v202 offset:34816
	ds_read_b128 v[204:207], v202 offset:35840
	ds_read_b128 v[208:211], v202 offset:36864
	ds_read_b128 v[212:215], v202 offset:37888
	ds_read_b128 v[220:223], v202 offset:38912
	ds_read_b128 v[224:227], v202 offset:39936
	global_load_lds_dwordx4 v[232:233], off
	v_lshl_add_u64 v[232:233], s[8:9], 0, v[174:175]
	s_mov_b32 m0, s70
	s_nop 0
	global_load_lds_dwordx4 v[232:233], off
	s_waitcnt vmcnt(8)
	s_waitcnt lgkmcnt(0)
	s_barrier
	s_waitcnt lgkmcnt(0)
	v_mfma_f32_16x16x32_bf16 v[128:131], v[108:111], v[160:163], v[128:131]
	v_mfma_f32_16x16x32_bf16 v[124:127], v[136:139], v[160:163], v[124:127]
	v_mfma_f32_16x16x32_bf16 v[112:115], v[108:111], v[168:171], v[112:115]
	v_mfma_f32_16x16x32_bf16 v[104:107], v[136:139], v[168:171], v[104:107]
	v_mfma_f32_16x16x32_bf16 v[92:95], v[108:111], v[208:211], v[92:95]
	v_mfma_f32_16x16x32_bf16 v[88:91], v[136:139], v[208:211], v[88:91]
	v_mfma_f32_16x16x32_bf16 v[76:79], v[108:111], v[220:223], v[76:79]
	v_mfma_f32_16x16x32_bf16 v[72:75], v[136:139], v[220:223], v[72:75]
	v_mfma_f32_16x16x32_bf16 v[128:131], v[132:135], v[164:167], v[128:131]
	v_mfma_f32_16x16x32_bf16 v[124:127], v[140:143], v[164:167], v[124:127]
	v_mfma_f32_16x16x32_bf16 v[112:115], v[132:135], v[204:207], v[112:115]
	v_mfma_f32_16x16x32_bf16 v[104:107], v[140:143], v[204:207], v[104:107]
	v_mfma_f32_16x16x32_bf16 v[92:95], v[132:135], v[212:215], v[92:95]
	v_mfma_f32_16x16x32_bf16 v[88:91], v[140:143], v[212:215], v[88:91]
	v_mfma_f32_16x16x32_bf16 v[76:79], v[132:135], v[224:227], v[76:79]
	v_mfma_f32_16x16x32_bf16 v[72:75], v[140:143], v[224:227], v[72:75]
	v_mfma_f32_16x16x32_bf16 v[120:123], v[144:147], v[160:163], v[120:123]
	v_mfma_f32_16x16x32_bf16 v[116:119], v[152:155], v[160:163], v[116:119]
	v_mfma_f32_16x16x32_bf16 v[100:103], v[144:147], v[168:171], v[100:103]
	v_mfma_f32_16x16x32_bf16 v[96:99], v[152:155], v[168:171], v[96:99]
	v_mfma_f32_16x16x32_bf16 v[84:87], v[144:147], v[208:211], v[84:87]
	v_mfma_f32_16x16x32_bf16 v[80:83], v[152:155], v[208:211], v[80:83]
	v_mfma_f32_16x16x32_bf16 v[68:71], v[144:147], v[220:223], v[68:71]
	v_mfma_f32_16x16x32_bf16 v[64:67], v[152:155], v[220:223], v[64:67]
	v_mfma_f32_16x16x32_bf16 v[120:123], v[148:151], v[164:167], v[120:123]
	v_mfma_f32_16x16x32_bf16 v[116:119], v[156:159], v[164:167], v[116:119]
	v_mfma_f32_16x16x32_bf16 v[100:103], v[148:151], v[204:207], v[100:103]
	v_mfma_f32_16x16x32_bf16 v[96:99], v[156:159], v[204:207], v[96:99]
	v_mfma_f32_16x16x32_bf16 v[84:87], v[148:151], v[212:215], v[84:87]
	v_mfma_f32_16x16x32_bf16 v[80:83], v[156:159], v[212:215], v[80:83]
	v_mfma_f32_16x16x32_bf16 v[68:71], v[148:151], v[224:227], v[68:71]
	v_mfma_f32_16x16x32_bf16 v[64:67], v[156:159], v[224:227], v[64:67]
	s_barrier
; #define PG8_STAGE(bufoff, gbase, voff) do { _Pragma("unroll") for (int _i = 0; _i < 2; ++_i) \
;         __builtin_amdgcn_global_load_lds((const unsigned*)((const char*)(gbase) + (voff)[_i]), (PG8_LAS unsigned*)(lds + (bufoff) + ldsw + _i * 8192), 16, 0, 0); } while (0)
; #define PG8_LDA(dst, b, h) do { _Pragma("unroll") for (int m = 0; m < 4; ++m) _Pragma("unroll") for (int k = 0; k < 2; ++k) dst[m][k] = *(const PG8_LAS bf16x8*)(lds + PG8_SA(b, h) + aoff + m * 2048 + k * 1024); } while (0)
; #define PG8_MMA(ai, bj, At, Bt) do { __builtin_amdgcn_s_setprio(1); _Pragma("unroll") for (int m = 0; m < 4; ++m) _Pragma("unroll") for (int n = 0; n < 2; ++n) _Pragma("unroll") for (int k = 0; k < 2; ++k) \
;         acc[ai][bj][m][n] = __builtin_amdgcn_mfma_f32_16x16x32_bf16(Bt[n][k], At[m][k], acc[ai][bj][m][n], 0, 0, 0); __builtin_amdgcn_s_setprio(0); } while (0)
; #define PG8_WAIT_V(n) asm volatile("s_waitcnt vmcnt(" #n ")" ::: "memory")
; #define PG8_WAIT_L(n) asm volatile("s_waitcnt lgkmcnt(" #n ")" ::: "memory")
; #define PG8_BAR __builtin_amdgcn_s_barrier()
; #define PG8_SCHED __builtin_amdgcn_sched_barrier(0)
; template <class Epi, class Sched, bool ALIGN_EPI = false, bool SP2 = false>
; __device__ __forceinline__ void gemm_phase(PG8_LAS unsigned char* lds, const Gemm g, const Sched& S, const Epi& E) {
;     ...
;         for (int t = 0; t < nt; t += 2) {
;     ...
;             PG8_LDA(At, 1, 1); PG8_STAGE(PG8_SB(1, 0), b3, voffB); PG8_STAGE(PG8_SB(1, 1), b3 + hstepB, voffB); PG8_STAGE(PG8_SA(1, 0), a3, voffA);
;             PG8_WAIT_V(8); PG8_WAIT_L(0); PG8_BAR; PG8_MMA(1, 0, At, B0); PG8_MMA(1, 1, At, B1); PG8_BAR; PG8_SCHED;
	s_add_i32 s8, s81, s15
	v_lshl_add_u64 v[232:233], v[216:217], 0, s[38:39]
	s_mov_b32 m0, s8
	ds_read_b128 v[160:163], v202 offset:49152
	ds_read_b128 v[164:167], v202 offset:50176
	ds_read_b128 v[168:171], v202 offset:51200
	ds_read_b128 v[204:207], v202 offset:52224
	ds_read_b128 v[208:211], v202 offset:53248
	ds_read_b128 v[212:215], v202 offset:54272
	ds_read_b128 v[220:223], v202 offset:55296
	ds_read_b128 v[224:227], v202 offset:56320
	global_load_lds_dwordx4 v[232:233], off
	v_lshl_add_u64 v[232:233], v[216:217], 0, s[40:41]
	s_add_i32 m0, s8, 0x2000
	s_add_i32 s8, s78, s15
	global_load_lds_dwordx4 v[232:233], off
	v_lshl_add_u64 v[232:233], v[216:217], 0, s[44:45]
	s_mov_b32 m0, s8
	v_lshl_add_u64 v[216:217], v[216:217], 0, s[46:47]
	global_load_lds_dwordx4 v[232:233], off
	s_add_i32 m0, s8, 0x2000
	s_nop 0
	global_load_lds_dwordx4 v[216:217], off
	v_lshl_add_u64 v[216:217], v[228:229], 0, s[42:43]
	s_mov_b32 m0, s71
	s_nop 0
	global_load_lds_dwordx4 v[216:217], off
	v_lshl_add_u64 v[216:217], v[230:231], 0, s[42:43]
	s_mov_b32 m0, s72
	s_nop 0
	global_load_lds_dwordx4 v[216:217], off
	s_waitcnt vmcnt(8)
	s_waitcnt lgkmcnt(0)
	s_barrier
	s_waitcnt lgkmcnt(0)
	v_mfma_f32_16x16x32_bf16 v[60:63], v[108:111], v[160:163], v[60:63]
	v_mfma_f32_16x16x32_bf16 v[56:59], v[136:139], v[160:163], v[56:59]
	v_mfma_f32_16x16x32_bf16 v[44:47], v[108:111], v[168:171], v[44:47]
	v_mfma_f32_16x16x32_bf16 v[40:43], v[136:139], v[168:171], v[40:43]
	v_mfma_f32_16x16x32_bf16 v[28:31], v[108:111], v[208:211], v[28:31]
	v_mfma_f32_16x16x32_bf16 v[24:27], v[136:139], v[208:211], v[24:27]
	v_mfma_f32_16x16x32_bf16 v[12:15], v[108:111], v[220:223], v[12:15]
	v_mfma_f32_16x16x32_bf16 v[8:11], v[136:139], v[220:223], v[8:11]
	v_mfma_f32_16x16x32_bf16 v[60:63], v[132:135], v[164:167], v[60:63]
	v_mfma_f32_16x16x32_bf16 v[56:59], v[140:143], v[164:167], v[56:59]
	v_mfma_f32_16x16x32_bf16 v[44:47], v[132:135], v[204:207], v[44:47]
	v_mfma_f32_16x16x32_bf16 v[40:43], v[140:143], v[204:207], v[40:43]
	v_mfma_f32_16x16x32_bf16 v[28:31], v[132:135], v[212:215], v[28:31]
	v_mfma_f32_16x16x32_bf16 v[24:27], v[140:143], v[212:215], v[24:27]
	v_mfma_f32_16x16x32_bf16 v[12:15], v[132:135], v[224:227], v[12:15]
	v_mfma_f32_16x16x32_bf16 v[8:11], v[140:143], v[224:227], v[8:11]
	v_mfma_f32_16x16x32_bf16 v[52:55], v[144:147], v[160:163], v[52:55]
	v_mfma_f32_16x16x32_bf16 v[48:51], v[152:155], v[160:163], v[48:51]
	v_mfma_f32_16x16x32_bf16 v[36:39], v[144:147], v[168:171], v[36:39]
	v_mfma_f32_16x16x32_bf16 v[32:35], v[152:155], v[168:171], v[32:35]
	v_mfma_f32_16x16x32_bf16 v[20:23], v[144:147], v[208:211], v[20:23]
	v_mfma_f32_16x16x32_bf16 v[16:19], v[152:155], v[208:211], v[16:19]
	v_mfma_f32_16x16x32_bf16 v[4:7], v[144:147], v[220:223], v[4:7]
	v_mfma_f32_16x16x32_bf16 v[0:3], v[152:155], v[220:223], v[0:3]
	v_mfma_f32_16x16x32_bf16 v[52:55], v[148:151], v[164:167], v[52:55]
	v_mfma_f32_16x16x32_bf16 v[48:51], v[156:159], v[164:167], v[48:51]
	v_mfma_f32_16x16x32_bf16 v[36:39], v[148:151], v[204:207], v[36:39]
	v_mfma_f32_16x16x32_bf16 v[32:35], v[156:159], v[204:207], v[32:35]
	v_mfma_f32_16x16x32_bf16 v[20:23], v[148:151], v[212:215], v[20:23]
	v_mfma_f32_16x16x32_bf16 v[16:19], v[156:159], v[212:215], v[16:19]
	v_mfma_f32_16x16x32_bf16 v[4:7], v[148:151], v[224:227], v[4:7]
	v_mfma_f32_16x16x32_bf16 v[0:3], v[156:159], v[224:227], v[0:3]
	s_barrier
	s_add_i32 s86, s86, 2
	s_add_u32 s82, s82, 0x10000
	s_addc_u32 s85, s85, 0
	s_add_u32 s64, s64, 0x100
	s_addc_u32 s65, s65, 0
	s_cmp_gt_u32 s86, 5

; #define PG8_STAGE(bufoff, gbase, voff) do { _Pragma("unroll") for (int _i = 0; _i < 2; ++_i) \
;         __builtin_amdgcn_global_load_lds((const unsigned*)((const char*)(gbase) + (voff)[_i]), (PG8_LAS unsigned*)(lds + (bufoff) + ldsw + _i * 8192), 16, 0, 0); } while (0)
; #define PG8_WAIT_V(n) asm volatile("s_waitcnt vmcnt(" #n ")" ::: "memory")
; #define PG8_BAR __builtin_amdgcn_s_barrier()
; template <class Epi, class Sched, bool ALIGN_EPI = false, bool SP2 = false>
; __device__ __forceinline__ void gemm_phase(PG8_LAS unsigned char* lds, const Gemm g, const Sched& S, const Epi& E) {
;     const int tid = threadIdx.x, wid = __builtin_amdgcn_readfirstlane(tid >> 6), lane = tid & 63, wr = wid >> 2, wc = wid & 3, fr = lane & 15, fq = lane >> 4;
;     const int K = g.K, nt = K / BK;
;     unsigned voffA[2], voffB[2];
; #pragma unroll
;     for (int i = 0; i < 2; ++i) { int R, C; stage_rc(tid * 16 + i * 8192, R, C); const int Rb = Epi::PERM ? ((R & ~31) + perm32(R & 31)) : R;
;         voffA[i] = g.a_pre ? (unsigned)(tid * 16 + i * 8192) : (unsigned)(R * g.lda + C) * 2u; voffB[i] = g.b_pre ? (unsigned)(tid * 16 + i * 8192) : (unsigned)(Rb * g.ldb + C) * 2u; }
;     const size_t kstep = g.b_pre ? (size_t)(2 * HTB) : (size_t)(BK * 2);
;     const size_t hstepA = (size_t)HALF * g.lda * 2, hstepB = (size_t)HALF * g.ldb * 2;
;     const size_t tstepA = g.pstepA, tstepB = g.b_pre ? (size_t)(g.K / BK) * (2 * HTB) : 2 * hstepB;
;     const size_t kstepA = g.kstepA;
;     const unsigned ldsw = (unsigned)wid * 1024u;
;     const int aoff = lds_byte(wr * 64 + fr, fq * 8), boff = lds_byte(wc * 32 + fr, fq * 8);
;     ...
;     if constexpr (SP2) {
;         PG8_STAGE(PG8_SB(0, 0), cB, voffB); PG8_STAGE(PG8_SB(0, 1), cB + hstepB, voffB); PG8_STAGE(PG8_SA(0, 0), cA, voffA); PG8_STAGE(PG8_SA(0, 1), cA + hstepA, voffA);
;         PG8_STAGE(PG8_SB(1, 0), cB + kstep, voffB); PG8_STAGE(PG8_SA(1, 0), cA + kstepA, voffA); PG8_STAGE(PG8_SB(1, 1), cB + hstepB + kstep, voffB);
;         if (wr == 1) PG8_BAR;
;         PG8_WAIT_V(8); PG8_BAR;
;         PG8_WAIT_V(6); PG8_BAR;
.LBB0_741:
	s_lshl_b32 s4, s2, 12
	v_lshl_or_b32 v210, s3, 6, v189
	s_lshl_b32 s3, s3, 13
	s_and_b32 s4, s4, 0x3000
	v_bfe_u32 v0, v188, 4, 2
	v_lshlrev_b32_e32 v4, 2, v188
	v_lshlrev_b32_e32 v5, 6, v188
	s_cmpk_lt_u32 s52, 0x100
	v_lshlrev_b32_e32 v1, 6, v189
	v_and_b32_e32 v2, 48, v188
	v_and_b32_e32 v4, 32, v4
	v_and_b32_e32 v5, 0x3c0, v5
	s_cselect_b64 s[48:49], -1, 0
	s_and_b32 s77, s2, 2
	v_lshlrev_b32_e32 v6, 4, v0
	s_lshl_b32 s2, s52, 4
	v_or_b32_e32 v3, v1, v2
	v_bitop3_b32 v2, v5, v4, v2 bitop3:0x36
	s_and_b32 s2, s2, 0x400
	v_bitop3_b32 v1, v1, v4, v6 bitop3:0x36
	v_or_b32_e32 v2, s4, v2
	s_or_b32 s4, s3, s2
	v_bitop3_b32 v5, v5, v4, v6 bitop3:0x36
	v_or_b32_e32 v1, s2, v1
	s_waitcnt vmcnt(8)
	s_barrier
	s_waitcnt vmcnt(0)
	v_or_b32_e32 v5, s4, v5
	v_or_b32_e32 v186, s3, v1
	v_bitop3_b32 v3, v3, s3, v4 bitop3:0xde
	v_or_b32_e32 v184, 0x1800, v5
	v_mov_b32_e32 v185, v191
	v_ashrrev_i32_e32 v187, 31, v186
	v_or_b32_e32 v192, 0x800, v5
	v_mov_b32_e32 v193, v191
	v_or_b32_e32 v194, 0x1000, v5
	v_mov_b32_e32 v195, v191
	v_cmp_eq_u32_e64 s[2:3], 0, v0
	s_add_i32 s85, 0, 0x10000
	s_add_i32 s86, 0, 0x14000
	s_movk_i32 s52, 0xc000
	s_movk_i32 s54, 0xe000
	s_add_i32 s87, 0, 0x18000
	s_add_i32 s88, 0, 0x1c000
	v_mbcnt_lo_u32_b32 v0, -1, 0
	s_ashr_i32 s80, s26, 31
	s_mov_b32 s81, s26
	s_ashr_i32 s82, s16, 31
	v_lshl_add_u64 v[196:197], s[12:13], 0, v[184:185]
	v_lshl_add_u64 v[198:199], s[12:13], 0, v[186:187]
	v_lshl_add_u64 v[200:201], s[12:13], 0, v[192:193]
	v_lshl_add_u64 v[202:203], s[12:13], 0, v[194:195]
	v_mov_b64_e32 v[204:205], 0x200
	v_mov_b64_e32 v[206:207], 0x1ff
	v_add_u32_e32 v211, s85, v2
	v_add_u32_e32 v212, s86, v2
	v_add_u32_e32 v213, 0, v3
	s_mov_b32 s53, -1
	s_mov_b32 s55, -1
	v_add_u32_e32 v214, s87, v2
	v_add_u32_e32 v215, s88, v2
	v_mbcnt_hi_u32_b32 v216, -1, v0
	s_barrier
	s_branch .LBB0_744

; #define PG8_STAGE(bufoff, gbase, voff) do { _Pragma("unroll") for (int _i = 0; _i < 2; ++_i) \
;         __builtin_amdgcn_global_load_lds((const unsigned*)((const char*)(gbase) + (voff)[_i]), (PG8_LAS unsigned*)(lds + (bufoff) + ldsw + _i * 8192), 16, 0, 0); } while (0)
; #define PG8_LDA(dst, b, h) do { _Pragma("unroll") for (int m = 0; m < 4; ++m) _Pragma("unroll") for (int k = 0; k < 2; ++k) dst[m][k] = *(const PG8_LAS bf16x8*)(lds + PG8_SA(b, h) + aoff + m * 2048 + k * 1024); } while (0)
; #define PG8_LDB(dst, b, h) do { _Pragma("unroll") for (int n = 0; n < 2; ++n) _Pragma("unroll") for (int k = 0; k < 2; ++k) dst[n][k] = *(const PG8_LAS bf16x8*)(lds + PG8_SB(b, h) + boff + n * 2048 + k * 1024); } while (0)
; #define PG8_WAIT_V(n) asm volatile("s_waitcnt vmcnt(" #n ")" ::: "memory")
; #define PG8_WAIT_L(n) asm volatile("s_waitcnt lgkmcnt(" #n ")" ::: "memory")
; #define PG8_BAR __builtin_amdgcn_s_barrier()
; #define PG8_SCHED __builtin_amdgcn_sched_barrier(0)
; template <class Epi, class Sched, bool ALIGN_EPI = false, bool SP2 = false>
; __device__ __forceinline__ void gemm_phase(PG8_LAS unsigned char* lds, const Gemm g, const Sched& S, const Epi& E) {
;     ...
;         const bool has_next = S.next(ui + 1, nxt);
;         const char* nA = has_next ? (const char*)g.A + (size_t)nxt.pm * tstepA : cA; const char* nB = has_next ? (const char*)g.Bt + (size_t)nxt.pn * tstepB : cB;
;         for (int t = 0; t < nt; t += 2) {
;             const bool last = (t == nt - 2);
;             const char* a1 = cA + (size_t)(t + 1) * kstepA;
;             const char* a2 = last ? nA : cA + (size_t)(t + 2) * kstepA; const char* b2 = last ? nB : cB + (size_t)(t + 2) * kstep;
;             const char* a3 = a2 + kstepA; const char* b3 = b2 + kstep;
;             if (last && has_next) S.a_ready(nxt);
;             if constexpr (SP2) {
;             PG8_LDB(B0, 0, 0); PG8_LDB(B1, 0, 1); PG8_SCHED; PG8_LDA(At, 0, 0); PG8_STAGE(PG8_SA(1, 1), a1 + hstepA, voffA);
;             PG8_WAIT_V(8); PG8_WAIT_L(0); PG8_BAR; PG8_MMA(0, 0, At, B0); PG8_MMA(0, 1, At, B1); PG8_BAR; PG8_SCHED;
;             PG8_LDA(At, 0, 1); PG8_STAGE(PG8_SB(0, 0), b2, voffB); PG8_STAGE(PG8_SB(0, 1), b2 + hstepB, voffB); PG8_STAGE(PG8_SA(0, 0), a2, voffA);
;             PG8_WAIT_V(8); PG8_WAIT_L(0); PG8_BAR; PG8_MMA(1, 0, At, B0); PG8_MMA(1, 1, At, B1); PG8_BAR; PG8_SCHED;
.LBB0_750:
	s_ashr_i32 s59, s58, 31
	s_lshl_b64 s[60:61], s[58:59], 19
	s_add_u32 s60, s6, s60
	s_addc_u32 s61, s7, s61
	s_and_b64 s[62:63], s[4:5], exec
	s_cselect_b32 s59, s61, s69
	s_cselect_b32 s65, s60, s68
	s_ashr_i32 s57, s56, 31
	s_lshl_b64 s[62:63], s[56:57], 19
	s_add_u32 s62, s93, s62
	s_addc_u32 s63, s84, s63
	s_and_b64 s[72:73], s[4:5], exec
	s_cselect_b32 s57, s63, s71
	s_cselect_b32 s67, s62, s70
	s_add_u32 s68, s68, 0x10000
	s_addc_u32 s69, s69, 0
	s_add_u32 s70, s70, 0x10000
	s_addc_u32 s71, s71, 0
	s_mov_b32 s72, -2
	s_waitcnt lgkmcnt(0)
	ds_read_b128 v[128:131], v211
	ds_read_b128 v[132:135], v211 offset:1024
	ds_read_b128 v[136:139], v211 offset:2048
	ds_read_b128 v[140:143], v211 offset:3072
	ds_read_b128 v[144:147], v212
	ds_read_b128 v[148:151], v212 offset:1024
	ds_read_b128 v[152:155], v212 offset:2048
	ds_read_b128 v[156:159], v212 offset:3072
	s_cmp_eq_u32 s72, 12
	s_cselect_b32 s79, s59, s69
	s_cselect_b32 s78, s65, s68
	s_cselect_b32 s91, s57, s71
	s_cselect_b32 s90, s67, s70
	v_lshl_add_u64 v[208:209], s[68:69], 0, v[190:191]
	v_lshl_add_u64 v[228:229], v[208:209], 0, s[52:53]
	s_add_i32 m0, s15, 0xc000
	ds_read_b128 v[160:163], v213
	ds_read_b128 v[164:167], v213 offset:1024
	ds_read_b128 v[168:171], v213 offset:2048
	ds_read_b128 v[172:175], v213 offset:3072
	ds_read_b128 v[176:179], v213 offset:4096
	ds_read_b128 v[180:183], v213 offset:5120
	ds_read_b128 v[220:223], v213 offset:6144
	ds_read_b128 v[224:227], v213 offset:7168
	global_load_lds_dwordx4 v[228:229], off
	v_lshl_add_u64 v[208:209], v[208:209], 0, s[54:55]
	s_add_i32 m0, s15, 0xe000
	s_nop 0
	global_load_lds_dwordx4 v[208:209], off
	s_waitcnt vmcnt(56)
	s_waitcnt lgkmcnt(0)
	s_barrier
	s_waitcnt lgkmcnt(0)
	v_mfma_f32_16x16x32_bf16 v[124:127], v[128:131], v[160:163], 0
	v_mfma_f32_16x16x32_bf16 v[120:123], v[136:139], v[160:163], 0
	v_mfma_f32_16x16x32_bf16 v[108:111], v[128:131], v[168:171], 0
	v_mfma_f32_16x16x32_bf16 v[104:107], v[136:139], v[168:171], 0
	v_mfma_f32_16x16x32_bf16 v[92:95], v[128:131], v[176:179], 0
	v_mfma_f32_16x16x32_bf16 v[88:91], v[136:139], v[176:179], 0
	v_mfma_f32_16x16x32_bf16 v[76:79], v[128:131], v[220:223], 0
	v_mfma_f32_16x16x32_bf16 v[72:75], v[136:139], v[220:223], 0
	v_mfma_f32_16x16x32_bf16 v[124:127], v[132:135], v[164:167], v[124:127]
	v_mfma_f32_16x16x32_bf16 v[120:123], v[140:143], v[164:167], v[120:123]
	v_mfma_f32_16x16x32_bf16 v[108:111], v[132:135], v[172:175], v[108:111]
	v_mfma_f32_16x16x32_bf16 v[104:107], v[140:143], v[172:175], v[104:107]
	v_mfma_f32_16x16x32_bf16 v[92:95], v[132:135], v[180:183], v[92:95]
	v_mfma_f32_16x16x32_bf16 v[88:91], v[140:143], v[180:183], v[88:91]
	v_mfma_f32_16x16x32_bf16 v[76:79], v[132:135], v[224:227], v[76:79]
	v_mfma_f32_16x16x32_bf16 v[72:75], v[140:143], v[224:227], v[72:75]
	v_mfma_f32_16x16x32_bf16 v[116:119], v[144:147], v[160:163], 0
	v_mfma_f32_16x16x32_bf16 v[112:115], v[152:155], v[160:163], 0
	v_mfma_f32_16x16x32_bf16 v[100:103], v[144:147], v[168:171], 0
	v_mfma_f32_16x16x32_bf16 v[96:99], v[152:155], v[168:171], 0
	v_mfma_f32_16x16x32_bf16 v[84:87], v[144:147], v[176:179], 0
	v_mfma_f32_16x16x32_bf16 v[80:83], v[152:155], v[176:179], 0
	v_mfma_f32_16x16x32_bf16 v[68:71], v[144:147], v[220:223], 0
	v_mfma_f32_16x16x32_bf16 v[64:67], v[152:155], v[220:223], 0
	v_mfma_f32_16x16x32_bf16 v[116:119], v[148:151], v[164:167], v[116:119]
	v_mfma_f32_16x16x32_bf16 v[112:115], v[156:159], v[164:167], v[112:115]
	v_mfma_f32_16x16x32_bf16 v[100:103], v[148:151], v[172:175], v[100:103]
	v_mfma_f32_16x16x32_bf16 v[96:99], v[156:159], v[172:175], v[96:99]
	v_mfma_f32_16x16x32_bf16 v[84:87], v[148:151], v[180:183], v[84:87]
	v_mfma_f32_16x16x32_bf16 v[80:83], v[156:159], v[180:183], v[80:83]
	v_mfma_f32_16x16x32_bf16 v[68:71], v[148:151], v[224:227], v[68:71]
	v_mfma_f32_16x16x32_bf16 v[64:67], v[156:159], v[224:227], v[64:67]
	s_barrier
	s_add_i32 s73, s85, s14
	v_lshl_add_u64 v[208:209], s[90:91], 0, v[190:191]
	s_mov_b32 m0, s73
	ds_read_b128 v[160:163], v213 offset:16384
	ds_read_b128 v[164:167], v213 offset:17408
	ds_read_b128 v[168:171], v213 offset:18432
	ds_read_b128 v[172:175], v213 offset:19456
	ds_read_b128 v[176:179], v213 offset:20480
	ds_read_b128 v[180:183], v213 offset:21504
	ds_read_b128 v[220:223], v213 offset:22528
	ds_read_b128 v[224:227], v213 offset:23552
	global_load_lds_dwordx4 v[208:209], off
	v_lshl_add_u64 v[228:229], v[208:209], 0, s[10:11]
	s_add_i32 m0, s73, 0x2000
	s_add_i32 s73, s86, s14
	global_load_lds_dwordx4 v[228:229], off
	v_lshl_add_u64 v[228:229], v[208:209], 0, s[34:35]
	s_mov_b32 m0, s73
	s_nop 0
	global_load_lds_dwordx4 v[228:229], off
	v_lshl_add_u64 v[228:229], v[208:209], 0, s[36:37]
	s_add_i32 m0, s73, 0x2000
	s_nop 0
	global_load_lds_dwordx4 v[228:229], off
	v_lshl_add_u64 v[228:229], s[78:79], 0, v[190:191]
	s_mov_b32 m0, s15
	v_lshl_add_u64 v[230:231], v[228:229], 0, s[10:11]
	global_load_lds_dwordx4 v[228:229], off
	s_mov_b32 m0, s17
	s_nop 0
	global_load_lds_dwordx4 v[230:231], off
	s_waitcnt vmcnt(56)
	s_waitcnt lgkmcnt(0)
	s_barrier
; #define PG8_STAGE(bufoff, gbase, voff) do { _Pragma("unroll") for (int _i = 0; _i < 2; ++_i) \
;         __builtin_amdgcn_global_load_lds((const unsigned*)((const char*)(gbase) + (voff)[_i]), (PG8_LAS unsigned*)(lds + (bufoff) + ldsw + _i * 8192), 16, 0, 0); } while (0)
; #define PG8_LDA(dst, b, h) do { _Pragma("unroll") for (int m = 0; m < 4; ++m) _Pragma("unroll") for (int k = 0; k < 2; ++k) dst[m][k] = *(const PG8_LAS bf16x8*)(lds + PG8_SA(b, h) + aoff + m * 2048 + k * 1024); } while (0)
; #define PG8_LDB(dst, b, h) do { _Pragma("unroll") for (int n = 0; n < 2; ++n) _Pragma("unroll") for (int k = 0; k < 2; ++k) dst[n][k] = *(const PG8_LAS bf16x8*)(lds + PG8_SB(b, h) + boff + n * 2048 + k * 1024); } while (0)
; #define PG8_MMA(ai, bj, At, Bt) do { __builtin_amdgcn_s_setprio(1); _Pragma("unroll") for (int m = 0; m < 4; ++m) _Pragma("unroll") for (int n = 0; n < 2; ++n) _Pragma("unroll") for (int k = 0; k < 2; ++k) \
;         acc[ai][bj][m][n] = __builtin_amdgcn_mfma_f32_16x16x32_bf16(Bt[n][k], At[m][k], acc[ai][bj][m][n], 0, 0, 0); __builtin_amdgcn_s_setprio(0); } while (0)
; #define PG8_WAIT_V(n) asm volatile("s_waitcnt vmcnt(" #n ")" ::: "memory")
; #define PG8_WAIT_L(n) asm volatile("s_waitcnt lgkmcnt(" #n ")" ::: "memory")
; #define PG8_BAR __builtin_amdgcn_s_barrier()
; #define PG8_SCHED __builtin_amdgcn_sched_barrier(0)
; template <class Epi, class Sched, bool ALIGN_EPI = false, bool SP2 = false>
; __device__ __forceinline__ void gemm_phase(PG8_LAS unsigned char* lds, const Gemm g, const Sched& S, const Epi& E) {
;     ...
;             PG8_WAIT_V(8); PG8_WAIT_L(0); PG8_BAR; PG8_MMA(1, 0, At, B0); PG8_MMA(1, 1, At, B1); PG8_BAR; PG8_SCHED;
;             PG8_LDB(B0, 1, 0); PG8_LDB(B1, 1, 1); PG8_SCHED; PG8_LDA(At, 1, 0); PG8_STAGE(PG8_SA(0, 1), a2 + hstepA, voffA);
;             PG8_WAIT_V(8); PG8_WAIT_L(0); PG8_BAR; PG8_MMA(0, 0, At, B0); PG8_MMA(0, 1, At, B1); PG8_BAR; PG8_SCHED;
	s_waitcnt lgkmcnt(0)
	v_mfma_f32_16x16x32_bf16 v[60:63], v[128:131], v[160:163], 0
	v_mfma_f32_16x16x32_bf16 v[56:59], v[136:139], v[160:163], 0
	v_mfma_f32_16x16x32_bf16 v[44:47], v[128:131], v[168:171], 0
	v_mfma_f32_16x16x32_bf16 v[40:43], v[136:139], v[168:171], 0
	v_mfma_f32_16x16x32_bf16 v[28:31], v[128:131], v[176:179], 0
	v_mfma_f32_16x16x32_bf16 v[24:27], v[136:139], v[176:179], 0
	v_mfma_f32_16x16x32_bf16 v[12:15], v[128:131], v[220:223], 0
	v_mfma_f32_16x16x32_bf16 v[8:11], v[136:139], v[220:223], 0
	v_mfma_f32_16x16x32_bf16 v[60:63], v[132:135], v[164:167], v[60:63]
	v_mfma_f32_16x16x32_bf16 v[56:59], v[140:143], v[164:167], v[56:59]
	v_mfma_f32_16x16x32_bf16 v[44:47], v[132:135], v[172:175], v[44:47]
	v_mfma_f32_16x16x32_bf16 v[40:43], v[140:143], v[172:175], v[40:43]
	v_mfma_f32_16x16x32_bf16 v[28:31], v[132:135], v[180:183], v[28:31]
	v_mfma_f32_16x16x32_bf16 v[24:27], v[140:143], v[180:183], v[24:27]
	v_mfma_f32_16x16x32_bf16 v[12:15], v[132:135], v[224:227], v[12:15]
	v_mfma_f32_16x16x32_bf16 v[8:11], v[140:143], v[224:227], v[8:11]
	v_mfma_f32_16x16x32_bf16 v[52:55], v[144:147], v[160:163], 0
	v_mfma_f32_16x16x32_bf16 v[48:51], v[152:155], v[160:163], 0
	v_mfma_f32_16x16x32_bf16 v[36:39], v[144:147], v[168:171], 0
	v_mfma_f32_16x16x32_bf16 v[32:35], v[152:155], v[168:171], 0
	v_mfma_f32_16x16x32_bf16 v[20:23], v[144:147], v[176:179], 0
	v_mfma_f32_16x16x32_bf16 v[16:19], v[152:155], v[176:179], 0
	v_mfma_f32_16x16x32_bf16 v[4:7], v[144:147], v[220:223], 0
	v_mfma_f32_16x16x32_bf16 v[0:3], v[152:155], v[220:223], 0
	v_mfma_f32_16x16x32_bf16 v[52:55], v[148:151], v[164:167], v[52:55]
	v_mfma_f32_16x16x32_bf16 v[48:51], v[156:159], v[164:167], v[48:51]
	v_mfma_f32_16x16x32_bf16 v[36:39], v[148:151], v[172:175], v[36:39]
	v_mfma_f32_16x16x32_bf16 v[32:35], v[156:159], v[172:175], v[32:35]
	v_mfma_f32_16x16x32_bf16 v[20:23], v[148:151], v[180:183], v[20:23]
	v_mfma_f32_16x16x32_bf16 v[16:19], v[156:159], v[180:183], v[16:19]
	v_mfma_f32_16x16x32_bf16 v[4:7], v[148:151], v[224:227], v[4:7]
	v_mfma_f32_16x16x32_bf16 v[0:3], v[156:159], v[224:227], v[0:3]
	s_barrier
	ds_read_b128 v[128:131], v214
	ds_read_b128 v[132:135], v214 offset:1024
	ds_read_b128 v[136:139], v214 offset:2048
	ds_read_b128 v[140:143], v214 offset:3072
	ds_read_b128 v[144:147], v215
	ds_read_b128 v[148:151], v215 offset:1024
	ds_read_b128 v[152:155], v215 offset:2048
	ds_read_b128 v[156:159], v215 offset:3072
	s_mov_b32 m0, s18
	v_lshl_add_u64 v[230:231], v[228:229], 0, s[34:35]
	ds_read_b128 v[160:163], v213 offset:32768
	ds_read_b128 v[164:167], v213 offset:33792
	ds_read_b128 v[168:171], v213 offset:34816
	ds_read_b128 v[172:175], v213 offset:35840
	ds_read_b128 v[176:179], v213 offset:36864
	ds_read_b128 v[180:183], v213 offset:37888
	ds_read_b128 v[220:223], v213 offset:38912
	ds_read_b128 v[224:227], v213 offset:39936
	global_load_lds_dwordx4 v[230:231], off
	v_lshl_add_u64 v[230:231], v[228:229], 0, s[36:37]
	s_mov_b32 m0, s19
	s_nop 0
	global_load_lds_dwordx4 v[230:231], off
	s_waitcnt vmcnt(8)
	s_waitcnt lgkmcnt(0)
	s_barrier
	s_waitcnt lgkmcnt(0)
	v_mfma_f32_16x16x32_bf16 v[124:127], v[128:131], v[160:163], v[124:127]
	v_mfma_f32_16x16x32_bf16 v[120:123], v[136:139], v[160:163], v[120:123]
	v_mfma_f32_16x16x32_bf16 v[108:111], v[128:131], v[168:171], v[108:111]
	v_mfma_f32_16x16x32_bf16 v[104:107], v[136:139], v[168:171], v[104:107]
	v_mfma_f32_16x16x32_bf16 v[92:95], v[128:131], v[176:179], v[92:95]
	v_mfma_f32_16x16x32_bf16 v[88:91], v[136:139], v[176:179], v[88:91]
	v_mfma_f32_16x16x32_bf16 v[76:79], v[128:131], v[220:223], v[76:79]
	v_mfma_f32_16x16x32_bf16 v[72:75], v[136:139], v[220:223], v[72:75]
	v_mfma_f32_16x16x32_bf16 v[124:127], v[132:135], v[164:167], v[124:127]
	v_mfma_f32_16x16x32_bf16 v[120:123], v[140:143], v[164:167], v[120:123]
	v_mfma_f32_16x16x32_bf16 v[108:111], v[132:135], v[172:175], v[108:111]
	v_mfma_f32_16x16x32_bf16 v[104:107], v[140:143], v[172:175], v[104:107]
	v_mfma_f32_16x16x32_bf16 v[92:95], v[132:135], v[180:183], v[92:95]
	v_mfma_f32_16x16x32_bf16 v[88:91], v[140:143], v[180:183], v[88:91]
	v_mfma_f32_16x16x32_bf16 v[76:79], v[132:135], v[224:227], v[76:79]
	v_mfma_f32_16x16x32_bf16 v[72:75], v[140:143], v[224:227], v[72:75]
	v_mfma_f32_16x16x32_bf16 v[116:119], v[144:147], v[160:163], v[116:119]
	v_mfma_f32_16x16x32_bf16 v[112:115], v[152:155], v[160:163], v[112:115]
	v_mfma_f32_16x16x32_bf16 v[100:103], v[144:147], v[168:171], v[100:103]
	v_mfma_f32_16x16x32_bf16 v[96:99], v[152:155], v[168:171], v[96:99]
	v_mfma_f32_16x16x32_bf16 v[84:87], v[144:147], v[176:179], v[84:87]
	v_mfma_f32_16x16x32_bf16 v[80:83], v[152:155], v[176:179], v[80:83]
	v_mfma_f32_16x16x32_bf16 v[68:71], v[144:147], v[220:223], v[68:71]
	v_mfma_f32_16x16x32_bf16 v[64:67], v[152:155], v[220:223], v[64:67]
	v_mfma_f32_16x16x32_bf16 v[116:119], v[148:151], v[164:167], v[116:119]
	v_mfma_f32_16x16x32_bf16 v[112:115], v[156:159], v[164:167], v[112:115]
	v_mfma_f32_16x16x32_bf16 v[100:103], v[148:151], v[172:175], v[100:103]
	v_mfma_f32_16x16x32_bf16 v[96:99], v[156:159], v[172:175], v[96:99]
	v_mfma_f32_16x16x32_bf16 v[84:87], v[148:151], v[180:183], v[84:87]
	v_mfma_f32_16x16x32_bf16 v[80:83], v[156:159], v[180:183], v[80:83]
	v_mfma_f32_16x16x32_bf16 v[68:71], v[148:151], v[224:227], v[68:71]
	v_mfma_f32_16x16x32_bf16 v[64:67], v[156:159], v[224:227], v[64:67]
	s_barrier
; #define PG8_STAGE(bufoff, gbase, voff) do { _Pragma("unroll") for (int _i = 0; _i < 2; ++_i) \
;         __builtin_amdgcn_global_load_lds((const unsigned*)((const char*)(gbase) + (voff)[_i]), (PG8_LAS unsigned*)(lds + (bufoff) + ldsw + _i * 8192), 16, 0, 0); } while (0)
; #define PG8_LDA(dst, b, h) do { _Pragma("unroll") for (int m = 0; m < 4; ++m) _Pragma("unroll") for (int k = 0; k < 2; ++k) dst[m][k] = *(const PG8_LAS bf16x8*)(lds + PG8_SA(b, h) + aoff + m * 2048 + k * 1024); } while (0)
; #define PG8_MMA(ai, bj, At, Bt) do { __builtin_amdgcn_s_setprio(1); _Pragma("unroll") for (int m = 0; m < 4; ++m) _Pragma("unroll") for (int n = 0; n < 2; ++n) _Pragma("unroll") for (int k = 0; k < 2; ++k) \
;         acc[ai][bj][m][n] = __builtin_amdgcn_mfma_f32_16x16x32_bf16(Bt[n][k], At[m][k], acc[ai][bj][m][n], 0, 0, 0); __builtin_amdgcn_s_setprio(0); } while (0)
; #define PG8_WAIT_V(n) asm volatile("s_waitcnt vmcnt(" #n ")" ::: "memory")
; #define PG8_WAIT_L(n) asm volatile("s_waitcnt lgkmcnt(" #n ")" ::: "memory")
; #define PG8_BAR __builtin_amdgcn_s_barrier()
; #define PG8_SCHED __builtin_amdgcn_sched_barrier(0)
; template <class Epi, class Sched, bool ALIGN_EPI = false, bool SP2 = false>
; __device__ __forceinline__ void gemm_phase(PG8_LAS unsigned char* lds, const Gemm g, const Sched& S, const Epi& E) {
;     ...
;         for (int t = 0; t < nt; t += 2) {
;     ...
;             PG8_LDA(At, 1, 1); PG8_STAGE(PG8_SB(1, 0), b3, voffB); PG8_STAGE(PG8_SB(1, 1), b3 + hstepB, voffB); PG8_STAGE(PG8_SA(1, 0), a3, voffA);
;             PG8_WAIT_V(8); PG8_WAIT_L(0); PG8_BAR; PG8_MMA(1, 0, At, B0); PG8_MMA(1, 1, At, B1); PG8_BAR; PG8_SCHED;
	s_add_i32 s73, s87, s14
	v_lshl_add_u64 v[230:231], v[208:209], 0, s[38:39]
	s_mov_b32 m0, s73
	ds_read_b128 v[160:163], v213 offset:49152
	ds_read_b128 v[164:167], v213 offset:50176
	ds_read_b128 v[168:171], v213 offset:51200
	ds_read_b128 v[172:175], v213 offset:52224
	ds_read_b128 v[176:179], v213 offset:53248
	ds_read_b128 v[180:183], v213 offset:54272
	ds_read_b128 v[220:223], v213 offset:55296
	ds_read_b128 v[224:227], v213 offset:56320
	global_load_lds_dwordx4 v[230:231], off
	v_lshl_add_u64 v[230:231], v[208:209], 0, s[40:41]
	s_add_i32 m0, s73, 0x2000
	s_add_i32 s73, s88, s14
	global_load_lds_dwordx4 v[230:231], off
	v_lshl_add_u64 v[230:231], v[208:209], 0, s[42:43]
	s_mov_b32 m0, s73
	v_lshl_add_u64 v[208:209], v[208:209], 0, s[44:45]
	global_load_lds_dwordx4 v[230:231], off
	s_add_i32 m0, s73, 0x2000
	s_nop 0
	global_load_lds_dwordx4 v[208:209], off
	v_lshl_add_u64 v[208:209], v[228:229], 0, s[38:39]
	s_mov_b32 m0, s74
	s_nop 0
	global_load_lds_dwordx4 v[208:209], off
	v_lshl_add_u64 v[208:209], v[228:229], 0, s[40:41]
	s_mov_b32 m0, s75
	s_nop 0
	global_load_lds_dwordx4 v[208:209], off
	s_waitcnt vmcnt(8)
	s_waitcnt lgkmcnt(0)
	s_barrier
	s_waitcnt lgkmcnt(0)
	v_mfma_f32_16x16x32_bf16 v[60:63], v[128:131], v[160:163], v[60:63]
	v_mfma_f32_16x16x32_bf16 v[56:59], v[136:139], v[160:163], v[56:59]
	v_mfma_f32_16x16x32_bf16 v[44:47], v[128:131], v[168:171], v[44:47]
	v_mfma_f32_16x16x32_bf16 v[40:43], v[136:139], v[168:171], v[40:43]
	v_mfma_f32_16x16x32_bf16 v[28:31], v[128:131], v[176:179], v[28:31]
	v_mfma_f32_16x16x32_bf16 v[24:27], v[136:139], v[176:179], v[24:27]
	v_mfma_f32_16x16x32_bf16 v[12:15], v[128:131], v[220:223], v[12:15]
	v_mfma_f32_16x16x32_bf16 v[8:11], v[136:139], v[220:223], v[8:11]
	v_mfma_f32_16x16x32_bf16 v[60:63], v[132:135], v[164:167], v[60:63]
	v_mfma_f32_16x16x32_bf16 v[56:59], v[140:143], v[164:167], v[56:59]
	v_mfma_f32_16x16x32_bf16 v[44:47], v[132:135], v[172:175], v[44:47]
	v_mfma_f32_16x16x32_bf16 v[40:43], v[140:143], v[172:175], v[40:43]
	v_mfma_f32_16x16x32_bf16 v[28:31], v[132:135], v[180:183], v[28:31]
	v_mfma_f32_16x16x32_bf16 v[24:27], v[140:143], v[180:183], v[24:27]
	v_mfma_f32_16x16x32_bf16 v[12:15], v[132:135], v[224:227], v[12:15]
	v_mfma_f32_16x16x32_bf16 v[8:11], v[140:143], v[224:227], v[8:11]
	v_mfma_f32_16x16x32_bf16 v[52:55], v[144:147], v[160:163], v[52:55]
	v_mfma_f32_16x16x32_bf16 v[48:51], v[152:155], v[160:163], v[48:51]
	v_mfma_f32_16x16x32_bf16 v[36:39], v[144:147], v[168:171], v[36:39]
	v_mfma_f32_16x16x32_bf16 v[32:35], v[152:155], v[168:171], v[32:35]
	v_mfma_f32_16x16x32_bf16 v[20:23], v[144:147], v[176:179], v[20:23]
	v_mfma_f32_16x16x32_bf16 v[16:19], v[152:155], v[176:179], v[16:19]
	v_mfma_f32_16x16x32_bf16 v[4:7], v[144:147], v[220:223], v[4:7]
	v_mfma_f32_16x16x32_bf16 v[0:3], v[152:155], v[220:223], v[0:3]
	v_mfma_f32_16x16x32_bf16 v[52:55], v[148:151], v[164:167], v[52:55]
	v_mfma_f32_16x16x32_bf16 v[48:51], v[156:159], v[164:167], v[48:51]
	v_mfma_f32_16x16x32_bf16 v[36:39], v[148:151], v[172:175], v[36:39]
	v_mfma_f32_16x16x32_bf16 v[32:35], v[156:159], v[172:175], v[32:35]
	v_mfma_f32_16x16x32_bf16 v[20:23], v[148:151], v[180:183], v[20:23]
	v_mfma_f32_16x16x32_bf16 v[16:19], v[156:159], v[180:183], v[16:19]
	v_mfma_f32_16x16x32_bf16 v[4:7], v[148:151], v[224:227], v[4:7]
	v_mfma_f32_16x16x32_bf16 v[0:3], v[156:159], v[224:227], v[0:3]
	s_barrier
	s_add_i32 s72, s72, 2
	s_add_u32 s68, s68, 0x10000
	s_addc_u32 s69, s69, 0
	s_add_u32 s70, s70, 0x10000
	s_addc_u32 s71, s71, 0
	s_cmp_gt_u32 s72, 13

; #define PG8_STAGE(bufoff, gbase, voff) do { _Pragma("unroll") for (int _i = 0; _i < 2; ++_i) \
;         __builtin_amdgcn_global_load_lds((const unsigned*)((const char*)(gbase) + (voff)[_i]), (PG8_LAS unsigned*)(lds + (bufoff) + ldsw + _i * 8192), 16, 0, 0); } while (0)
; #define PG8_WAIT_V(n) asm volatile("s_waitcnt vmcnt(" #n ")" ::: "memory")
; #define PG8_BAR __builtin_amdgcn_s_barrier()
; template <class Epi, class Sched, bool ALIGN_EPI = false, bool SP2 = false>
; __device__ __forceinline__ void gemm_phase(PG8_LAS unsigned char* lds, const Gemm g, const Sched& S, const Epi& E) {
;     const int tid = threadIdx.x, wid = __builtin_amdgcn_readfirstlane(tid >> 6), lane = tid & 63, wr = wid >> 2, wc = wid & 3, fr = lane & 15, fq = lane >> 4;
;     const int K = g.K, nt = K / BK;
;     unsigned voffA[2], voffB[2];
; #pragma unroll
;     for (int i = 0; i < 2; ++i) { int R, C; stage_rc(tid * 16 + i * 8192, R, C); const int Rb = Epi::PERM ? ((R & ~31) + perm32(R & 31)) : R;
;         voffA[i] = g.a_pre ? (unsigned)(tid * 16 + i * 8192) : (unsigned)(R * g.lda + C) * 2u; voffB[i] = g.b_pre ? (unsigned)(tid * 16 + i * 8192) : (unsigned)(Rb * g.ldb + C) * 2u; }
;     const size_t kstep = g.b_pre ? (size_t)(2 * HTB) : (size_t)(BK * 2);
;     const size_t hstepA = (size_t)HALF * g.lda * 2, hstepB = (size_t)HALF * g.ldb * 2;
;     const size_t tstepA = g.pstepA, tstepB = g.b_pre ? (size_t)(g.K / BK) * (2 * HTB) : 2 * hstepB;
;     const size_t kstepA = g.kstepA;
;     const unsigned ldsw = (unsigned)wid * 1024u;
;     const int aoff = lds_byte(wr * 64 + fr, fq * 8), boff = lds_byte(wc * 32 + fr, fq * 8);
;     ...
;     if constexpr (SP2) {
;         PG8_STAGE(PG8_SB(0, 0), cB, voffB); PG8_STAGE(PG8_SB(0, 1), cB + hstepB, voffB); PG8_STAGE(PG8_SA(0, 0), cA, voffA); PG8_STAGE(PG8_SA(0, 1), cA + hstepA, voffA);
;         PG8_STAGE(PG8_SB(1, 0), cB + kstep, voffB); PG8_STAGE(PG8_SA(1, 0), cA + kstepA, voffA); PG8_STAGE(PG8_SB(1, 1), cB + hstepB + kstep, voffB);
;         if (wr == 1) PG8_BAR;
;         PG8_WAIT_V(8); PG8_BAR;
;         PG8_WAIT_V(6); PG8_BAR;
.LBB0_832:
	s_sext_i32_i8 s61, s2
	s_and_b32 s2, s45, 3
	v_lshlrev_b32_e32 v4, 6, v188
	v_and_b32_e32 v0, 48, v188
	s_lshl_b32 s46, s44, 13
	v_lshlrev_b32_e32 v1, 6, v189
	v_lshlrev_b32_e32 v3, 2, v188
	s_lshl_b32 s71, s2, 5
	s_lshl_b32 s2, s2, 12
	v_and_b32_e32 v4, 0x3c0, v4
	v_or_b32_e32 v2, v1, v0
	v_and_b32_e32 v3, 32, v3
	v_or_b32_e32 v5, v4, v0
	s_cmpk_lt_u32 s3, 0x100
	v_lshl_or_b32 v140, s44, 6, v189
	v_bitop3_b32 v1, v1, v3, v0 bitop3:0x36
	v_bitop3_b32 v2, v2, s46, v3 bitop3:0xde
	v_bitop3_b32 v0, v4, v3, v0 bitop3:0x36
	v_bitop3_b32 v3, s2, v5, v3 bitop3:0xf6
	s_cselect_b64 s[44:45], -1, 0
	s_lshl_b32 s2, s3, 4
	s_and_b32 s2, s2, 0x400
	s_waitcnt vmcnt(8)
	s_barrier
	s_waitcnt vmcnt(0)
	s_or_b32 s2, s2, s46
	v_or_b32_e32 v128, s2, v1
	v_or_b32_e32 v0, s2, v0
	s_add_i32 s74, 0, 0x10000
	s_add_i32 s75, 0, 0x14000
	s_movk_i32 s46, 0xc000
	s_movk_i32 s48, 0xe000
	s_add_i32 s76, 0, 0x18000
	s_add_i32 s77, 0, 0x1c000
	v_ashrrev_i32_e32 v129, 31, v128
	v_or_b32_e32 v130, 0x800, v0
	v_mov_b32_e32 v131, v191
	v_or_b32_e32 v132, 0x1000, v0
	v_mov_b32_e32 v133, v191
	v_or_b32_e32 v134, 0x1800, v0
	v_mov_b32_e32 v135, v191
	s_ashr_i32 s72, s26, 31
	s_mov_b32 s73, s26
	v_mov_b64_e32 v[136:137], 0xb00
	v_mov_b64_e32 v[138:139], 0xaff
	v_add_u32_e32 v141, s74, v3
	v_add_u32_e32 v142, s75, v3
	v_add_u32_e32 v143, 0, v2
	s_mov_b32 s47, -1
	s_mov_b32 s49, -1
	v_add_u32_e32 v144, s76, v3
	v_add_u32_e32 v145, s77, v3
	v_mov_b32_e32 v146, 0x358637bd
	s_barrier
	s_branch .LBB0_835

; #define PG8_STAGE(bufoff, gbase, voff) do { _Pragma("unroll") for (int _i = 0; _i < 2; ++_i) \
;         __builtin_amdgcn_global_load_lds((const unsigned*)((const char*)(gbase) + (voff)[_i]), (PG8_LAS unsigned*)(lds + (bufoff) + ldsw + _i * 8192), 16, 0, 0); } while (0)
; #define PG8_LDA(dst, b, h) do { _Pragma("unroll") for (int m = 0; m < 4; ++m) _Pragma("unroll") for (int k = 0; k < 2; ++k) dst[m][k] = *(const PG8_LAS bf16x8*)(lds + PG8_SA(b, h) + aoff + m * 2048 + k * 1024); } while (0)
; #define PG8_LDB(dst, b, h) do { _Pragma("unroll") for (int n = 0; n < 2; ++n) _Pragma("unroll") for (int k = 0; k < 2; ++k) dst[n][k] = *(const PG8_LAS bf16x8*)(lds + PG8_SB(b, h) + boff + n * 2048 + k * 1024); } while (0)
; #define PG8_WAIT_V(n) asm volatile("s_waitcnt vmcnt(" #n ")" ::: "memory")
; #define PG8_WAIT_L(n) asm volatile("s_waitcnt lgkmcnt(" #n ")" ::: "memory")
; #define PG8_BAR __builtin_amdgcn_s_barrier()
; #define PG8_SCHED __builtin_amdgcn_sched_barrier(0)
; template <class Epi, class Sched, bool ALIGN_EPI = false, bool SP2 = false>
; __device__ __forceinline__ void gemm_phase(PG8_LAS unsigned char* lds, const Gemm g, const Sched& S, const Epi& E) {
;     ...
;         const bool has_next = S.next(ui + 1, nxt);
;         const char* nA = has_next ? (const char*)g.A + (size_t)nxt.pm * tstepA : cA; const char* nB = has_next ? (const char*)g.Bt + (size_t)nxt.pn * tstepB : cB;
;         for (int t = 0; t < nt; t += 2) {
;             const bool last = (t == nt - 2);
;             const char* a1 = cA + (size_t)(t + 1) * kstepA;
;             const char* a2 = last ? nA : cA + (size_t)(t + 2) * kstepA; const char* b2 = last ? nB : cB + (size_t)(t + 2) * kstep;
;             const char* a3 = a2 + kstepA; const char* b3 = b2 + kstep;
;             if (last && has_next) S.a_ready(nxt);
;             if constexpr (SP2) {
;             PG8_LDB(B0, 0, 0); PG8_LDB(B1, 0, 1); PG8_SCHED; PG8_LDA(At, 0, 0); PG8_STAGE(PG8_SA(1, 1), a1 + hstepA, voffA);
;             PG8_WAIT_V(8); PG8_WAIT_L(0); PG8_BAR; PG8_MMA(0, 0, At, B0); PG8_MMA(0, 1, At, B1); PG8_BAR; PG8_SCHED;
;             PG8_LDA(At, 0, 1); PG8_STAGE(PG8_SB(0, 0), b2, voffB); PG8_STAGE(PG8_SB(0, 1), b2 + hstepB, voffB); PG8_STAGE(PG8_SA(0, 0), a2, voffA);
;             PG8_WAIT_V(8); PG8_WAIT_L(0); PG8_BAR; PG8_MMA(1, 0, At, B0); PG8_MMA(1, 1, At, B1); PG8_BAR; PG8_SCHED;
.LBB0_837:
	s_ashr_i32 s55, s54, 31
	s_lshl_b64 s[56:57], s[54:55], 19
	s_add_u32 s56, s12, s56
	s_addc_u32 s57, s13, s57
	s_and_b64 s[58:59], s[2:3], exec
	s_cselect_b32 s55, s57, s63
	s_cselect_b32 s80, s56, s62
	s_ashr_i32 s53, s52, 31
	s_lshl_b64 s[58:59], s[52:53], 19
	s_add_u32 s58, s33, s58
	s_addc_u32 s59, s83, s59
	s_and_b64 s[78:79], s[2:3], exec
	s_cselect_b32 s53, s59, s65
	s_cselect_b32 s81, s58, s64
	s_add_u32 s62, s62, 0x10000
	s_addc_u32 s63, s63, 0
	s_add_u32 s64, s64, 0x10000
	s_addc_u32 s65, s65, 0
	s_mov_b32 s82, -2
	ds_read_b128 v[148:151], v141
	ds_read_b128 v[152:155], v141 offset:1024
	ds_read_b128 v[156:159], v141 offset:2048
	ds_read_b128 v[160:163], v141 offset:3072
	ds_read_b128 v[164:167], v142
	ds_read_b128 v[168:171], v142 offset:1024
	ds_read_b128 v[172:175], v142 offset:2048
	ds_read_b128 v[176:179], v142 offset:3072
	s_cmp_eq_u32 s82, 12
	s_cselect_b32 s79, s55, s63
	s_cselect_b32 s78, s80, s62
	s_cselect_b32 s85, s53, s65
	s_cselect_b32 s84, s81, s64
	v_lshl_add_u64 v[216:217], s[62:63], 0, v[190:191]
	v_lshl_add_u64 v[220:221], v[216:217], 0, s[46:47]
	s_add_i32 m0, s18, 0xc000
	ds_read_b128 v[180:183], v143
	ds_read_b128 v[184:187], v143 offset:1024
	ds_read_b128 v[192:195], v143 offset:2048
	ds_read_b128 v[196:199], v143 offset:3072
	ds_read_b128 v[200:203], v143 offset:4096
	ds_read_b128 v[204:207], v143 offset:5120
	ds_read_b128 v[208:211], v143 offset:6144
	ds_read_b128 v[212:215], v143 offset:7168
	global_load_lds_dwordx4 v[220:221], off
	v_lshl_add_u64 v[216:217], v[216:217], 0, s[48:49]
	s_add_i32 m0, s18, 0xe000
	s_nop 0
	global_load_lds_dwordx4 v[216:217], off
	s_waitcnt vmcnt(56)
	s_waitcnt lgkmcnt(0)
	s_barrier
	s_waitcnt lgkmcnt(0)
	v_mfma_f32_16x16x32_bf16 v[116:119], v[148:151], v[180:183], 0
	v_mfma_f32_16x16x32_bf16 v[112:115], v[156:159], v[180:183], 0
	v_mfma_f32_16x16x32_bf16 v[108:111], v[148:151], v[192:195], 0
	v_mfma_f32_16x16x32_bf16 v[100:103], v[156:159], v[192:195], 0
	v_mfma_f32_16x16x32_bf16 v[92:95], v[148:151], v[200:203], 0
	v_mfma_f32_16x16x32_bf16 v[84:87], v[156:159], v[200:203], 0
	v_mfma_f32_16x16x32_bf16 v[76:79], v[148:151], v[208:211], 0
	v_mfma_f32_16x16x32_bf16 v[68:71], v[156:159], v[208:211], 0
	v_mfma_f32_16x16x32_bf16 v[116:119], v[152:155], v[184:187], v[116:119]
	v_mfma_f32_16x16x32_bf16 v[112:115], v[160:163], v[184:187], v[112:115]
	v_mfma_f32_16x16x32_bf16 v[108:111], v[152:155], v[196:199], v[108:111]
	v_mfma_f32_16x16x32_bf16 v[100:103], v[160:163], v[196:199], v[100:103]
	v_mfma_f32_16x16x32_bf16 v[92:95], v[152:155], v[204:207], v[92:95]
	v_mfma_f32_16x16x32_bf16 v[84:87], v[160:163], v[204:207], v[84:87]
	v_mfma_f32_16x16x32_bf16 v[76:79], v[152:155], v[212:215], v[76:79]
	v_mfma_f32_16x16x32_bf16 v[68:71], v[160:163], v[212:215], v[68:71]
	v_mfma_f32_16x16x32_bf16 v[124:127], v[164:167], v[180:183], 0
	v_mfma_f32_16x16x32_bf16 v[120:123], v[172:175], v[180:183], 0
	v_mfma_f32_16x16x32_bf16 v[104:107], v[164:167], v[192:195], 0
	v_mfma_f32_16x16x32_bf16 v[96:99], v[172:175], v[192:195], 0
	v_mfma_f32_16x16x32_bf16 v[88:91], v[164:167], v[200:203], 0
	v_mfma_f32_16x16x32_bf16 v[80:83], v[172:175], v[200:203], 0
	v_mfma_f32_16x16x32_bf16 v[72:75], v[164:167], v[208:211], 0
	v_mfma_f32_16x16x32_bf16 v[64:67], v[172:175], v[208:211], 0
	v_mfma_f32_16x16x32_bf16 v[124:127], v[168:171], v[184:187], v[124:127]
	v_mfma_f32_16x16x32_bf16 v[120:123], v[176:179], v[184:187], v[120:123]
	v_mfma_f32_16x16x32_bf16 v[104:107], v[168:171], v[196:199], v[104:107]
	v_mfma_f32_16x16x32_bf16 v[96:99], v[176:179], v[196:199], v[96:99]
	v_mfma_f32_16x16x32_bf16 v[88:91], v[168:171], v[204:207], v[88:91]
	v_mfma_f32_16x16x32_bf16 v[80:83], v[176:179], v[204:207], v[80:83]
	v_mfma_f32_16x16x32_bf16 v[72:75], v[168:171], v[212:215], v[72:75]
	v_mfma_f32_16x16x32_bf16 v[64:67], v[176:179], v[212:215], v[64:67]
	s_barrier
	v_lshl_add_u64 v[216:217], s[84:85], 0, v[190:191]
	s_add_i32 s84, s74, s14
	s_mov_b32 m0, s84
	ds_read_b128 v[180:183], v143 offset:16384
	ds_read_b128 v[184:187], v143 offset:17408
	ds_read_b128 v[192:195], v143 offset:18432
	ds_read_b128 v[196:199], v143 offset:19456
	ds_read_b128 v[200:203], v143 offset:20480
	ds_read_b128 v[204:207], v143 offset:21504
	ds_read_b128 v[208:211], v143 offset:22528
	ds_read_b128 v[212:215], v143 offset:23552
	global_load_lds_dwordx4 v[216:217], off
	v_lshl_add_u64 v[220:221], v[216:217], 0, s[6:7]
	s_add_i32 m0, s84, 0x2000
	s_add_i32 s84, s75, s14
	global_load_lds_dwordx4 v[220:221], off
	v_lshl_add_u64 v[220:221], v[216:217], 0, s[8:9]
	s_mov_b32 m0, s84
	s_nop 0
	global_load_lds_dwordx4 v[220:221], off
	v_lshl_add_u64 v[220:221], v[216:217], 0, s[10:11]
	s_add_i32 m0, s84, 0x2000
	s_nop 0
	global_load_lds_dwordx4 v[220:221], off
	v_lshl_add_u64 v[220:221], s[78:79], 0, v[190:191]
	s_mov_b32 m0, s18
	v_lshl_add_u64 v[222:223], v[220:221], 0, s[6:7]
	global_load_lds_dwordx4 v[220:221], off
	s_mov_b32 m0, s19
	s_nop 0
	global_load_lds_dwordx4 v[222:223], off
	s_waitcnt vmcnt(56)
	s_waitcnt lgkmcnt(0)
	s_barrier
; #define PG8_STAGE(bufoff, gbase, voff) do { _Pragma("unroll") for (int _i = 0; _i < 2; ++_i) \
;         __builtin_amdgcn_global_load_lds((const unsigned*)((const char*)(gbase) + (voff)[_i]), (PG8_LAS unsigned*)(lds + (bufoff) + ldsw + _i * 8192), 16, 0, 0); } while (0)
; #define PG8_LDA(dst, b, h) do { _Pragma("unroll") for (int m = 0; m < 4; ++m) _Pragma("unroll") for (int k = 0; k < 2; ++k) dst[m][k] = *(const PG8_LAS bf16x8*)(lds + PG8_SA(b, h) + aoff + m * 2048 + k * 1024); } while (0)
; #define PG8_LDB(dst, b, h) do { _Pragma("unroll") for (int n = 0; n < 2; ++n) _Pragma("unroll") for (int k = 0; k < 2; ++k) dst[n][k] = *(const PG8_LAS bf16x8*)(lds + PG8_SB(b, h) + boff + n * 2048 + k * 1024); } while (0)
; #define PG8_MMA(ai, bj, At, Bt) do { __builtin_amdgcn_s_setprio(1); _Pragma("unroll") for (int m = 0; m < 4; ++m) _Pragma("unroll") for (int n = 0; n < 2; ++n) _Pragma("unroll") for (int k = 0; k < 2; ++k) \
;         acc[ai][bj][m][n] = __builtin_amdgcn_mfma_f32_16x16x32_bf16(Bt[n][k], At[m][k], acc[ai][bj][m][n], 0, 0, 0); __builtin_amdgcn_s_setprio(0); } while (0)
; #define PG8_WAIT_V(n) asm volatile("s_waitcnt vmcnt(" #n ")" ::: "memory")
; #define PG8_WAIT_L(n) asm volatile("s_waitcnt lgkmcnt(" #n ")" ::: "memory")
; #define PG8_BAR __builtin_amdgcn_s_barrier()
; #define PG8_SCHED __builtin_amdgcn_sched_barrier(0)
; template <class Epi, class Sched, bool ALIGN_EPI = false, bool SP2 = false>
; __device__ __forceinline__ void gemm_phase(PG8_LAS unsigned char* lds, const Gemm g, const Sched& S, const Epi& E) {
;     ...
;             PG8_WAIT_V(8); PG8_WAIT_L(0); PG8_BAR; PG8_MMA(1, 0, At, B0); PG8_MMA(1, 1, At, B1); PG8_BAR; PG8_SCHED;
;             PG8_LDB(B0, 1, 0); PG8_LDB(B1, 1, 1); PG8_SCHED; PG8_LDA(At, 1, 0); PG8_STAGE(PG8_SA(0, 1), a2 + hstepA, voffA);
;             PG8_WAIT_V(8); PG8_WAIT_L(0); PG8_BAR; PG8_MMA(0, 0, At, B0); PG8_MMA(0, 1, At, B1); PG8_BAR; PG8_SCHED;
	s_waitcnt lgkmcnt(0)
	v_mfma_f32_16x16x32_bf16 v[60:63], v[148:151], v[180:183], 0
	v_mfma_f32_16x16x32_bf16 v[52:55], v[156:159], v[180:183], 0
	v_mfma_f32_16x16x32_bf16 v[44:47], v[148:151], v[192:195], 0
	v_mfma_f32_16x16x32_bf16 v[36:39], v[156:159], v[192:195], 0
	v_mfma_f32_16x16x32_bf16 v[28:31], v[148:151], v[200:203], 0
	v_mfma_f32_16x16x32_bf16 v[20:23], v[156:159], v[200:203], 0
	v_mfma_f32_16x16x32_bf16 v[12:15], v[148:151], v[208:211], 0
	v_mfma_f32_16x16x32_bf16 v[4:7], v[156:159], v[208:211], 0
	v_mfma_f32_16x16x32_bf16 v[60:63], v[152:155], v[184:187], v[60:63]
	v_mfma_f32_16x16x32_bf16 v[52:55], v[160:163], v[184:187], v[52:55]
	v_mfma_f32_16x16x32_bf16 v[44:47], v[152:155], v[196:199], v[44:47]
	v_mfma_f32_16x16x32_bf16 v[36:39], v[160:163], v[196:199], v[36:39]
	v_mfma_f32_16x16x32_bf16 v[28:31], v[152:155], v[204:207], v[28:31]
	v_mfma_f32_16x16x32_bf16 v[20:23], v[160:163], v[204:207], v[20:23]
	v_mfma_f32_16x16x32_bf16 v[12:15], v[152:155], v[212:215], v[12:15]
	v_mfma_f32_16x16x32_bf16 v[4:7], v[160:163], v[212:215], v[4:7]
	v_mfma_f32_16x16x32_bf16 v[56:59], v[164:167], v[180:183], 0
	v_mfma_f32_16x16x32_bf16 v[48:51], v[172:175], v[180:183], 0
	v_mfma_f32_16x16x32_bf16 v[40:43], v[164:167], v[192:195], 0
	v_mfma_f32_16x16x32_bf16 v[32:35], v[172:175], v[192:195], 0
	v_mfma_f32_16x16x32_bf16 v[24:27], v[164:167], v[200:203], 0
	v_mfma_f32_16x16x32_bf16 v[16:19], v[172:175], v[200:203], 0
	v_mfma_f32_16x16x32_bf16 v[8:11], v[164:167], v[208:211], 0
	v_mfma_f32_16x16x32_bf16 v[0:3], v[172:175], v[208:211], 0
	v_mfma_f32_16x16x32_bf16 v[56:59], v[168:171], v[184:187], v[56:59]
	v_mfma_f32_16x16x32_bf16 v[48:51], v[176:179], v[184:187], v[48:51]
	v_mfma_f32_16x16x32_bf16 v[40:43], v[168:171], v[196:199], v[40:43]
	v_mfma_f32_16x16x32_bf16 v[32:35], v[176:179], v[196:199], v[32:35]
	v_mfma_f32_16x16x32_bf16 v[24:27], v[168:171], v[204:207], v[24:27]
	v_mfma_f32_16x16x32_bf16 v[16:19], v[176:179], v[204:207], v[16:19]
	v_mfma_f32_16x16x32_bf16 v[8:11], v[168:171], v[212:215], v[8:11]
	v_mfma_f32_16x16x32_bf16 v[0:3], v[176:179], v[212:215], v[0:3]
	s_barrier
	ds_read_b128 v[148:151], v144
	ds_read_b128 v[152:155], v144 offset:1024
	ds_read_b128 v[156:159], v144 offset:2048
	ds_read_b128 v[160:163], v144 offset:3072
	ds_read_b128 v[164:167], v145
	ds_read_b128 v[168:171], v145 offset:1024
	ds_read_b128 v[172:175], v145 offset:2048
	ds_read_b128 v[176:179], v145 offset:3072
	s_mov_b32 m0, s66
	v_lshl_add_u64 v[222:223], v[220:221], 0, s[8:9]
	ds_read_b128 v[180:183], v143 offset:32768
	ds_read_b128 v[184:187], v143 offset:33792
	ds_read_b128 v[192:195], v143 offset:34816
	ds_read_b128 v[196:199], v143 offset:35840
	ds_read_b128 v[200:203], v143 offset:36864
	ds_read_b128 v[204:207], v143 offset:37888
	ds_read_b128 v[208:211], v143 offset:38912
	ds_read_b128 v[212:215], v143 offset:39936
	global_load_lds_dwordx4 v[222:223], off
	v_lshl_add_u64 v[222:223], v[220:221], 0, s[10:11]
	s_mov_b32 m0, s67
	s_nop 0
	global_load_lds_dwordx4 v[222:223], off
	s_waitcnt vmcnt(8)
	s_waitcnt lgkmcnt(0)
	s_barrier
	s_waitcnt lgkmcnt(0)
	v_mfma_f32_16x16x32_bf16 v[116:119], v[148:151], v[180:183], v[116:119]
	v_mfma_f32_16x16x32_bf16 v[112:115], v[156:159], v[180:183], v[112:115]
	v_mfma_f32_16x16x32_bf16 v[108:111], v[148:151], v[192:195], v[108:111]
	v_mfma_f32_16x16x32_bf16 v[100:103], v[156:159], v[192:195], v[100:103]
	v_mfma_f32_16x16x32_bf16 v[92:95], v[148:151], v[200:203], v[92:95]
	v_mfma_f32_16x16x32_bf16 v[84:87], v[156:159], v[200:203], v[84:87]
	v_mfma_f32_16x16x32_bf16 v[76:79], v[148:151], v[208:211], v[76:79]
	v_mfma_f32_16x16x32_bf16 v[68:71], v[156:159], v[208:211], v[68:71]
	v_mfma_f32_16x16x32_bf16 v[116:119], v[152:155], v[184:187], v[116:119]
	v_mfma_f32_16x16x32_bf16 v[112:115], v[160:163], v[184:187], v[112:115]
	v_mfma_f32_16x16x32_bf16 v[108:111], v[152:155], v[196:199], v[108:111]
	v_mfma_f32_16x16x32_bf16 v[100:103], v[160:163], v[196:199], v[100:103]
	v_mfma_f32_16x16x32_bf16 v[92:95], v[152:155], v[204:207], v[92:95]
	v_mfma_f32_16x16x32_bf16 v[84:87], v[160:163], v[204:207], v[84:87]
	v_mfma_f32_16x16x32_bf16 v[76:79], v[152:155], v[212:215], v[76:79]
	v_mfma_f32_16x16x32_bf16 v[68:71], v[160:163], v[212:215], v[68:71]
	v_mfma_f32_16x16x32_bf16 v[124:127], v[164:167], v[180:183], v[124:127]
	v_mfma_f32_16x16x32_bf16 v[120:123], v[172:175], v[180:183], v[120:123]
	v_mfma_f32_16x16x32_bf16 v[104:107], v[164:167], v[192:195], v[104:107]
	v_mfma_f32_16x16x32_bf16 v[96:99], v[172:175], v[192:195], v[96:99]
	v_mfma_f32_16x16x32_bf16 v[88:91], v[164:167], v[200:203], v[88:91]
	v_mfma_f32_16x16x32_bf16 v[80:83], v[172:175], v[200:203], v[80:83]
	v_mfma_f32_16x16x32_bf16 v[72:75], v[164:167], v[208:211], v[72:75]
	v_mfma_f32_16x16x32_bf16 v[64:67], v[172:175], v[208:211], v[64:67]
	v_mfma_f32_16x16x32_bf16 v[124:127], v[168:171], v[184:187], v[124:127]
	v_mfma_f32_16x16x32_bf16 v[120:123], v[176:179], v[184:187], v[120:123]
	v_mfma_f32_16x16x32_bf16 v[104:107], v[168:171], v[196:199], v[104:107]
	v_mfma_f32_16x16x32_bf16 v[96:99], v[176:179], v[196:199], v[96:99]
	v_mfma_f32_16x16x32_bf16 v[88:91], v[168:171], v[204:207], v[88:91]
	v_mfma_f32_16x16x32_bf16 v[80:83], v[176:179], v[204:207], v[80:83]
	v_mfma_f32_16x16x32_bf16 v[72:75], v[168:171], v[212:215], v[72:75]
	v_mfma_f32_16x16x32_bf16 v[64:67], v[176:179], v[212:215], v[64:67]
	s_barrier
; #define PG8_STAGE(bufoff, gbase, voff) do { _Pragma("unroll") for (int _i = 0; _i < 2; ++_i) \
;         __builtin_amdgcn_global_load_lds((const unsigned*)((const char*)(gbase) + (voff)[_i]), (PG8_LAS unsigned*)(lds + (bufoff) + ldsw + _i * 8192), 16, 0, 0); } while (0)
; #define PG8_LDA(dst, b, h) do { _Pragma("unroll") for (int m = 0; m < 4; ++m) _Pragma("unroll") for (int k = 0; k < 2; ++k) dst[m][k] = *(const PG8_LAS bf16x8*)(lds + PG8_SA(b, h) + aoff + m * 2048 + k * 1024); } while (0)
; #define PG8_MMA(ai, bj, At, Bt) do { __builtin_amdgcn_s_setprio(1); _Pragma("unroll") for (int m = 0; m < 4; ++m) _Pragma("unroll") for (int n = 0; n < 2; ++n) _Pragma("unroll") for (int k = 0; k < 2; ++k) \
;         acc[ai][bj][m][n] = __builtin_amdgcn_mfma_f32_16x16x32_bf16(Bt[n][k], At[m][k], acc[ai][bj][m][n], 0, 0, 0); __builtin_amdgcn_s_setprio(0); } while (0)
; #define PG8_WAIT_V(n) asm volatile("s_waitcnt vmcnt(" #n ")" ::: "memory")
; #define PG8_WAIT_L(n) asm volatile("s_waitcnt lgkmcnt(" #n ")" ::: "memory")
; #define PG8_BAR __builtin_amdgcn_s_barrier()
; #define PG8_SCHED __builtin_amdgcn_sched_barrier(0)
; template <class Epi, class Sched, bool ALIGN_EPI = false, bool SP2 = false>
; __device__ __forceinline__ void gemm_phase(PG8_LAS unsigned char* lds, const Gemm g, const Sched& S, const Epi& E) {
;     ...
;         for (int t = 0; t < nt; t += 2) {
;     ...
;             PG8_LDA(At, 1, 1); PG8_STAGE(PG8_SB(1, 0), b3, voffB); PG8_STAGE(PG8_SB(1, 1), b3 + hstepB, voffB); PG8_STAGE(PG8_SA(1, 0), a3, voffA);
;             PG8_WAIT_V(8); PG8_WAIT_L(0); PG8_BAR; PG8_MMA(1, 0, At, B0); PG8_MMA(1, 1, At, B1); PG8_BAR; PG8_SCHED;
	s_add_i32 s78, s76, s14
	v_lshl_add_u64 v[222:223], v[216:217], 0, s[34:35]
	s_mov_b32 m0, s78
	ds_read_b128 v[180:183], v143 offset:49152
	ds_read_b128 v[184:187], v143 offset:50176
	ds_read_b128 v[192:195], v143 offset:51200
	ds_read_b128 v[196:199], v143 offset:52224
	ds_read_b128 v[200:203], v143 offset:53248
	ds_read_b128 v[204:207], v143 offset:54272
	ds_read_b128 v[208:211], v143 offset:55296
	ds_read_b128 v[212:215], v143 offset:56320
	global_load_lds_dwordx4 v[222:223], off
	v_lshl_add_u64 v[222:223], v[216:217], 0, s[36:37]
	s_add_i32 m0, s78, 0x2000
	s_add_i32 s78, s77, s14
	global_load_lds_dwordx4 v[222:223], off
	v_lshl_add_u64 v[222:223], v[216:217], 0, s[38:39]
	s_mov_b32 m0, s78
	v_lshl_add_u64 v[216:217], v[216:217], 0, s[40:41]
	global_load_lds_dwordx4 v[222:223], off
	s_add_i32 m0, s78, 0x2000
	s_nop 0
	global_load_lds_dwordx4 v[216:217], off
	v_lshl_add_u64 v[216:217], v[220:221], 0, s[34:35]
	s_mov_b32 m0, s68
	s_nop 0
	global_load_lds_dwordx4 v[216:217], off
	v_lshl_add_u64 v[216:217], v[220:221], 0, s[36:37]
	s_mov_b32 m0, s69
	s_nop 0
	global_load_lds_dwordx4 v[216:217], off
	s_waitcnt vmcnt(8)
	s_waitcnt lgkmcnt(0)
	s_barrier
	s_waitcnt lgkmcnt(0)
	v_mfma_f32_16x16x32_bf16 v[60:63], v[148:151], v[180:183], v[60:63]
	v_mfma_f32_16x16x32_bf16 v[52:55], v[156:159], v[180:183], v[52:55]
	v_mfma_f32_16x16x32_bf16 v[44:47], v[148:151], v[192:195], v[44:47]
	v_mfma_f32_16x16x32_bf16 v[36:39], v[156:159], v[192:195], v[36:39]
	v_mfma_f32_16x16x32_bf16 v[28:31], v[148:151], v[200:203], v[28:31]
	v_mfma_f32_16x16x32_bf16 v[20:23], v[156:159], v[200:203], v[20:23]
	v_mfma_f32_16x16x32_bf16 v[12:15], v[148:151], v[208:211], v[12:15]
	v_mfma_f32_16x16x32_bf16 v[4:7], v[156:159], v[208:211], v[4:7]
	v_mfma_f32_16x16x32_bf16 v[60:63], v[152:155], v[184:187], v[60:63]
	v_mfma_f32_16x16x32_bf16 v[52:55], v[160:163], v[184:187], v[52:55]
	v_mfma_f32_16x16x32_bf16 v[44:47], v[152:155], v[196:199], v[44:47]
	v_mfma_f32_16x16x32_bf16 v[36:39], v[160:163], v[196:199], v[36:39]
	v_mfma_f32_16x16x32_bf16 v[28:31], v[152:155], v[204:207], v[28:31]
	v_mfma_f32_16x16x32_bf16 v[20:23], v[160:163], v[204:207], v[20:23]
	v_mfma_f32_16x16x32_bf16 v[12:15], v[152:155], v[212:215], v[12:15]
	v_mfma_f32_16x16x32_bf16 v[4:7], v[160:163], v[212:215], v[4:7]
	v_mfma_f32_16x16x32_bf16 v[56:59], v[164:167], v[180:183], v[56:59]
	v_mfma_f32_16x16x32_bf16 v[48:51], v[172:175], v[180:183], v[48:51]
	v_mfma_f32_16x16x32_bf16 v[40:43], v[164:167], v[192:195], v[40:43]
	v_mfma_f32_16x16x32_bf16 v[32:35], v[172:175], v[192:195], v[32:35]
	v_mfma_f32_16x16x32_bf16 v[24:27], v[164:167], v[200:203], v[24:27]
	v_mfma_f32_16x16x32_bf16 v[16:19], v[172:175], v[200:203], v[16:19]
	v_mfma_f32_16x16x32_bf16 v[8:11], v[164:167], v[208:211], v[8:11]
	v_mfma_f32_16x16x32_bf16 v[0:3], v[172:175], v[208:211], v[0:3]
	v_mfma_f32_16x16x32_bf16 v[56:59], v[168:171], v[184:187], v[56:59]
	v_mfma_f32_16x16x32_bf16 v[48:51], v[176:179], v[184:187], v[48:51]
	v_mfma_f32_16x16x32_bf16 v[40:43], v[168:171], v[196:199], v[40:43]
	v_mfma_f32_16x16x32_bf16 v[32:35], v[176:179], v[196:199], v[32:35]
	v_mfma_f32_16x16x32_bf16 v[24:27], v[168:171], v[204:207], v[24:27]
	v_mfma_f32_16x16x32_bf16 v[16:19], v[176:179], v[204:207], v[16:19]
	v_mfma_f32_16x16x32_bf16 v[8:11], v[168:171], v[212:215], v[8:11]
	v_mfma_f32_16x16x32_bf16 v[0:3], v[176:179], v[212:215], v[0:3]
	s_barrier
	s_add_i32 s82, s82, 2
	s_add_u32 s62, s62, 0x10000
	s_addc_u32 s63, s63, 0
	s_add_u32 s64, s64, 0x10000
	s_addc_u32 s65, s65, 0
	s_cmp_gt_u32 s82, 13

; #define PG8_STAGE(bufoff, gbase, voff) do { _Pragma("unroll") for (int _i = 0; _i < 2; ++_i) \
;         __builtin_amdgcn_global_load_lds((const unsigned*)((const char*)(gbase) + (voff)[_i]), (PG8_LAS unsigned*)(lds + (bufoff) + ldsw + _i * 8192), 16, 0, 0); } while (0)
; #define PG8_WAIT_V(n) asm volatile("s_waitcnt vmcnt(" #n ")" ::: "memory")
; #define PG8_BAR __builtin_amdgcn_s_barrier()
; template <class Epi, class Sched, bool ALIGN_EPI = false, bool SP2 = false>
; __device__ __forceinline__ void gemm_phase(PG8_LAS unsigned char* lds, const Gemm g, const Sched& S, const Epi& E) {
;     const int tid = threadIdx.x, wid = __builtin_amdgcn_readfirstlane(tid >> 6), lane = tid & 63, wr = wid >> 2, wc = wid & 3, fr = lane & 15, fq = lane >> 4;
;     const int K = g.K, nt = K / BK;
;     unsigned voffA[2], voffB[2];
; #pragma unroll
;     for (int i = 0; i < 2; ++i) { int R, C; stage_rc(tid * 16 + i * 8192, R, C); const int Rb = Epi::PERM ? ((R & ~31) + perm32(R & 31)) : R;
;         voffA[i] = g.a_pre ? (unsigned)(tid * 16 + i * 8192) : (unsigned)(R * g.lda + C) * 2u; voffB[i] = g.b_pre ? (unsigned)(tid * 16 + i * 8192) : (unsigned)(Rb * g.ldb + C) * 2u; }
;     const size_t kstep = g.b_pre ? (size_t)(2 * HTB) : (size_t)(BK * 2);
;     const size_t hstepA = (size_t)HALF * g.lda * 2, hstepB = (size_t)HALF * g.ldb * 2;
;     const size_t tstepA = g.pstepA, tstepB = g.b_pre ? (size_t)(g.K / BK) * (2 * HTB) : 2 * hstepB;
;     const size_t kstepA = g.kstepA;
;     const unsigned ldsw = (unsigned)wid * 1024u;
;     const int aoff = lds_byte(wr * 64 + fr, fq * 8), boff = lds_byte(wc * 32 + fr, fq * 8);
;     ...
;     if constexpr (SP2) {
;         PG8_STAGE(PG8_SB(0, 0), cB, voffB); PG8_STAGE(PG8_SB(0, 1), cB + hstepB, voffB); PG8_STAGE(PG8_SA(0, 0), cA, voffA); PG8_STAGE(PG8_SA(0, 1), cA + hstepA, voffA);
;         PG8_STAGE(PG8_SB(1, 0), cB + kstep, voffB); PG8_STAGE(PG8_SA(1, 0), cA + kstepA, voffA); PG8_STAGE(PG8_SB(1, 1), cB + hstepB + kstep, voffB);
;         if (wr == 1) PG8_BAR;
;         PG8_WAIT_V(8); PG8_BAR;
;         PG8_WAIT_V(6); PG8_BAR;
.LBB0_910:
	s_and_b32 s2, s0, 3
	v_lshl_or_b32 v219, s1, 6, v189
	s_lshl_b32 s1, s1, 13
	s_lshl_b32 s3, s2, 12
	v_bfe_u32 v0, v188, 4, 2
	s_cmpk_lt_u32 s4, 0x100
	v_lshlrev_b32_e32 v1, 3, v0
	v_lshlrev_b32_e32 v5, 2, v189
	s_cselect_b64 s[54:55], -1, 0
	s_and_b32 s77, s0, 2
	s_lshl_b32 s0, s4, 4
	v_lshlrev_b32_e32 v2, 6, v189
	v_and_b32_e32 v5, 32, v5
	v_lshl_or_b32 v220, s2, 5, v1
	v_lshlrev_b32_e32 v1, 4, v0
	s_and_b32 s0, s0, 0x400
	v_and_b32_e32 v3, 48, v188
	v_lshlrev_b32_e32 v6, 6, v188
	s_movk_i32 s5, 0x3c0
	s_or_b32 s2, s1, s0
	v_bitop3_b32 v1, v2, v5, v1 bitop3:0x36
	v_or_b32_e32 v4, v2, v3
	v_and_or_b32 v3, v6, s5, v3
	v_lshlrev_b32_e32 v6, 2, v188
	v_or_b32_e32 v2, s2, v1
	v_or_b32_e32 v1, s0, v1
	s_ashr_i32 s78, s26, 31
	s_ashr_i32 s80, s16, 31
	v_and_b32_e32 v6, 32, v6
	s_waitcnt vmcnt(8)
	s_barrier
	s_waitcnt vmcnt(0)
	v_or_b32_e32 v194, s1, v1
	s_cmp_lg_u64 s[20:21], 0
	v_bitop3_b32 v4, v4, s1, v5 bitop3:0xde
	v_bitop3_b32 v3, s3, v3, v6 bitop3:0xf6
	v_or_b32_e32 v192, 0x1800, v2
	v_mov_b32_e32 v193, v191
	v_ashrrev_i32_e32 v195, 31, v194
	v_or_b32_e32 v196, 0x800, v2
	v_mov_b32_e32 v197, v191
	v_or_b32_e32 v198, 0x1000, v2
	v_mov_b32_e32 v199, v191
	v_cmp_eq_u32_e64 s[2:3], 0, v0
	s_cselect_b64 s[56:57], -1, 0
	s_add_i32 s81, 0, 0x10000
	s_add_i32 s82, 0, 0x14000
	s_movk_i32 s58, 0xc000
	s_movk_i32 s60, 0xe000
	s_add_i32 s83, 0, 0x18000
	s_add_i32 s84, 0, 0x1c000
	v_mbcnt_lo_u32_b32 v0, -1, 0
	s_mov_b32 s79, s26
	v_lshl_add_u64 v[200:201], s[12:13], 0, v[192:193]
	v_lshl_add_u64 v[202:203], s[12:13], 0, v[194:195]
	v_lshl_add_u64 v[204:205], s[12:13], 0, v[196:197]
	v_lshl_add_u64 v[206:207], s[12:13], 0, v[198:199]
	v_mov_b64_e32 v[208:209], 0x200
	v_mov_b64_e32 v[210:211], 0x1ff
	v_add_u32_e32 v221, s81, v3
	v_add_u32_e32 v222, s82, v3
	v_add_u32_e32 v223, 0, v4
	s_mov_b32 s59, -1
	s_mov_b32 s61, -1
	v_add_u32_e32 v224, s83, v3
	v_add_u32_e32 v225, s84, v3
	v_mbcnt_hi_u32_b32 v226, -1, v0
	s_barrier
	s_branch .LBB0_913

; #define PG8_STAGE(bufoff, gbase, voff) do { _Pragma("unroll") for (int _i = 0; _i < 2; ++_i) \
;         __builtin_amdgcn_global_load_lds((const unsigned*)((const char*)(gbase) + (voff)[_i]), (PG8_LAS unsigned*)(lds + (bufoff) + ldsw + _i * 8192), 16, 0, 0); } while (0)
; #define PG8_LDA(dst, b, h) do { _Pragma("unroll") for (int m = 0; m < 4; ++m) _Pragma("unroll") for (int k = 0; k < 2; ++k) dst[m][k] = *(const PG8_LAS bf16x8*)(lds + PG8_SA(b, h) + aoff + m * 2048 + k * 1024); } while (0)
; #define PG8_LDB(dst, b, h) do { _Pragma("unroll") for (int n = 0; n < 2; ++n) _Pragma("unroll") for (int k = 0; k < 2; ++k) dst[n][k] = *(const PG8_LAS bf16x8*)(lds + PG8_SB(b, h) + boff + n * 2048 + k * 1024); } while (0)
; #define PG8_WAIT_V(n) asm volatile("s_waitcnt vmcnt(" #n ")" ::: "memory")
; #define PG8_WAIT_L(n) asm volatile("s_waitcnt lgkmcnt(" #n ")" ::: "memory")
; #define PG8_BAR __builtin_amdgcn_s_barrier()
; #define PG8_SCHED __builtin_amdgcn_sched_barrier(0)
; template <class Epi, class Sched, bool ALIGN_EPI = false, bool SP2 = false>
; __device__ __forceinline__ void gemm_phase(PG8_LAS unsigned char* lds, const Gemm g, const Sched& S, const Epi& E) {
;     ...
;         const bool has_next = S.next(ui + 1, nxt);
;         const char* nA = has_next ? (const char*)g.A + (size_t)nxt.pm * tstepA : cA; const char* nB = has_next ? (const char*)g.Bt + (size_t)nxt.pn * tstepB : cB;
;         for (int t = 0; t < nt; t += 2) {
;             const bool last = (t == nt - 2);
;             const char* a1 = cA + (size_t)(t + 1) * kstepA;
;             const char* a2 = last ? nA : cA + (size_t)(t + 2) * kstepA; const char* b2 = last ? nB : cB + (size_t)(t + 2) * kstep;
;             const char* a3 = a2 + kstepA; const char* b3 = b2 + kstep;
;             if (last && has_next) S.a_ready(nxt);
;             if constexpr (SP2) {
;             PG8_LDB(B0, 0, 0); PG8_LDB(B1, 0, 1); PG8_SCHED; PG8_LDA(At, 0, 0); PG8_STAGE(PG8_SA(1, 1), a1 + hstepA, voffA);
;             PG8_WAIT_V(8); PG8_WAIT_L(0); PG8_BAR; PG8_MMA(0, 0, At, B0); PG8_MMA(0, 1, At, B1); PG8_BAR; PG8_SCHED;
;             PG8_LDA(At, 0, 1); PG8_STAGE(PG8_SB(0, 0), b2, voffB); PG8_STAGE(PG8_SB(0, 1), b2 + hstepB, voffB); PG8_STAGE(PG8_SA(0, 0), a2, voffA);
;             PG8_WAIT_V(8); PG8_WAIT_L(0); PG8_BAR; PG8_MMA(1, 0, At, B0); PG8_MMA(1, 1, At, B1); PG8_BAR; PG8_SCHED;
.LBB0_923:
	s_add_u32 s6, s6, 0x10000
	s_addc_u32 s7, s7, 0
	s_add_u32 s64, s64, 0x10000
	s_addc_u32 s65, s65, 0
	s_mov_b32 s66, -2
	s_waitcnt lgkmcnt(0)
	ds_read_b128 v[84:87], v221
	ds_read_b128 v[92:95], v221 offset:1024
	ds_read_b128 v[104:107], v221 offset:2048
	ds_read_b128 v[116:119], v221 offset:3072
	ds_read_b128 v[128:131], v222
	ds_read_b128 v[140:143], v222 offset:1024
	ds_read_b128 v[152:155], v222 offset:2048
	ds_read_b128 v[156:159], v222 offset:3072
	s_cmp_eq_u32 s66, 40
	s_cselect_b32 s69, s1, s7
	s_cselect_b32 s68, s0, s6
	s_cselect_b32 s71, s63, s65
	s_cselect_b32 s70, s62, s64
	v_lshl_add_u64 v[216:217], s[6:7], 0, v[190:191]
	v_lshl_add_u64 v[228:229], v[216:217], 0, s[58:59]
	s_add_i32 m0, s15, 0xc000
	ds_read_b128 v[160:163], v223
	ds_read_b128 v[164:167], v223 offset:1024
	ds_read_b128 v[168:171], v223 offset:2048
	ds_read_b128 v[172:175], v223 offset:3072
	ds_read_b128 v[176:179], v223 offset:4096
	ds_read_b128 v[180:183], v223 offset:5120
	ds_read_b128 v[184:187], v223 offset:6144
	ds_read_b128 v[212:215], v223 offset:7168
	global_load_lds_dwordx4 v[228:229], off
	v_lshl_add_u64 v[216:217], v[216:217], 0, s[60:61]
	s_add_i32 m0, s15, 0xe000
	s_nop 0
	global_load_lds_dwordx4 v[216:217], off
	s_waitcnt vmcnt(56)
	s_waitcnt lgkmcnt(0)
	s_barrier
	s_waitcnt lgkmcnt(0)
	v_mfma_f32_16x16x32_bf16 v[148:151], v[84:87], v[160:163], 0
	v_mfma_f32_16x16x32_bf16 v[144:147], v[104:107], v[160:163], 0
	v_mfma_f32_16x16x32_bf16 v[124:127], v[84:87], v[168:171], 0
	v_mfma_f32_16x16x32_bf16 v[120:123], v[104:107], v[168:171], 0
	v_mfma_f32_16x16x32_bf16 v[100:103], v[84:87], v[176:179], 0
	v_mfma_f32_16x16x32_bf16 v[96:99], v[104:107], v[176:179], 0
	v_mfma_f32_16x16x32_bf16 v[76:79], v[84:87], v[184:187], 0
	v_mfma_f32_16x16x32_bf16 v[72:75], v[104:107], v[184:187], 0
	v_mfma_f32_16x16x32_bf16 v[148:151], v[92:95], v[164:167], v[148:151]
	v_mfma_f32_16x16x32_bf16 v[144:147], v[116:119], v[164:167], v[144:147]
	v_mfma_f32_16x16x32_bf16 v[124:127], v[92:95], v[172:175], v[124:127]
	v_mfma_f32_16x16x32_bf16 v[120:123], v[116:119], v[172:175], v[120:123]
	v_mfma_f32_16x16x32_bf16 v[100:103], v[92:95], v[180:183], v[100:103]
	v_mfma_f32_16x16x32_bf16 v[96:99], v[116:119], v[180:183], v[96:99]
	v_mfma_f32_16x16x32_bf16 v[76:79], v[92:95], v[212:215], v[76:79]
	v_mfma_f32_16x16x32_bf16 v[72:75], v[116:119], v[212:215], v[72:75]
	v_mfma_f32_16x16x32_bf16 v[136:139], v[128:131], v[160:163], 0
	v_mfma_f32_16x16x32_bf16 v[132:135], v[152:155], v[160:163], 0
	v_mfma_f32_16x16x32_bf16 v[112:115], v[128:131], v[168:171], 0
	v_mfma_f32_16x16x32_bf16 v[108:111], v[152:155], v[168:171], 0
	v_mfma_f32_16x16x32_bf16 v[88:91], v[128:131], v[176:179], 0
	v_mfma_f32_16x16x32_bf16 v[80:83], v[152:155], v[176:179], 0
	v_mfma_f32_16x16x32_bf16 v[68:71], v[128:131], v[184:187], 0
	v_mfma_f32_16x16x32_bf16 v[64:67], v[152:155], v[184:187], 0
	v_mfma_f32_16x16x32_bf16 v[136:139], v[140:143], v[164:167], v[136:139]
	v_mfma_f32_16x16x32_bf16 v[132:135], v[156:159], v[164:167], v[132:135]
	v_mfma_f32_16x16x32_bf16 v[112:115], v[140:143], v[172:175], v[112:115]
	v_mfma_f32_16x16x32_bf16 v[108:111], v[156:159], v[172:175], v[108:111]
	v_mfma_f32_16x16x32_bf16 v[88:91], v[140:143], v[180:183], v[88:91]
	v_mfma_f32_16x16x32_bf16 v[80:83], v[156:159], v[180:183], v[80:83]
	v_mfma_f32_16x16x32_bf16 v[68:71], v[140:143], v[212:215], v[68:71]
	v_mfma_f32_16x16x32_bf16 v[64:67], v[156:159], v[212:215], v[64:67]
	s_barrier
	s_add_i32 s33, s81, s14
	v_lshl_add_u64 v[216:217], s[70:71], 0, v[190:191]
	s_mov_b32 m0, s33
	ds_read_b128 v[160:163], v223 offset:16384
	ds_read_b128 v[164:167], v223 offset:17408
	ds_read_b128 v[168:171], v223 offset:18432
	ds_read_b128 v[172:175], v223 offset:19456
	ds_read_b128 v[176:179], v223 offset:20480
	ds_read_b128 v[180:183], v223 offset:21504
	ds_read_b128 v[184:187], v223 offset:22528
	ds_read_b128 v[212:215], v223 offset:23552
	global_load_lds_dwordx4 v[216:217], off
	v_lshl_add_u64 v[228:229], v[216:217], 0, s[8:9]
	s_add_i32 m0, s33, 0x2000
	s_add_i32 s33, s82, s14
	global_load_lds_dwordx4 v[228:229], off
	v_lshl_add_u64 v[228:229], v[216:217], 0, s[10:11]
	s_mov_b32 m0, s33
	s_nop 0
	global_load_lds_dwordx4 v[228:229], off
	v_lshl_add_u64 v[228:229], v[216:217], 0, s[40:41]
	s_add_i32 m0, s33, 0x2000
	s_nop 0
	global_load_lds_dwordx4 v[228:229], off
	v_lshl_add_u64 v[228:229], s[68:69], 0, v[190:191]
	s_mov_b32 m0, s15
	v_lshl_add_u64 v[230:231], v[228:229], 0, s[8:9]
	global_load_lds_dwordx4 v[228:229], off
	s_mov_b32 m0, s17
	s_nop 0
	global_load_lds_dwordx4 v[230:231], off
	s_waitcnt vmcnt(56)
	s_waitcnt lgkmcnt(0)
	s_barrier
; #define PG8_STAGE(bufoff, gbase, voff) do { _Pragma("unroll") for (int _i = 0; _i < 2; ++_i) \
;         __builtin_amdgcn_global_load_lds((const unsigned*)((const char*)(gbase) + (voff)[_i]), (PG8_LAS unsigned*)(lds + (bufoff) + ldsw + _i * 8192), 16, 0, 0); } while (0)
; #define PG8_LDA(dst, b, h) do { _Pragma("unroll") for (int m = 0; m < 4; ++m) _Pragma("unroll") for (int k = 0; k < 2; ++k) dst[m][k] = *(const PG8_LAS bf16x8*)(lds + PG8_SA(b, h) + aoff + m * 2048 + k * 1024); } while (0)
; #define PG8_LDB(dst, b, h) do { _Pragma("unroll") for (int n = 0; n < 2; ++n) _Pragma("unroll") for (int k = 0; k < 2; ++k) dst[n][k] = *(const PG8_LAS bf16x8*)(lds + PG8_SB(b, h) + boff + n * 2048 + k * 1024); } while (0)
; #define PG8_MMA(ai, bj, At, Bt) do { __builtin_amdgcn_s_setprio(1); _Pragma("unroll") for (int m = 0; m < 4; ++m) _Pragma("unroll") for (int n = 0; n < 2; ++n) _Pragma("unroll") for (int k = 0; k < 2; ++k) \
;         acc[ai][bj][m][n] = __builtin_amdgcn_mfma_f32_16x16x32_bf16(Bt[n][k], At[m][k], acc[ai][bj][m][n], 0, 0, 0); __builtin_amdgcn_s_setprio(0); } while (0)
; #define PG8_WAIT_V(n) asm volatile("s_waitcnt vmcnt(" #n ")" ::: "memory")
; #define PG8_WAIT_L(n) asm volatile("s_waitcnt lgkmcnt(" #n ")" ::: "memory")
; #define PG8_BAR __builtin_amdgcn_s_barrier()
; #define PG8_SCHED __builtin_amdgcn_sched_barrier(0)
; template <class Epi, class Sched, bool ALIGN_EPI = false, bool SP2 = false>
; __device__ __forceinline__ void gemm_phase(PG8_LAS unsigned char* lds, const Gemm g, const Sched& S, const Epi& E) {
;     ...
;             PG8_WAIT_V(8); PG8_WAIT_L(0); PG8_BAR; PG8_MMA(1, 0, At, B0); PG8_MMA(1, 1, At, B1); PG8_BAR; PG8_SCHED;
;             PG8_LDB(B0, 1, 0); PG8_LDB(B1, 1, 1); PG8_SCHED; PG8_LDA(At, 1, 0); PG8_STAGE(PG8_SA(0, 1), a2 + hstepA, voffA);
;             PG8_WAIT_V(8); PG8_WAIT_L(0); PG8_BAR; PG8_MMA(0, 0, At, B0); PG8_MMA(0, 1, At, B1); PG8_BAR; PG8_SCHED;
	s_waitcnt lgkmcnt(0)
	v_mfma_f32_16x16x32_bf16 v[60:63], v[84:87], v[160:163], 0
	v_mfma_f32_16x16x32_bf16 v[56:59], v[104:107], v[160:163], 0
	v_mfma_f32_16x16x32_bf16 v[44:47], v[84:87], v[168:171], 0
	v_mfma_f32_16x16x32_bf16 v[40:43], v[104:107], v[168:171], 0
	v_mfma_f32_16x16x32_bf16 v[28:31], v[84:87], v[176:179], 0
	v_mfma_f32_16x16x32_bf16 v[24:27], v[104:107], v[176:179], 0
	v_mfma_f32_16x16x32_bf16 v[12:15], v[84:87], v[184:187], 0
	v_mfma_f32_16x16x32_bf16 v[8:11], v[104:107], v[184:187], 0
	v_mfma_f32_16x16x32_bf16 v[60:63], v[92:95], v[164:167], v[60:63]
	v_mfma_f32_16x16x32_bf16 v[56:59], v[116:119], v[164:167], v[56:59]
	v_mfma_f32_16x16x32_bf16 v[44:47], v[92:95], v[172:175], v[44:47]
	v_mfma_f32_16x16x32_bf16 v[40:43], v[116:119], v[172:175], v[40:43]
	v_mfma_f32_16x16x32_bf16 v[28:31], v[92:95], v[180:183], v[28:31]
	v_mfma_f32_16x16x32_bf16 v[24:27], v[116:119], v[180:183], v[24:27]
	v_mfma_f32_16x16x32_bf16 v[12:15], v[92:95], v[212:215], v[12:15]
	v_mfma_f32_16x16x32_bf16 v[8:11], v[116:119], v[212:215], v[8:11]
	v_mfma_f32_16x16x32_bf16 v[52:55], v[128:131], v[160:163], 0
	v_mfma_f32_16x16x32_bf16 v[48:51], v[152:155], v[160:163], 0
	v_mfma_f32_16x16x32_bf16 v[36:39], v[128:131], v[168:171], 0
	v_mfma_f32_16x16x32_bf16 v[32:35], v[152:155], v[168:171], 0
	v_mfma_f32_16x16x32_bf16 v[20:23], v[128:131], v[176:179], 0
	v_mfma_f32_16x16x32_bf16 v[16:19], v[152:155], v[176:179], 0
	v_mfma_f32_16x16x32_bf16 v[4:7], v[128:131], v[184:187], 0
	v_mfma_f32_16x16x32_bf16 v[0:3], v[152:155], v[184:187], 0
	v_mfma_f32_16x16x32_bf16 v[52:55], v[140:143], v[164:167], v[52:55]
	v_mfma_f32_16x16x32_bf16 v[48:51], v[156:159], v[164:167], v[48:51]
	v_mfma_f32_16x16x32_bf16 v[36:39], v[140:143], v[172:175], v[36:39]
	v_mfma_f32_16x16x32_bf16 v[32:35], v[156:159], v[172:175], v[32:35]
	v_mfma_f32_16x16x32_bf16 v[20:23], v[140:143], v[180:183], v[20:23]
	v_mfma_f32_16x16x32_bf16 v[16:19], v[156:159], v[180:183], v[16:19]
	v_mfma_f32_16x16x32_bf16 v[4:7], v[140:143], v[212:215], v[4:7]
	v_mfma_f32_16x16x32_bf16 v[0:3], v[156:159], v[212:215], v[0:3]
	s_barrier
	ds_read_b128 v[84:87], v224
	ds_read_b128 v[92:95], v224 offset:1024
	ds_read_b128 v[104:107], v224 offset:2048
	ds_read_b128 v[116:119], v224 offset:3072
	ds_read_b128 v[128:131], v225
	ds_read_b128 v[140:143], v225 offset:1024
	ds_read_b128 v[152:155], v225 offset:2048
	ds_read_b128 v[156:159], v225 offset:3072
	s_mov_b32 m0, s18
	v_lshl_add_u64 v[230:231], v[228:229], 0, s[10:11]
	ds_read_b128 v[160:163], v223 offset:32768
	ds_read_b128 v[164:167], v223 offset:33792
	ds_read_b128 v[168:171], v223 offset:34816
	ds_read_b128 v[172:175], v223 offset:35840
	ds_read_b128 v[176:179], v223 offset:36864
	ds_read_b128 v[180:183], v223 offset:37888
	ds_read_b128 v[184:187], v223 offset:38912
	ds_read_b128 v[212:215], v223 offset:39936
	global_load_lds_dwordx4 v[230:231], off
	v_lshl_add_u64 v[230:231], v[228:229], 0, s[40:41]
	s_mov_b32 m0, s19
	s_nop 0
	global_load_lds_dwordx4 v[230:231], off
	s_waitcnt vmcnt(8)
	s_waitcnt lgkmcnt(0)
	s_barrier
	s_waitcnt lgkmcnt(0)
	v_mfma_f32_16x16x32_bf16 v[148:151], v[84:87], v[160:163], v[148:151]
	v_mfma_f32_16x16x32_bf16 v[144:147], v[104:107], v[160:163], v[144:147]
	v_mfma_f32_16x16x32_bf16 v[124:127], v[84:87], v[168:171], v[124:127]
	v_mfma_f32_16x16x32_bf16 v[120:123], v[104:107], v[168:171], v[120:123]
	v_mfma_f32_16x16x32_bf16 v[100:103], v[84:87], v[176:179], v[100:103]
	v_mfma_f32_16x16x32_bf16 v[96:99], v[104:107], v[176:179], v[96:99]
	v_mfma_f32_16x16x32_bf16 v[76:79], v[84:87], v[184:187], v[76:79]
	v_mfma_f32_16x16x32_bf16 v[72:75], v[104:107], v[184:187], v[72:75]
	v_mfma_f32_16x16x32_bf16 v[148:151], v[92:95], v[164:167], v[148:151]
	v_mfma_f32_16x16x32_bf16 v[144:147], v[116:119], v[164:167], v[144:147]
	v_mfma_f32_16x16x32_bf16 v[124:127], v[92:95], v[172:175], v[124:127]
	v_mfma_f32_16x16x32_bf16 v[120:123], v[116:119], v[172:175], v[120:123]
	v_mfma_f32_16x16x32_bf16 v[100:103], v[92:95], v[180:183], v[100:103]
	v_mfma_f32_16x16x32_bf16 v[96:99], v[116:119], v[180:183], v[96:99]
	v_mfma_f32_16x16x32_bf16 v[76:79], v[92:95], v[212:215], v[76:79]
	v_mfma_f32_16x16x32_bf16 v[72:75], v[116:119], v[212:215], v[72:75]
	v_mfma_f32_16x16x32_bf16 v[136:139], v[128:131], v[160:163], v[136:139]
	v_mfma_f32_16x16x32_bf16 v[132:135], v[152:155], v[160:163], v[132:135]
	v_mfma_f32_16x16x32_bf16 v[112:115], v[128:131], v[168:171], v[112:115]
	v_mfma_f32_16x16x32_bf16 v[108:111], v[152:155], v[168:171], v[108:111]
	v_mfma_f32_16x16x32_bf16 v[88:91], v[128:131], v[176:179], v[88:91]
	v_mfma_f32_16x16x32_bf16 v[80:83], v[152:155], v[176:179], v[80:83]
	v_mfma_f32_16x16x32_bf16 v[68:71], v[128:131], v[184:187], v[68:71]
	v_mfma_f32_16x16x32_bf16 v[64:67], v[152:155], v[184:187], v[64:67]
	v_mfma_f32_16x16x32_bf16 v[136:139], v[140:143], v[164:167], v[136:139]
	v_mfma_f32_16x16x32_bf16 v[132:135], v[156:159], v[164:167], v[132:135]
	v_mfma_f32_16x16x32_bf16 v[112:115], v[140:143], v[172:175], v[112:115]
	v_mfma_f32_16x16x32_bf16 v[108:111], v[156:159], v[172:175], v[108:111]
	v_mfma_f32_16x16x32_bf16 v[88:91], v[140:143], v[180:183], v[88:91]
	v_mfma_f32_16x16x32_bf16 v[80:83], v[156:159], v[180:183], v[80:83]
	v_mfma_f32_16x16x32_bf16 v[68:71], v[140:143], v[212:215], v[68:71]
	v_mfma_f32_16x16x32_bf16 v[64:67], v[156:159], v[212:215], v[64:67]
	s_barrier
; #define PG8_STAGE(bufoff, gbase, voff) do { _Pragma("unroll") for (int _i = 0; _i < 2; ++_i) \
;         __builtin_amdgcn_global_load_lds((const unsigned*)((const char*)(gbase) + (voff)[_i]), (PG8_LAS unsigned*)(lds + (bufoff) + ldsw + _i * 8192), 16, 0, 0); } while (0)
; #define PG8_LDA(dst, b, h) do { _Pragma("unroll") for (int m = 0; m < 4; ++m) _Pragma("unroll") for (int k = 0; k < 2; ++k) dst[m][k] = *(const PG8_LAS bf16x8*)(lds + PG8_SA(b, h) + aoff + m * 2048 + k * 1024); } while (0)
; #define PG8_MMA(ai, bj, At, Bt) do { __builtin_amdgcn_s_setprio(1); _Pragma("unroll") for (int m = 0; m < 4; ++m) _Pragma("unroll") for (int n = 0; n < 2; ++n) _Pragma("unroll") for (int k = 0; k < 2; ++k) \
;         acc[ai][bj][m][n] = __builtin_amdgcn_mfma_f32_16x16x32_bf16(Bt[n][k], At[m][k], acc[ai][bj][m][n], 0, 0, 0); __builtin_amdgcn_s_setprio(0); } while (0)
; #define PG8_WAIT_V(n) asm volatile("s_waitcnt vmcnt(" #n ")" ::: "memory")
; #define PG8_WAIT_L(n) asm volatile("s_waitcnt lgkmcnt(" #n ")" ::: "memory")
; #define PG8_BAR __builtin_amdgcn_s_barrier()
; #define PG8_SCHED __builtin_amdgcn_sched_barrier(0)
; template <class Epi, class Sched, bool ALIGN_EPI = false, bool SP2 = false>
; __device__ __forceinline__ void gemm_phase(PG8_LAS unsigned char* lds, const Gemm g, const Sched& S, const Epi& E) {
;     ...
;         for (int t = 0; t < nt; t += 2) {
;     ...
;             PG8_LDA(At, 1, 1); PG8_STAGE(PG8_SB(1, 0), b3, voffB); PG8_STAGE(PG8_SB(1, 1), b3 + hstepB, voffB); PG8_STAGE(PG8_SA(1, 0), a3, voffA);
;             PG8_WAIT_V(8); PG8_WAIT_L(0); PG8_BAR; PG8_MMA(1, 0, At, B0); PG8_MMA(1, 1, At, B1); PG8_BAR; PG8_SCHED;
	s_add_i32 s33, s83, s14
	v_lshl_add_u64 v[230:231], v[216:217], 0, s[42:43]
	s_mov_b32 m0, s33
	ds_read_b128 v[160:163], v223 offset:49152
	ds_read_b128 v[164:167], v223 offset:50176
	ds_read_b128 v[168:171], v223 offset:51200
	ds_read_b128 v[172:175], v223 offset:52224
	ds_read_b128 v[176:179], v223 offset:53248
	ds_read_b128 v[180:183], v223 offset:54272
	ds_read_b128 v[184:187], v223 offset:55296
	ds_read_b128 v[212:215], v223 offset:56320
	global_load_lds_dwordx4 v[230:231], off
	v_lshl_add_u64 v[230:231], v[216:217], 0, s[44:45]
	s_add_i32 m0, s33, 0x2000
	s_add_i32 s33, s84, s14
	global_load_lds_dwordx4 v[230:231], off
	v_lshl_add_u64 v[230:231], v[216:217], 0, s[46:47]
	s_mov_b32 m0, s33
	v_lshl_add_u64 v[216:217], v[216:217], 0, s[48:49]
	global_load_lds_dwordx4 v[230:231], off
	s_add_i32 m0, s33, 0x2000
	s_nop 0
	global_load_lds_dwordx4 v[216:217], off
	v_lshl_add_u64 v[216:217], v[228:229], 0, s[42:43]
	s_mov_b32 m0, s74
	s_nop 0
	global_load_lds_dwordx4 v[216:217], off
	v_lshl_add_u64 v[216:217], v[228:229], 0, s[44:45]
	s_mov_b32 m0, s75
	s_nop 0
	global_load_lds_dwordx4 v[216:217], off
	s_waitcnt vmcnt(8)
	s_waitcnt lgkmcnt(0)
	s_barrier
	s_waitcnt lgkmcnt(0)
	v_mfma_f32_16x16x32_bf16 v[60:63], v[84:87], v[160:163], v[60:63]
	v_mfma_f32_16x16x32_bf16 v[56:59], v[104:107], v[160:163], v[56:59]
	v_mfma_f32_16x16x32_bf16 v[44:47], v[84:87], v[168:171], v[44:47]
	v_mfma_f32_16x16x32_bf16 v[40:43], v[104:107], v[168:171], v[40:43]
	v_mfma_f32_16x16x32_bf16 v[28:31], v[84:87], v[176:179], v[28:31]
	v_mfma_f32_16x16x32_bf16 v[24:27], v[104:107], v[176:179], v[24:27]
	v_mfma_f32_16x16x32_bf16 v[12:15], v[84:87], v[184:187], v[12:15]
	v_mfma_f32_16x16x32_bf16 v[8:11], v[104:107], v[184:187], v[8:11]
	v_mfma_f32_16x16x32_bf16 v[60:63], v[92:95], v[164:167], v[60:63]
	v_mfma_f32_16x16x32_bf16 v[56:59], v[116:119], v[164:167], v[56:59]
	v_mfma_f32_16x16x32_bf16 v[44:47], v[92:95], v[172:175], v[44:47]
	v_mfma_f32_16x16x32_bf16 v[40:43], v[116:119], v[172:175], v[40:43]
	v_mfma_f32_16x16x32_bf16 v[28:31], v[92:95], v[180:183], v[28:31]
	v_mfma_f32_16x16x32_bf16 v[24:27], v[116:119], v[180:183], v[24:27]
	v_mfma_f32_16x16x32_bf16 v[12:15], v[92:95], v[212:215], v[12:15]
	v_mfma_f32_16x16x32_bf16 v[8:11], v[116:119], v[212:215], v[8:11]
	v_mfma_f32_16x16x32_bf16 v[52:55], v[128:131], v[160:163], v[52:55]
	v_mfma_f32_16x16x32_bf16 v[48:51], v[152:155], v[160:163], v[48:51]
	v_mfma_f32_16x16x32_bf16 v[36:39], v[128:131], v[168:171], v[36:39]
	v_mfma_f32_16x16x32_bf16 v[32:35], v[152:155], v[168:171], v[32:35]
	v_mfma_f32_16x16x32_bf16 v[20:23], v[128:131], v[176:179], v[20:23]
	v_mfma_f32_16x16x32_bf16 v[16:19], v[152:155], v[176:179], v[16:19]
	v_mfma_f32_16x16x32_bf16 v[4:7], v[128:131], v[184:187], v[4:7]
	v_mfma_f32_16x16x32_bf16 v[0:3], v[152:155], v[184:187], v[0:3]
	v_mfma_f32_16x16x32_bf16 v[52:55], v[140:143], v[164:167], v[52:55]
	v_mfma_f32_16x16x32_bf16 v[48:51], v[156:159], v[164:167], v[48:51]
	v_mfma_f32_16x16x32_bf16 v[36:39], v[140:143], v[172:175], v[36:39]
	v_mfma_f32_16x16x32_bf16 v[32:35], v[156:159], v[172:175], v[32:35]
	v_mfma_f32_16x16x32_bf16 v[20:23], v[140:143], v[180:183], v[20:23]
	v_mfma_f32_16x16x32_bf16 v[16:19], v[156:159], v[180:183], v[16:19]
	v_mfma_f32_16x16x32_bf16 v[4:7], v[140:143], v[212:215], v[4:7]
	v_mfma_f32_16x16x32_bf16 v[0:3], v[156:159], v[212:215], v[0:3]
	s_barrier
	s_add_i32 s66, s66, 2
	s_add_u32 s6, s6, 0x10000
	s_addc_u32 s7, s7, 0
	s_add_u32 s64, s64, 0x10000
	s_addc_u32 s65, s65, 0
	s_cmp_gt_u32 s66, 41

; #define PG8_STAGE(bufoff, gbase, voff) do { _Pragma("unroll") for (int _i = 0; _i < 2; ++_i) \
;         __builtin_amdgcn_global_load_lds((const unsigned*)((const char*)(gbase) + (voff)[_i]), (PG8_LAS unsigned*)(lds + (bufoff) + ldsw + _i * 8192), 16, 0, 0); } while (0)
; #define PG8_WAIT_V(n) asm volatile("s_waitcnt vmcnt(" #n ")" ::: "memory")
; #define PG8_BAR __builtin_amdgcn_s_barrier()
; template <class Epi, class Sched, bool ALIGN_EPI = false, bool SP2 = false>
; __device__ __forceinline__ void gemm_phase(PG8_LAS unsigned char* lds, const Gemm g, const Sched& S, const Epi& E) {
;     const int tid = threadIdx.x, wid = __builtin_amdgcn_readfirstlane(tid >> 6), lane = tid & 63, wr = wid >> 2, wc = wid & 3, fr = lane & 15, fq = lane >> 4;
;     const int K = g.K, nt = K / BK;
;     unsigned voffA[2], voffB[2];
; #pragma unroll
;     for (int i = 0; i < 2; ++i) { int R, C; stage_rc(tid * 16 + i * 8192, R, C); const int Rb = Epi::PERM ? ((R & ~31) + perm32(R & 31)) : R;
;         voffA[i] = g.a_pre ? (unsigned)(tid * 16 + i * 8192) : (unsigned)(R * g.lda + C) * 2u; voffB[i] = g.b_pre ? (unsigned)(tid * 16 + i * 8192) : (unsigned)(Rb * g.ldb + C) * 2u; }
;     const size_t kstep = g.b_pre ? (size_t)(2 * HTB) : (size_t)(BK * 2);
;     const size_t hstepA = (size_t)HALF * g.lda * 2, hstepB = (size_t)HALF * g.ldb * 2;
;     const size_t tstepA = g.pstepA, tstepB = g.b_pre ? (size_t)(g.K / BK) * (2 * HTB) : 2 * hstepB;
;     const size_t kstepA = g.kstepA;
;     const unsigned ldsw = (unsigned)wid * 1024u;
;     const int aoff = lds_byte(wr * 64 + fr, fq * 8), boff = lds_byte(wc * 32 + fr, fq * 8);
;     ...
;     if constexpr (SP2) {
;         PG8_STAGE(PG8_SB(0, 0), cB, voffB); PG8_STAGE(PG8_SB(0, 1), cB + hstepB, voffB); PG8_STAGE(PG8_SA(0, 0), cA, voffA); PG8_STAGE(PG8_SA(0, 1), cA + hstepA, voffA);
;         PG8_STAGE(PG8_SB(1, 0), cB + kstep, voffB); PG8_STAGE(PG8_SA(1, 0), cA + kstepA, voffA); PG8_STAGE(PG8_SB(1, 1), cB + hstepB + kstep, voffB);
;         if (wr == 1) PG8_BAR;
;         PG8_WAIT_V(8); PG8_BAR;
;         PG8_WAIT_V(6); PG8_BAR;
.LBB0_990:
	v_lshl_or_b32 v200, s1, 6, v189
	s_add_u32 s82, s22, 0x84000
	v_lshlrev_b32_e32 v2, 6, v189
	v_and_b32_e32 v1, 48, v188
	v_lshlrev_b32_e32 v9, 2, v200
	s_addc_u32 s83, s23, 0
	s_and_b32 s33, s0, 3
	s_lshl_b32 s1, s1, 13
	v_or_b32_e32 v3, v2, v1
	v_and_b32_e32 v4, 32, v9
	v_bfe_u32 v8, v188, 4, 2
	v_bitop3_b32 v10, v3, s1, v4 bitop3:0xde
	s_lshl_b32 s2, s33, 12
	v_lshlrev_b32_e32 v3, 6, v188
	s_movk_i32 s3, 0x3c0
	v_lshlrev_b32_e32 v0, 3, v8
	v_and_or_b32 v1, v3, s3, v1
	v_lshlrev_b32_e32 v3, 2, v188
	s_cmpk_lt_u32 s4, 0x100
	v_and_b32_e32 v3, 32, v3
	v_lshl_or_b32 v201, s33, 5, v0
	s_cselect_b64 s[60:61], -1, 0
	s_and_b32 s84, s0, 2
	s_lshl_b32 s0, s4, 4
	v_lshlrev_b32_e32 v0, 2, v189
	v_bitop3_b32 v11, s2, v1, v3 bitop3:0xf6
	v_lshlrev_b32_e32 v3, 4, v8
	s_and_b32 s0, s0, 0x400
	v_and_b32_e32 v0, 32, v0
	s_or_b32 s2, s1, s0
	v_bitop3_b32 v0, v2, v0, v3 bitop3:0x36
	v_bitop3_b32 v2, v2, v4, v3 bitop3:0x36
	v_or_b32_e32 v6, s2, v0
	v_or_b32_e32 v2, s0, v2
	v_lshrrev_b32_e32 v12, 1, v188
	v_and_b32_e32 v13, 31, v188
	s_movk_i32 s0, 0x1e0
	v_or_b32_e32 v0, 0x1800, v6
	v_mov_b32_e32 v1, v191
	v_and_or_b32 v202, v12, s0, v13
	s_lshl_b32 s0, s33, 2
	s_waitcnt vmcnt(8)
	s_barrier
	s_waitcnt vmcnt(0)
	v_or_b32_e32 v2, s1, v2
	v_lshlrev_b32_e32 v12, 4, v202
	v_lshl_add_u64 v[184:185], s[12:13], 0, v[0:1]
	s_add_i32 s0, s0, 0
	v_mbcnt_lo_u32_b32 v0, -1, 0
	v_ashrrev_i32_e32 v3, 31, v2
	v_or_b32_e32 v4, 0x800, v6
	v_mov_b32_e32 v5, v191
	v_or_b32_e32 v6, 0x1000, v6
	v_mov_b32_e32 v7, v191
	v_cmp_eq_u32_e64 s[2:3], 0, v8
	v_lshlrev_b32_e32 v8, 4, v200
	v_or_b32_e32 v203, 16, v200
	v_or_b32_e32 v204, 32, v200
	v_or_b32_e32 v205, 48, v200
	v_add_u32_e32 v206, 0x80, v200
	v_add_u32_e32 v207, 0x90, v200
	v_add_u32_e32 v208, 0xa0, v200
	v_add_u32_e32 v209, 0xb0, v200
	s_add_i32 s0, s0, 0x20100
	s_add_i32 s1, 0, 0x21100
	s_add_i32 s86, 0, 0x10000
	s_add_i32 s87, 0, 0x14000
	s_movk_i32 s62, 0xc000
	s_movk_i32 s64, 0xe000
	s_add_i32 s88, 0, 0x18000
	s_add_i32 s89, 0, 0x1c000
	v_mbcnt_hi_u32_b32 v225, -1, v0
	v_add_u32_e32 v0, 0, v12
	v_cmp_gt_u32_e64 s[4:5], 32, v218
	v_cmp_lt_u32_e64 s[6:7], 31, v218
	v_cmp_eq_u32_e64 s[8:9], 0, v218
	v_cmp_gt_u32_e64 s[10:11], 64, v188
	s_ashr_i32 s85, s16, 31
	v_lshl_add_u64 v[186:187], s[12:13], 0, v[2:3]
	v_lshl_add_u64 v[188:189], s[12:13], 0, v[4:5]
	v_lshl_add_u64 v[192:193], s[12:13], 0, v[6:7]
	v_lshl_add_u32 v210, v202, 2, s1
	v_add_u32_e32 v211, s1, v9
	v_lshl_add_u32 v212, v203, 2, s1
	v_lshl_add_u32 v213, v204, 2, s1
	v_lshl_add_u32 v214, v205, 2, s1
	v_lshl_add_u32 v215, v206, 2, s1
	v_lshl_add_u32 v216, v207, 2, s1
	v_lshl_add_u32 v217, v208, 2, s1
	v_lshl_add_u32 v219, v209, 2, s1
	v_mov_b64_e32 v[194:195], 0x200
	v_mov_b64_e32 v[196:197], 0x1ff
	v_add_u32_e32 v220, s86, v11
	v_add_u32_e32 v221, s87, v11
	v_add_u32_e32 v222, 0, v10
	s_mov_b32 s63, -1
	s_mov_b32 s65, -1
	v_add_u32_e32 v223, s88, v11
	v_add_u32_e32 v224, s89, v11
	v_add_u32_e32 v226, 0x20100, v0
	s_add_i32 s90, 0, 0x21500
	v_mov_b32_e32 v227, 0x358637bd
	v_add_u32_e32 v228, s0, v8
	v_mov_b64_e32 v[198:199], 0x1e8481
	v_mov_b32_e32 v229, 0x7fc00000
	s_mov_b32 s58, s59
	s_barrier
	s_branch .LBB0_993

; #define PG8_STAGE(bufoff, gbase, voff) do { _Pragma("unroll") for (int _i = 0; _i < 2; ++_i) \
;         __builtin_amdgcn_global_load_lds((const unsigned*)((const char*)(gbase) + (voff)[_i]), (PG8_LAS unsigned*)(lds + (bufoff) + ldsw + _i * 8192), 16, 0, 0); } while (0)
; #define PG8_LDA(dst, b, h) do { _Pragma("unroll") for (int m = 0; m < 4; ++m) _Pragma("unroll") for (int k = 0; k < 2; ++k) dst[m][k] = *(const PG8_LAS bf16x8*)(lds + PG8_SA(b, h) + aoff + m * 2048 + k * 1024); } while (0)
; #define PG8_LDB(dst, b, h) do { _Pragma("unroll") for (int n = 0; n < 2; ++n) _Pragma("unroll") for (int k = 0; k < 2; ++k) dst[n][k] = *(const PG8_LAS bf16x8*)(lds + PG8_SB(b, h) + boff + n * 2048 + k * 1024); } while (0)
; #define PG8_MMA(ai, bj, At, Bt) do { __builtin_amdgcn_s_setprio(1); _Pragma("unroll") for (int m = 0; m < 4; ++m) _Pragma("unroll") for (int n = 0; n < 2; ++n) _Pragma("unroll") for (int k = 0; k < 2; ++k) \
;         acc[ai][bj][m][n] = __builtin_amdgcn_mfma_f32_16x16x32_bf16(Bt[n][k], At[m][k], acc[ai][bj][m][n], 0, 0, 0); __builtin_amdgcn_s_setprio(0); } while (0)
; #define PG8_WAIT_V(n) asm volatile("s_waitcnt vmcnt(" #n ")" ::: "memory")
; #define PG8_BAR __builtin_amdgcn_s_barrier()
; template <class Epi, class Sched, bool ALIGN_EPI = false, bool SP2 = false>
; __device__ __forceinline__ void gemm_phase(PG8_LAS unsigned char* lds, const Gemm g, const Sched& S, const Epi& E) {
;     ...
;         for (int t = 0; t < nt; t += 2) {
;             const bool last = (t == nt - 2);
;             const char* a1 = cA + (size_t)(t + 1) * kstepA;
;             const char* a2 = last ? nA : cA + (size_t)(t + 2) * kstepA; const char* b2 = last ? nB : cB + (size_t)(t + 2) * kstep;
;             const char* a3 = a2 + kstepA; const char* b3 = b2 + kstep;
;             if (last && has_next) S.a_ready(nxt);
;             if constexpr (SP2) {
;             PG8_LDB(B0, 0, 0); PG8_LDB(B1, 0, 1); PG8_SCHED; PG8_LDA(At, 0, 0); PG8_STAGE(PG8_SA(1, 1), a1 + hstepA, voffA);
;             PG8_WAIT_V(8); PG8_WAIT_L(0); PG8_BAR; PG8_MMA(0, 0, At, B0); PG8_MMA(0, 1, At, B1); PG8_BAR; PG8_SCHED;
;             PG8_LDA(At, 0, 1); PG8_STAGE(PG8_SB(0, 0), b2, voffB); PG8_STAGE(PG8_SB(0, 1), b2 + hstepB, voffB); PG8_STAGE(PG8_SA(0, 0), a2, voffA);
;             PG8_WAIT_V(8); PG8_WAIT_L(0); PG8_BAR; PG8_MMA(1, 0, At, B0); PG8_MMA(1, 1, At, B1); PG8_BAR; PG8_SCHED;
.LBB0_1003:
	s_add_u32 s70, s70, 0x10000
	s_addc_u32 s71, s71, 0
	s_add_u32 s69, s72, 0x10000
	s_addc_u32 s72, s73, 0
	s_mov_b32 s73, -2
	ds_read_b128 v[128:131], v220
	ds_read_b128 v[132:135], v220 offset:1024
	ds_read_b128 v[136:139], v220 offset:2048
	ds_read_b128 v[140:143], v220 offset:3072
	ds_read_b128 v[144:147], v221
	ds_read_b128 v[148:151], v221 offset:1024
	ds_read_b128 v[152:155], v221 offset:2048
	ds_read_b128 v[156:159], v221 offset:3072
	s_cmp_eq_u32 s73, 40
	s_cselect_b32 s75, s1, s71
	s_cselect_b32 s74, s0, s70
	s_cselect_b32 s77, s67, s72
	s_cselect_b32 s76, s66, s69
	v_lshl_add_u64 v[238:239], s[70:71], 0, v[190:191]
	v_lshl_add_u64 v[240:241], v[238:239], 0, s[62:63]
	s_add_i32 m0, s15, 0xc000
	ds_read_b128 v[160:163], v222
	ds_read_b128 v[164:167], v222 offset:1024
	ds_read_b128 v[168:171], v222 offset:2048
	ds_read_b128 v[172:175], v222 offset:3072
	ds_read_b128 v[176:179], v222 offset:4096
	ds_read_b128 v[180:183], v222 offset:5120
	ds_read_b128 v[230:233], v222 offset:6144
	ds_read_b128 v[234:237], v222 offset:7168
	global_load_lds_dwordx4 v[240:241], off
	v_lshl_add_u64 v[238:239], v[238:239], 0, s[64:65]
	s_add_i32 m0, s15, 0xe000
	s_nop 0
	global_load_lds_dwordx4 v[238:239], off
	s_waitcnt vmcnt(56)
	s_waitcnt lgkmcnt(0)
	s_barrier
	s_waitcnt lgkmcnt(0)
	v_mfma_f32_16x16x32_bf16 v[124:127], v[128:131], v[160:163], 0
	v_mfma_f32_16x16x32_bf16 v[120:123], v[136:139], v[160:163], 0
	v_mfma_f32_16x16x32_bf16 v[108:111], v[128:131], v[168:171], 0
	v_mfma_f32_16x16x32_bf16 v[104:107], v[136:139], v[168:171], 0
	v_mfma_f32_16x16x32_bf16 v[92:95], v[128:131], v[176:179], 0
	v_mfma_f32_16x16x32_bf16 v[88:91], v[136:139], v[176:179], 0
	v_mfma_f32_16x16x32_bf16 v[76:79], v[128:131], v[230:233], 0
	v_mfma_f32_16x16x32_bf16 v[72:75], v[136:139], v[230:233], 0
	v_mfma_f32_16x16x32_bf16 v[124:127], v[132:135], v[164:167], v[124:127]
	v_mfma_f32_16x16x32_bf16 v[120:123], v[140:143], v[164:167], v[120:123]
	v_mfma_f32_16x16x32_bf16 v[108:111], v[132:135], v[172:175], v[108:111]
	v_mfma_f32_16x16x32_bf16 v[104:107], v[140:143], v[172:175], v[104:107]
	v_mfma_f32_16x16x32_bf16 v[92:95], v[132:135], v[180:183], v[92:95]
	v_mfma_f32_16x16x32_bf16 v[88:91], v[140:143], v[180:183], v[88:91]
	v_mfma_f32_16x16x32_bf16 v[76:79], v[132:135], v[234:237], v[76:79]
	v_mfma_f32_16x16x32_bf16 v[72:75], v[140:143], v[234:237], v[72:75]
	v_mfma_f32_16x16x32_bf16 v[116:119], v[144:147], v[160:163], 0
	v_mfma_f32_16x16x32_bf16 v[112:115], v[152:155], v[160:163], 0
	v_mfma_f32_16x16x32_bf16 v[100:103], v[144:147], v[168:171], 0
	v_mfma_f32_16x16x32_bf16 v[96:99], v[152:155], v[168:171], 0
	v_mfma_f32_16x16x32_bf16 v[84:87], v[144:147], v[176:179], 0
	v_mfma_f32_16x16x32_bf16 v[80:83], v[152:155], v[176:179], 0
	v_mfma_f32_16x16x32_bf16 v[68:71], v[144:147], v[230:233], 0
	v_mfma_f32_16x16x32_bf16 v[64:67], v[152:155], v[230:233], 0
	v_mfma_f32_16x16x32_bf16 v[116:119], v[148:151], v[164:167], v[116:119]
	v_mfma_f32_16x16x32_bf16 v[112:115], v[156:159], v[164:167], v[112:115]
	v_mfma_f32_16x16x32_bf16 v[100:103], v[148:151], v[172:175], v[100:103]
	v_mfma_f32_16x16x32_bf16 v[96:99], v[156:159], v[172:175], v[96:99]
	v_mfma_f32_16x16x32_bf16 v[84:87], v[148:151], v[180:183], v[84:87]
	v_mfma_f32_16x16x32_bf16 v[80:83], v[156:159], v[180:183], v[80:83]
	v_mfma_f32_16x16x32_bf16 v[68:71], v[148:151], v[234:237], v[68:71]
	v_mfma_f32_16x16x32_bf16 v[64:67], v[156:159], v[234:237], v[64:67]
	s_barrier
	s_add_i32 s33, s86, s14
	v_lshl_add_u64 v[238:239], s[76:77], 0, v[190:191]
	s_mov_b32 m0, s33
	ds_read_b128 v[160:163], v222 offset:16384
	ds_read_b128 v[164:167], v222 offset:17408
	ds_read_b128 v[168:171], v222 offset:18432
	ds_read_b128 v[172:175], v222 offset:19456
	ds_read_b128 v[176:179], v222 offset:20480
	ds_read_b128 v[180:183], v222 offset:21504
	ds_read_b128 v[230:233], v222 offset:22528
	ds_read_b128 v[234:237], v222 offset:23552
	global_load_lds_dwordx4 v[238:239], off
	v_lshl_add_u64 v[240:241], v[238:239], 0, s[40:41]
	s_add_i32 m0, s33, 0x2000
	s_add_i32 s33, s87, s14
	global_load_lds_dwordx4 v[240:241], off
	v_lshl_add_u64 v[240:241], v[238:239], 0, s[42:43]
	s_mov_b32 m0, s33
	s_nop 0
	global_load_lds_dwordx4 v[240:241], off
	v_lshl_add_u64 v[240:241], v[238:239], 0, s[44:45]
	s_add_i32 m0, s33, 0x2000
	s_nop 0
	global_load_lds_dwordx4 v[240:241], off
	v_lshl_add_u64 v[240:241], s[74:75], 0, v[190:191]
	s_mov_b32 m0, s15
	v_lshl_add_u64 v[242:243], v[240:241], 0, s[40:41]
	global_load_lds_dwordx4 v[240:241], off
	s_mov_b32 m0, s17
	s_nop 0
	global_load_lds_dwordx4 v[242:243], off
	s_waitcnt vmcnt(56)
	s_waitcnt lgkmcnt(0)
	s_barrier
; #define PG8_STAGE(bufoff, gbase, voff) do { _Pragma("unroll") for (int _i = 0; _i < 2; ++_i) \
;         __builtin_amdgcn_global_load_lds((const unsigned*)((const char*)(gbase) + (voff)[_i]), (PG8_LAS unsigned*)(lds + (bufoff) + ldsw + _i * 8192), 16, 0, 0); } while (0)
; #define PG8_LDA(dst, b, h) do { _Pragma("unroll") for (int m = 0; m < 4; ++m) _Pragma("unroll") for (int k = 0; k < 2; ++k) dst[m][k] = *(const PG8_LAS bf16x8*)(lds + PG8_SA(b, h) + aoff + m * 2048 + k * 1024); } while (0)
; #define PG8_LDB(dst, b, h) do { _Pragma("unroll") for (int n = 0; n < 2; ++n) _Pragma("unroll") for (int k = 0; k < 2; ++k) dst[n][k] = *(const PG8_LAS bf16x8*)(lds + PG8_SB(b, h) + boff + n * 2048 + k * 1024); } while (0)
; #define PG8_MMA(ai, bj, At, Bt) do { __builtin_amdgcn_s_setprio(1); _Pragma("unroll") for (int m = 0; m < 4; ++m) _Pragma("unroll") for (int n = 0; n < 2; ++n) _Pragma("unroll") for (int k = 0; k < 2; ++k) \
;         acc[ai][bj][m][n] = __builtin_amdgcn_mfma_f32_16x16x32_bf16(Bt[n][k], At[m][k], acc[ai][bj][m][n], 0, 0, 0); __builtin_amdgcn_s_setprio(0); } while (0)
; #define PG8_WAIT_V(n) asm volatile("s_waitcnt vmcnt(" #n ")" ::: "memory")
; #define PG8_WAIT_L(n) asm volatile("s_waitcnt lgkmcnt(" #n ")" ::: "memory")
; #define PG8_BAR __builtin_amdgcn_s_barrier()
; #define PG8_SCHED __builtin_amdgcn_sched_barrier(0)
; template <class Epi, class Sched, bool ALIGN_EPI = false, bool SP2 = false>
; __device__ __forceinline__ void gemm_phase(PG8_LAS unsigned char* lds, const Gemm g, const Sched& S, const Epi& E) {
;     ...
;             PG8_WAIT_V(8); PG8_WAIT_L(0); PG8_BAR; PG8_MMA(1, 0, At, B0); PG8_MMA(1, 1, At, B1); PG8_BAR; PG8_SCHED;
;             PG8_LDB(B0, 1, 0); PG8_LDB(B1, 1, 1); PG8_SCHED; PG8_LDA(At, 1, 0); PG8_STAGE(PG8_SA(0, 1), a2 + hstepA, voffA);
;             PG8_WAIT_V(8); PG8_WAIT_L(0); PG8_BAR; PG8_MMA(0, 0, At, B0); PG8_MMA(0, 1, At, B1); PG8_BAR; PG8_SCHED;
	s_waitcnt lgkmcnt(0)
	v_mfma_f32_16x16x32_bf16 v[60:63], v[128:131], v[160:163], 0
	v_mfma_f32_16x16x32_bf16 v[56:59], v[136:139], v[160:163], 0
	v_mfma_f32_16x16x32_bf16 v[44:47], v[128:131], v[168:171], 0
	v_mfma_f32_16x16x32_bf16 v[40:43], v[136:139], v[168:171], 0
	v_mfma_f32_16x16x32_bf16 v[28:31], v[128:131], v[176:179], 0
	v_mfma_f32_16x16x32_bf16 v[24:27], v[136:139], v[176:179], 0
	v_mfma_f32_16x16x32_bf16 v[12:15], v[128:131], v[230:233], 0
	v_mfma_f32_16x16x32_bf16 v[8:11], v[136:139], v[230:233], 0
	v_mfma_f32_16x16x32_bf16 v[60:63], v[132:135], v[164:167], v[60:63]
	v_mfma_f32_16x16x32_bf16 v[56:59], v[140:143], v[164:167], v[56:59]
	v_mfma_f32_16x16x32_bf16 v[44:47], v[132:135], v[172:175], v[44:47]
	v_mfma_f32_16x16x32_bf16 v[40:43], v[140:143], v[172:175], v[40:43]
	v_mfma_f32_16x16x32_bf16 v[28:31], v[132:135], v[180:183], v[28:31]
	v_mfma_f32_16x16x32_bf16 v[24:27], v[140:143], v[180:183], v[24:27]
	v_mfma_f32_16x16x32_bf16 v[12:15], v[132:135], v[234:237], v[12:15]
	v_mfma_f32_16x16x32_bf16 v[8:11], v[140:143], v[234:237], v[8:11]
	v_mfma_f32_16x16x32_bf16 v[52:55], v[144:147], v[160:163], 0
	v_mfma_f32_16x16x32_bf16 v[48:51], v[152:155], v[160:163], 0
	v_mfma_f32_16x16x32_bf16 v[36:39], v[144:147], v[168:171], 0
	v_mfma_f32_16x16x32_bf16 v[32:35], v[152:155], v[168:171], 0
	v_mfma_f32_16x16x32_bf16 v[20:23], v[144:147], v[176:179], 0
	v_mfma_f32_16x16x32_bf16 v[16:19], v[152:155], v[176:179], 0
	v_mfma_f32_16x16x32_bf16 v[4:7], v[144:147], v[230:233], 0
	v_mfma_f32_16x16x32_bf16 v[0:3], v[152:155], v[230:233], 0
	v_mfma_f32_16x16x32_bf16 v[52:55], v[148:151], v[164:167], v[52:55]
	v_mfma_f32_16x16x32_bf16 v[48:51], v[156:159], v[164:167], v[48:51]
	v_mfma_f32_16x16x32_bf16 v[36:39], v[148:151], v[172:175], v[36:39]
	v_mfma_f32_16x16x32_bf16 v[32:35], v[156:159], v[172:175], v[32:35]
	v_mfma_f32_16x16x32_bf16 v[20:23], v[148:151], v[180:183], v[20:23]
	v_mfma_f32_16x16x32_bf16 v[16:19], v[156:159], v[180:183], v[16:19]
	v_mfma_f32_16x16x32_bf16 v[4:7], v[148:151], v[234:237], v[4:7]
	v_mfma_f32_16x16x32_bf16 v[0:3], v[156:159], v[234:237], v[0:3]
	s_barrier
	ds_read_b128 v[128:131], v223
	ds_read_b128 v[132:135], v223 offset:1024
	ds_read_b128 v[136:139], v223 offset:2048
	ds_read_b128 v[140:143], v223 offset:3072
	ds_read_b128 v[144:147], v224
	ds_read_b128 v[148:151], v224 offset:1024
	ds_read_b128 v[152:155], v224 offset:2048
	ds_read_b128 v[156:159], v224 offset:3072
	s_mov_b32 m0, s18
	v_lshl_add_u64 v[242:243], v[240:241], 0, s[42:43]
	ds_read_b128 v[160:163], v222 offset:32768
	ds_read_b128 v[164:167], v222 offset:33792
	ds_read_b128 v[168:171], v222 offset:34816
	ds_read_b128 v[172:175], v222 offset:35840
	ds_read_b128 v[176:179], v222 offset:36864
	ds_read_b128 v[180:183], v222 offset:37888
	ds_read_b128 v[230:233], v222 offset:38912
	ds_read_b128 v[234:237], v222 offset:39936
	global_load_lds_dwordx4 v[242:243], off
	v_lshl_add_u64 v[242:243], v[240:241], 0, s[44:45]
	s_mov_b32 m0, s19
	s_nop 0
	global_load_lds_dwordx4 v[242:243], off
	s_waitcnt vmcnt(8)
	s_waitcnt lgkmcnt(0)
	s_barrier
	s_waitcnt lgkmcnt(0)
	v_mfma_f32_16x16x32_bf16 v[124:127], v[128:131], v[160:163], v[124:127]
	v_mfma_f32_16x16x32_bf16 v[120:123], v[136:139], v[160:163], v[120:123]
	v_mfma_f32_16x16x32_bf16 v[108:111], v[128:131], v[168:171], v[108:111]
	v_mfma_f32_16x16x32_bf16 v[104:107], v[136:139], v[168:171], v[104:107]
	v_mfma_f32_16x16x32_bf16 v[92:95], v[128:131], v[176:179], v[92:95]
	v_mfma_f32_16x16x32_bf16 v[88:91], v[136:139], v[176:179], v[88:91]
	v_mfma_f32_16x16x32_bf16 v[76:79], v[128:131], v[230:233], v[76:79]
	v_mfma_f32_16x16x32_bf16 v[72:75], v[136:139], v[230:233], v[72:75]
	v_mfma_f32_16x16x32_bf16 v[124:127], v[132:135], v[164:167], v[124:127]
	v_mfma_f32_16x16x32_bf16 v[120:123], v[140:143], v[164:167], v[120:123]
	v_mfma_f32_16x16x32_bf16 v[108:111], v[132:135], v[172:175], v[108:111]
	v_mfma_f32_16x16x32_bf16 v[104:107], v[140:143], v[172:175], v[104:107]
	v_mfma_f32_16x16x32_bf16 v[92:95], v[132:135], v[180:183], v[92:95]
	v_mfma_f32_16x16x32_bf16 v[88:91], v[140:143], v[180:183], v[88:91]
	v_mfma_f32_16x16x32_bf16 v[76:79], v[132:135], v[234:237], v[76:79]
	v_mfma_f32_16x16x32_bf16 v[72:75], v[140:143], v[234:237], v[72:75]
	v_mfma_f32_16x16x32_bf16 v[116:119], v[144:147], v[160:163], v[116:119]
	v_mfma_f32_16x16x32_bf16 v[112:115], v[152:155], v[160:163], v[112:115]
	v_mfma_f32_16x16x32_bf16 v[100:103], v[144:147], v[168:171], v[100:103]
	v_mfma_f32_16x16x32_bf16 v[96:99], v[152:155], v[168:171], v[96:99]
	v_mfma_f32_16x16x32_bf16 v[84:87], v[144:147], v[176:179], v[84:87]
	v_mfma_f32_16x16x32_bf16 v[80:83], v[152:155], v[176:179], v[80:83]
	v_mfma_f32_16x16x32_bf16 v[68:71], v[144:147], v[230:233], v[68:71]
	v_mfma_f32_16x16x32_bf16 v[64:67], v[152:155], v[230:233], v[64:67]
	v_mfma_f32_16x16x32_bf16 v[116:119], v[148:151], v[164:167], v[116:119]
	v_mfma_f32_16x16x32_bf16 v[112:115], v[156:159], v[164:167], v[112:115]
	v_mfma_f32_16x16x32_bf16 v[100:103], v[148:151], v[172:175], v[100:103]
	v_mfma_f32_16x16x32_bf16 v[96:99], v[156:159], v[172:175], v[96:99]
	v_mfma_f32_16x16x32_bf16 v[84:87], v[148:151], v[180:183], v[84:87]
	v_mfma_f32_16x16x32_bf16 v[80:83], v[156:159], v[180:183], v[80:83]
	v_mfma_f32_16x16x32_bf16 v[68:71], v[148:151], v[234:237], v[68:71]
	v_mfma_f32_16x16x32_bf16 v[64:67], v[156:159], v[234:237], v[64:67]
	s_barrier
; #define PG8_STAGE(bufoff, gbase, voff) do { _Pragma("unroll") for (int _i = 0; _i < 2; ++_i) \
;         __builtin_amdgcn_global_load_lds((const unsigned*)((const char*)(gbase) + (voff)[_i]), (PG8_LAS unsigned*)(lds + (bufoff) + ldsw + _i * 8192), 16, 0, 0); } while (0)
; #define PG8_LDA(dst, b, h) do { _Pragma("unroll") for (int m = 0; m < 4; ++m) _Pragma("unroll") for (int k = 0; k < 2; ++k) dst[m][k] = *(const PG8_LAS bf16x8*)(lds + PG8_SA(b, h) + aoff + m * 2048 + k * 1024); } while (0)
; #define PG8_MMA(ai, bj, At, Bt) do { __builtin_amdgcn_s_setprio(1); _Pragma("unroll") for (int m = 0; m < 4; ++m) _Pragma("unroll") for (int n = 0; n < 2; ++n) _Pragma("unroll") for (int k = 0; k < 2; ++k) \
;         acc[ai][bj][m][n] = __builtin_amdgcn_mfma_f32_16x16x32_bf16(Bt[n][k], At[m][k], acc[ai][bj][m][n], 0, 0, 0); __builtin_amdgcn_s_setprio(0); } while (0)
; #define PG8_WAIT_V(n) asm volatile("s_waitcnt vmcnt(" #n ")" ::: "memory")
; #define PG8_WAIT_L(n) asm volatile("s_waitcnt lgkmcnt(" #n ")" ::: "memory")
; #define PG8_BAR __builtin_amdgcn_s_barrier()
; #define PG8_SCHED __builtin_amdgcn_sched_barrier(0)
; template <class Epi, class Sched, bool ALIGN_EPI = false, bool SP2 = false>
; __device__ __forceinline__ void gemm_phase(PG8_LAS unsigned char* lds, const Gemm g, const Sched& S, const Epi& E) {
;     ...
;         for (int t = 0; t < nt; t += 2) {
;     ...
;             PG8_LDA(At, 1, 1); PG8_STAGE(PG8_SB(1, 0), b3, voffB); PG8_STAGE(PG8_SB(1, 1), b3 + hstepB, voffB); PG8_STAGE(PG8_SA(1, 0), a3, voffA);
;             PG8_WAIT_V(8); PG8_WAIT_L(0); PG8_BAR; PG8_MMA(1, 0, At, B0); PG8_MMA(1, 1, At, B1); PG8_BAR; PG8_SCHED;
	s_add_i32 s33, s88, s14
	v_lshl_add_u64 v[242:243], v[238:239], 0, s[46:47]
	s_mov_b32 m0, s33
	ds_read_b128 v[160:163], v222 offset:49152
	ds_read_b128 v[164:167], v222 offset:50176
	ds_read_b128 v[168:171], v222 offset:51200
	ds_read_b128 v[172:175], v222 offset:52224
	ds_read_b128 v[176:179], v222 offset:53248
	ds_read_b128 v[180:183], v222 offset:54272
	ds_read_b128 v[230:233], v222 offset:55296
	ds_read_b128 v[234:237], v222 offset:56320
	global_load_lds_dwordx4 v[242:243], off
	v_lshl_add_u64 v[242:243], v[238:239], 0, s[48:49]
	s_add_i32 m0, s33, 0x2000
	s_add_i32 s33, s89, s14
	global_load_lds_dwordx4 v[242:243], off
	v_lshl_add_u64 v[242:243], v[238:239], 0, s[52:53]
	s_mov_b32 m0, s33
	v_lshl_add_u64 v[238:239], v[238:239], 0, s[54:55]
	global_load_lds_dwordx4 v[242:243], off
	s_add_i32 m0, s33, 0x2000
	s_nop 0
	global_load_lds_dwordx4 v[238:239], off
	v_lshl_add_u64 v[238:239], v[240:241], 0, s[46:47]
	s_mov_b32 m0, s80
	s_nop 0
	global_load_lds_dwordx4 v[238:239], off
	v_lshl_add_u64 v[238:239], v[240:241], 0, s[48:49]
	s_mov_b32 m0, s81
	s_nop 0
	global_load_lds_dwordx4 v[238:239], off
	s_waitcnt vmcnt(8)
	s_waitcnt lgkmcnt(0)
	s_barrier
	s_waitcnt lgkmcnt(0)
	v_mfma_f32_16x16x32_bf16 v[60:63], v[128:131], v[160:163], v[60:63]
	v_mfma_f32_16x16x32_bf16 v[56:59], v[136:139], v[160:163], v[56:59]
	v_mfma_f32_16x16x32_bf16 v[44:47], v[128:131], v[168:171], v[44:47]
	v_mfma_f32_16x16x32_bf16 v[40:43], v[136:139], v[168:171], v[40:43]
	v_mfma_f32_16x16x32_bf16 v[28:31], v[128:131], v[176:179], v[28:31]
	v_mfma_f32_16x16x32_bf16 v[24:27], v[136:139], v[176:179], v[24:27]
	v_mfma_f32_16x16x32_bf16 v[12:15], v[128:131], v[230:233], v[12:15]
	v_mfma_f32_16x16x32_bf16 v[8:11], v[136:139], v[230:233], v[8:11]
	v_mfma_f32_16x16x32_bf16 v[60:63], v[132:135], v[164:167], v[60:63]
	v_mfma_f32_16x16x32_bf16 v[56:59], v[140:143], v[164:167], v[56:59]
	v_mfma_f32_16x16x32_bf16 v[44:47], v[132:135], v[172:175], v[44:47]
	v_mfma_f32_16x16x32_bf16 v[40:43], v[140:143], v[172:175], v[40:43]
	v_mfma_f32_16x16x32_bf16 v[28:31], v[132:135], v[180:183], v[28:31]
	v_mfma_f32_16x16x32_bf16 v[24:27], v[140:143], v[180:183], v[24:27]
	v_mfma_f32_16x16x32_bf16 v[12:15], v[132:135], v[234:237], v[12:15]
	v_mfma_f32_16x16x32_bf16 v[8:11], v[140:143], v[234:237], v[8:11]
	v_mfma_f32_16x16x32_bf16 v[52:55], v[144:147], v[160:163], v[52:55]
	v_mfma_f32_16x16x32_bf16 v[48:51], v[152:155], v[160:163], v[48:51]
	v_mfma_f32_16x16x32_bf16 v[36:39], v[144:147], v[168:171], v[36:39]
	v_mfma_f32_16x16x32_bf16 v[32:35], v[152:155], v[168:171], v[32:35]
	v_mfma_f32_16x16x32_bf16 v[20:23], v[144:147], v[176:179], v[20:23]
	v_mfma_f32_16x16x32_bf16 v[16:19], v[152:155], v[176:179], v[16:19]
	v_mfma_f32_16x16x32_bf16 v[4:7], v[144:147], v[230:233], v[4:7]
	v_mfma_f32_16x16x32_bf16 v[0:3], v[152:155], v[230:233], v[0:3]
	v_mfma_f32_16x16x32_bf16 v[52:55], v[148:151], v[164:167], v[52:55]
	v_mfma_f32_16x16x32_bf16 v[48:51], v[156:159], v[164:167], v[48:51]
	v_mfma_f32_16x16x32_bf16 v[36:39], v[148:151], v[172:175], v[36:39]
	v_mfma_f32_16x16x32_bf16 v[32:35], v[156:159], v[172:175], v[32:35]
	v_mfma_f32_16x16x32_bf16 v[20:23], v[148:151], v[180:183], v[20:23]
	v_mfma_f32_16x16x32_bf16 v[16:19], v[156:159], v[180:183], v[16:19]
	v_mfma_f32_16x16x32_bf16 v[4:7], v[148:151], v[234:237], v[4:7]
	v_mfma_f32_16x16x32_bf16 v[0:3], v[156:159], v[234:237], v[0:3]
	s_barrier
	s_add_i32 s73, s73, 2
	s_add_u32 s70, s70, 0x10000
	s_addc_u32 s71, s71, 0
	s_add_u32 s69, s69, 0x10000
	s_addc_u32 s72, s72, 0
	s_cmp_gt_u32 s73, 41
